# forward substitution: each row's final 3-op reduction folded into the next row's first packed FMAs (two accumulator sets), removing 2 nops per row
# baseline (speedup 1.0000x reference)
; #define SUB_LROW(buf, i_, j0_, n_) do { _Pragma("unroll") for (int j4 = 0; j4 < (n_); ++j4) buf[j4] = *(const f32x4*)(Ls + (i_) * 68 + 4 * ((j0_) + j4)); } while (0)
; #define SUB_FROW(buf, j0_, n_) do { _Pragma("unroll") for (int j4 = 0; j4 < (n_); ++j4) { const f32x4 l = buf[j4]; \
;                 acc -= l.x * x[4 * ((j0_) + j4)]; acc -= l.y * x[4 * ((j0_) + j4) + 1]; acc -= l.z * x[4 * ((j0_) + j4) + 2]; acc -= l.w * x[4 * ((j0_) + j4) + 3]; } } while (0)
; __device__ __forceinline__ void gdn_prep(KA a, int layer, unsigned char* lds, const int tid_, const int bid_) {
;     ...
;         if (tid < 256) {
;             float x[64];
; #pragma unroll
;             for (int i = 0; i < 64; ++i) x[i] = RHS[i * 260 + tid];
;             f32x4 bufA[8], bufB[8];
;     ...
; #pragma unroll
;             for (int j4 = 0; j4 < 8; ++j4) { bufA[j4] = (f32x4){0.f, 0.f, 0.f, 0.f}; bufB[j4] = (f32x4){0.f, 0.f, 0.f, 0.f}; }
;             SUB_LROW(bufA, 1, 0, 1);
; #pragma unroll
;             for (int i = 1; i <= 32; ++i) {
;                 const int nn = (i + 4) / 4 < 8 ? (i + 4) / 4 : 8;
;                 float acc = x[i];
;                 if (i & 1) { SUB_LROW(bufB, i + 1, 0, nn); __builtin_amdgcn_sched_barrier(0); SUB_FROW(bufA, 0, (i + 3) / 4); }
;                 else       { SUB_LROW(bufA, i + 1, 0, nn); __builtin_amdgcn_sched_barrier(0); SUB_FROW(bufB, 0, (i + 3) / 4); }
;                 x[i] = acc;
;                 __builtin_amdgcn_sched_barrier(0);
;             }
.LBB0_221:
	s_or_saveexec_b64 s[90:91], s[90:91]
	s_nop 0
	v_mov_b64_e32 v[2:3], s[18:19]
	s_xor_b64 exec, exec, s[90:91]
	s_cbranch_execz .LBB0_208
	ds_read_b32 v2, v154 offset:52224
	ds_read_b32 v3, v154 offset:53264
	ds_read_b32 v4, v154 offset:54304
	ds_read_b32 v5, v154 offset:55344
	ds_read_b32 v6, v154 offset:56384
	ds_read_b32 v7, v154 offset:57424
	ds_read_b32 v8, v154 offset:58464
	ds_read_b32 v9, v154 offset:59504
	ds_read_b32 v10, v154 offset:60544
	ds_read_b32 v11, v154 offset:61584
	ds_read_b32 v12, v154 offset:62624
	ds_read_b32 v13, v154 offset:63664
	ds_read_b32 v14, v154 offset:64704
	ds_read_b32 v15, v155 offset:13520
	ds_read_b32 v16, v155 offset:14560
	ds_read_b32 v17, v155 offset:15600
	ds_read_b32 v18, v155 offset:16640
	ds_read_b32 v19, v155 offset:17680
	ds_read_b32 v20, v155 offset:18720
	ds_read_b32 v21, v155 offset:19760
	ds_read_b32 v22, v155 offset:20800
	ds_read_b32 v23, v155 offset:21840
	ds_read_b32 v24, v155 offset:22880
	ds_read_b32 v25, v155 offset:23920
	ds_read_b32 v26, v155 offset:24960
	ds_read_b32 v27, v155 offset:26000
	ds_read_b32 v28, v155 offset:27040
	ds_read_b32 v29, v155 offset:28080
	ds_read_b32 v30, v155 offset:29120
	ds_read_b32 v31, v155 offset:30160
	ds_read_b32 v32, v155 offset:31200
	ds_read_b32 v33, v155 offset:32240
	ds_read_b32 v34, v155 offset:33280
	ds_read_b32 v35, v155 offset:34320
	ds_read_b32 v36, v155 offset:35360
	ds_read_b32 v37, v155 offset:36400
	ds_read_b32 v38, v155 offset:37440
	ds_read_b32 v39, v155 offset:38480
	ds_read_b32 v40, v155 offset:39520
	ds_read_b32 v41, v155 offset:40560
	ds_read_b32 v42, v155 offset:41600
	ds_read_b32 v43, v155 offset:42640
	ds_read_b32 v44, v155 offset:43680
	ds_read_b32 v45, v155 offset:44720
	ds_read_b32 v46, v155 offset:45760
	ds_read_b32 v47, v155 offset:46800
	ds_read_b32 v48, v155 offset:47840
	ds_read_b32 v49, v155 offset:48880
	ds_read_b32 v50, v155 offset:49920
	ds_read_b32 v51, v155 offset:50960
	ds_read_b32 v52, v155 offset:52000
	ds_read_b32 v53, v155 offset:53040
	ds_read_b32 v54, v155 offset:54080
	ds_read_b32 v55, v155 offset:55120
	ds_read_b32 v56, v155 offset:56160
	ds_read_b32 v57, v155 offset:57200
	ds_read_b32 v58, v155 offset:58240
	ds_read_b32 v59, v155 offset:59280
	ds_read_b32 v60, v155 offset:60320
	ds_read_b32 v61, v155 offset:61360
	ds_read_b32 v62, v155 offset:62400
	ds_read_b32 v63, v155 offset:63440
	ds_read_b32 v64, v155 offset:64480
	ds_read_b32 v65, v155 offset:65520
	s_waitcnt lgkmcnt(0)
	ds_read_b128 v[66:69], v1 offset:35088
	ds_read_b128 v[70:73], v1 offset:35360
	ds_read_b128 v[74:77], v1 offset:35632
	ds_read_b128 v[78:81], v1 offset:35904
	ds_read_b128 v[82:85], v1 offset:36176
	ds_read_b128 v[86:89], v1 offset:36192
	ds_read_b128 v[116:119], v1 offset:36448
	ds_read_b128 v[120:123], v1 offset:36464
	ds_read_b128 v[124:127], v1 offset:36720
	ds_read_b128 v[128:131], v1 offset:36736
	ds_read_b128 v[132:135], v1 offset:36992
	ds_read_b128 v[136:139], v1 offset:37008
	ds_read_b128 v[140:143], v1 offset:37264
	ds_read_b128 v[200:203], v1 offset:37280
	ds_read_b128 v[204:207], v1 offset:37296
	s_waitcnt lgkmcnt(14)
	v_pk_mul_f32 v[250:251], v[2:3], v[66:67] neg_lo:[1,0] neg_hi:[1,0]
	v_pk_mul_f32 v[252:253], v[4:5], v[68:69] neg_lo:[1,0] neg_hi:[1,0]
	ds_read_b128 v[246:249], v1 offset:37536
	s_nop 0
	v_pk_add_f32 v[250:251], v[250:251], v[252:253]
	s_nop 0
	v_add_f32_e32 v250, v250, v251
	v_add_f32_e32 v3, v3, v250
	s_waitcnt lgkmcnt(14)
	v_pk_mul_f32 v[242:243], v[2:3], v[70:71] neg_lo:[1,0] neg_hi:[1,0]
	v_pk_mul_f32 v[244:245], v[4:5], v[72:73] neg_lo:[1,0] neg_hi:[1,0]
	ds_read_b128 v[66:69], v1 offset:37552
	s_nop 0
	v_pk_add_f32 v[242:243], v[242:243], v[244:245]
	s_nop 0
	v_add_f32_e32 v242, v242, v243
	v_add_f32_e32 v4, v4, v242
	s_waitcnt lgkmcnt(14)
	v_pk_mul_f32 v[250:251], v[2:3], v[74:75] neg_lo:[1,0] neg_hi:[1,0]
	v_pk_mul_f32 v[252:253], v[4:5], v[76:77] neg_lo:[1,0] neg_hi:[1,0]
	ds_read_b128 v[70:73], v1 offset:37568
	s_nop 0
	v_pk_add_f32 v[250:251], v[250:251], v[252:253]
	s_nop 0
	v_add_f32_e32 v250, v250, v251
	v_add_f32_e32 v5, v5, v250
	s_waitcnt lgkmcnt(14)
	v_pk_mul_f32 v[242:243], v[2:3], v[78:79] neg_lo:[1,0] neg_hi:[1,0]
	v_pk_mul_f32 v[244:245], v[4:5], v[80:81] neg_lo:[1,0] neg_hi:[1,0]
	ds_read_b128 v[74:77], v1 offset:37808
	s_nop 0
	v_pk_add_f32 v[242:243], v[242:243], v[244:245]
	s_nop 0
	v_add_f32_e32 v242, v242, v243
	v_add_f32_e32 v6, v6, v242
	s_waitcnt lgkmcnt(14)
	v_pk_mul_f32 v[250:251], v[2:3], v[82:83] neg_lo:[1,0] neg_hi:[1,0]
	v_pk_mul_f32 v[252:253], v[4:5], v[84:85] neg_lo:[1,0] neg_hi:[1,0]
	ds_read_b128 v[78:81], v1 offset:37824
	s_waitcnt lgkmcnt(14)
	v_pk_fma_f32 v[250:251], v[6:7], v[86:87], v[250:251] neg_lo:[1,0,0] neg_hi:[1,0,0]
	v_pk_fma_f32 v[252:253], v[8:9], v[88:89], v[252:253] neg_lo:[1,0,0] neg_hi:[1,0,0]
	ds_read_b128 v[82:85], v1 offset:37840
	s_nop 0
	v_pk_add_f32 v[250:251], v[250:251], v[252:253]
	s_nop 0
	v_add_f32_e32 v250, v250, v251
	v_add_f32_e32 v7, v7, v250
	s_waitcnt lgkmcnt(14)
	v_pk_mul_f32 v[242:243], v[2:3], v[116:117] neg_lo:[1,0] neg_hi:[1,0]
	v_pk_mul_f32 v[244:245], v[4:5], v[118:119] neg_lo:[1,0] neg_hi:[1,0]
	ds_read_b128 v[86:89], v1 offset:38080
	s_waitcnt lgkmcnt(14)
	v_pk_fma_f32 v[242:243], v[6:7], v[120:121], v[242:243] neg_lo:[1,0,0] neg_hi:[1,0,0]
	v_pk_fma_f32 v[244:245], v[8:9], v[122:123], v[244:245] neg_lo:[1,0,0] neg_hi:[1,0,0]
	ds_read_b128 v[116:119], v1 offset:38096
	s_nop 0
	v_pk_add_f32 v[242:243], v[242:243], v[244:245]
	s_nop 0
	v_add_f32_e32 v242, v242, v243
	v_add_f32_e32 v8, v8, v242
	s_waitcnt lgkmcnt(14)
; #define SUB_LROW(buf, i_, j0_, n_) do { _Pragma("unroll") for (int j4 = 0; j4 < (n_); ++j4) buf[j4] = *(const f32x4*)(Ls + (i_) * 68 + 4 * ((j0_) + j4)); } while (0)
; #define SUB_FROW(buf, j0_, n_) do { _Pragma("unroll") for (int j4 = 0; j4 < (n_); ++j4) { const f32x4 l = buf[j4]; \
;                 acc -= l.x * x[4 * ((j0_) + j4)]; acc -= l.y * x[4 * ((j0_) + j4) + 1]; acc -= l.z * x[4 * ((j0_) + j4) + 2]; acc -= l.w * x[4 * ((j0_) + j4) + 3]; } } while (0)
; __device__ __forceinline__ void gdn_prep(KA a, int layer, unsigned char* lds, const int tid_, const int bid_) {
;     ...
;             SUB_LROW(bufA, 1, 0, 1);
; #pragma unroll
;             for (int i = 1; i <= 32; ++i) {
;                 const int nn = (i + 4) / 4 < 8 ? (i + 4) / 4 : 8;
;                 float acc = x[i];
;                 if (i & 1) { SUB_LROW(bufB, i + 1, 0, nn); __builtin_amdgcn_sched_barrier(0); SUB_FROW(bufA, 0, (i + 3) / 4); }
;                 else       { SUB_LROW(bufA, i + 1, 0, nn); __builtin_amdgcn_sched_barrier(0); SUB_FROW(bufB, 0, (i + 3) / 4); }
;                 x[i] = acc;
;                 __builtin_amdgcn_sched_barrier(0);
;             }
	v_pk_mul_f32 v[250:251], v[2:3], v[124:125] neg_lo:[1,0] neg_hi:[1,0]
	v_pk_mul_f32 v[252:253], v[4:5], v[126:127] neg_lo:[1,0] neg_hi:[1,0]
	ds_read_b128 v[120:123], v1 offset:38112
	s_waitcnt lgkmcnt(14)
	v_pk_fma_f32 v[250:251], v[6:7], v[128:129], v[250:251] neg_lo:[1,0,0] neg_hi:[1,0,0]
	v_pk_fma_f32 v[252:253], v[8:9], v[130:131], v[252:253] neg_lo:[1,0,0] neg_hi:[1,0,0]
	ds_read_b128 v[124:127], v1 offset:38352
	s_nop 0
	v_pk_add_f32 v[250:251], v[250:251], v[252:253]
	s_nop 0
	v_add_f32_e32 v250, v250, v251
	v_add_f32_e32 v9, v9, v250
	s_waitcnt lgkmcnt(14)
	v_pk_mul_f32 v[242:243], v[2:3], v[132:133] neg_lo:[1,0] neg_hi:[1,0]
	v_pk_mul_f32 v[244:245], v[4:5], v[134:135] neg_lo:[1,0] neg_hi:[1,0]
	ds_read_b128 v[128:131], v1 offset:38368
	s_waitcnt lgkmcnt(14)
	v_pk_fma_f32 v[242:243], v[6:7], v[136:137], v[242:243] neg_lo:[1,0,0] neg_hi:[1,0,0]
	v_pk_fma_f32 v[244:245], v[8:9], v[138:139], v[244:245] neg_lo:[1,0,0] neg_hi:[1,0,0]
	ds_read_b128 v[132:135], v1 offset:38384
	s_waitcnt lgkmcnt(14)
	v_pk_mul_f32 v[250:251], v[2:3], v[140:141] neg_lo:[1,0] neg_hi:[1,0]
	v_pk_mul_f32 v[252:253], v[4:5], v[142:143] neg_lo:[1,0] neg_hi:[1,0]
	v_pk_add_f32 v[242:243], v[242:243], v[244:245]
	ds_read_b128 v[136:139], v1 offset:38400
	s_waitcnt lgkmcnt(14)
	v_pk_fma_f32 v[250:251], v[6:7], v[200:201], v[250:251] neg_lo:[1,0,0] neg_hi:[1,0,0]
	v_add_f32_e32 v242, v242, v243
	v_pk_fma_f32 v[252:253], v[8:9], v[202:203], v[252:253] neg_lo:[1,0,0] neg_hi:[1,0,0]
	v_add_f32_e32 v10, v10, v242
	ds_read_b128 v[140:143], v1 offset:38624
	s_waitcnt lgkmcnt(14)
	v_pk_fma_f32 v[250:251], v[10:11], v[204:205], v[250:251] neg_lo:[1,0,0] neg_hi:[1,0,0]
	v_pk_fma_f32 v[252:253], v[12:13], v[206:207], v[252:253] neg_lo:[1,0,0] neg_hi:[1,0,0]
	ds_read_b128 v[200:203], v1 offset:38640
	s_waitcnt lgkmcnt(14)
	v_pk_mul_f32 v[242:243], v[2:3], v[246:247] neg_lo:[1,0] neg_hi:[1,0]
	v_pk_mul_f32 v[244:245], v[4:5], v[248:249] neg_lo:[1,0] neg_hi:[1,0]
	v_pk_add_f32 v[250:251], v[250:251], v[252:253]
	ds_read_b128 v[204:207], v1 offset:38656
	s_waitcnt lgkmcnt(14)
	v_pk_fma_f32 v[242:243], v[6:7], v[66:67], v[242:243] neg_lo:[1,0,0] neg_hi:[1,0,0]
	v_add_f32_e32 v250, v250, v251
	v_pk_fma_f32 v[244:245], v[8:9], v[68:69], v[244:245] neg_lo:[1,0,0] neg_hi:[1,0,0]
	v_add_f32_e32 v11, v11, v250
	ds_read_b128 v[246:249], v1 offset:38672
	s_waitcnt lgkmcnt(14)
	v_pk_fma_f32 v[242:243], v[10:11], v[70:71], v[242:243] neg_lo:[1,0,0] neg_hi:[1,0,0]
	v_pk_fma_f32 v[244:245], v[12:13], v[72:73], v[244:245] neg_lo:[1,0,0] neg_hi:[1,0,0]
	ds_read_b128 v[66:69], v1 offset:38896
	s_waitcnt lgkmcnt(14)
	v_pk_mul_f32 v[250:251], v[2:3], v[74:75] neg_lo:[1,0] neg_hi:[1,0]
	v_pk_mul_f32 v[252:253], v[4:5], v[76:77] neg_lo:[1,0] neg_hi:[1,0]
	v_pk_add_f32 v[242:243], v[242:243], v[244:245]
	ds_read_b128 v[70:73], v1 offset:38912
	s_waitcnt lgkmcnt(14)
	v_pk_fma_f32 v[250:251], v[6:7], v[78:79], v[250:251] neg_lo:[1,0,0] neg_hi:[1,0,0]
	v_add_f32_e32 v242, v242, v243
	v_pk_fma_f32 v[252:253], v[8:9], v[80:81], v[252:253] neg_lo:[1,0,0] neg_hi:[1,0,0]
	v_add_f32_e32 v12, v12, v242
	ds_read_b128 v[74:77], v1 offset:38928
	s_waitcnt lgkmcnt(14)
	v_pk_fma_f32 v[250:251], v[10:11], v[82:83], v[250:251] neg_lo:[1,0,0] neg_hi:[1,0,0]
	v_pk_fma_f32 v[252:253], v[12:13], v[84:85], v[252:253] neg_lo:[1,0,0] neg_hi:[1,0,0]
	ds_read_b128 v[78:81], v1 offset:38944
	s_waitcnt lgkmcnt(14)
	v_pk_mul_f32 v[242:243], v[2:3], v[86:87] neg_lo:[1,0] neg_hi:[1,0]
	v_pk_mul_f32 v[244:245], v[4:5], v[88:89] neg_lo:[1,0] neg_hi:[1,0]
	v_pk_add_f32 v[250:251], v[250:251], v[252:253]
	ds_read_b128 v[82:85], v1 offset:39168
	s_waitcnt lgkmcnt(14)
	v_pk_fma_f32 v[242:243], v[6:7], v[116:117], v[242:243] neg_lo:[1,0,0] neg_hi:[1,0,0]
	v_add_f32_e32 v250, v250, v251
	v_pk_fma_f32 v[244:245], v[8:9], v[118:119], v[244:245] neg_lo:[1,0,0] neg_hi:[1,0,0]
	v_add_f32_e32 v13, v13, v250
	ds_read_b128 v[86:89], v1 offset:39184
	s_waitcnt lgkmcnt(14)
	v_pk_fma_f32 v[242:243], v[10:11], v[120:121], v[242:243] neg_lo:[1,0,0] neg_hi:[1,0,0]
	v_pk_fma_f32 v[244:245], v[12:13], v[122:123], v[244:245] neg_lo:[1,0,0] neg_hi:[1,0,0]
	ds_read_b128 v[116:119], v1 offset:39200
	s_waitcnt lgkmcnt(14)
	v_pk_mul_f32 v[250:251], v[2:3], v[124:125] neg_lo:[1,0] neg_hi:[1,0]
	v_pk_mul_f32 v[252:253], v[4:5], v[126:127] neg_lo:[1,0] neg_hi:[1,0]
	v_pk_add_f32 v[242:243], v[242:243], v[244:245]
	ds_read_b128 v[120:123], v1 offset:39216
	s_waitcnt lgkmcnt(14)
	v_pk_fma_f32 v[250:251], v[6:7], v[128:129], v[250:251] neg_lo:[1,0,0] neg_hi:[1,0,0]
	v_add_f32_e32 v242, v242, v243
	v_pk_fma_f32 v[252:253], v[8:9], v[130:131], v[252:253] neg_lo:[1,0,0] neg_hi:[1,0,0]
	v_add_f32_e32 v14, v14, v242
	ds_read_b128 v[124:127], v1 offset:39440
	s_waitcnt lgkmcnt(14)
	v_pk_fma_f32 v[250:251], v[10:11], v[132:133], v[250:251] neg_lo:[1,0,0] neg_hi:[1,0,0]
	v_pk_fma_f32 v[252:253], v[12:13], v[134:135], v[252:253] neg_lo:[1,0,0] neg_hi:[1,0,0]
	ds_read_b128 v[128:131], v1 offset:39456
	s_waitcnt lgkmcnt(14)
	v_pk_fma_f32 v[250:251], v[14:15], v[136:137], v[250:251] neg_lo:[1,0,0] neg_hi:[1,0,0]
	v_pk_fma_f32 v[252:253], v[16:17], v[138:139], v[252:253] neg_lo:[1,0,0] neg_hi:[1,0,0]
	ds_read_b128 v[132:135], v1 offset:39472
	s_waitcnt lgkmcnt(14)
	v_pk_mul_f32 v[242:243], v[2:3], v[140:141] neg_lo:[1,0] neg_hi:[1,0]
	v_pk_mul_f32 v[244:245], v[4:5], v[142:143] neg_lo:[1,0] neg_hi:[1,0]
	v_pk_add_f32 v[250:251], v[250:251], v[252:253]
	ds_read_b128 v[136:139], v1 offset:39488
	s_waitcnt lgkmcnt(14)
	v_pk_fma_f32 v[242:243], v[6:7], v[200:201], v[242:243] neg_lo:[1,0,0] neg_hi:[1,0,0]
	v_add_f32_e32 v250, v250, v251
	v_pk_fma_f32 v[244:245], v[8:9], v[202:203], v[244:245] neg_lo:[1,0,0] neg_hi:[1,0,0]
	v_add_f32_e32 v15, v15, v250
	ds_read_b128 v[140:143], v1 offset:39504
	s_waitcnt lgkmcnt(14)
; #define SUB_LROW(buf, i_, j0_, n_) do { _Pragma("unroll") for (int j4 = 0; j4 < (n_); ++j4) buf[j4] = *(const f32x4*)(Ls + (i_) * 68 + 4 * ((j0_) + j4)); } while (0)
; #define SUB_FROW(buf, j0_, n_) do { _Pragma("unroll") for (int j4 = 0; j4 < (n_); ++j4) { const f32x4 l = buf[j4]; \
;                 acc -= l.x * x[4 * ((j0_) + j4)]; acc -= l.y * x[4 * ((j0_) + j4) + 1]; acc -= l.z * x[4 * ((j0_) + j4) + 2]; acc -= l.w * x[4 * ((j0_) + j4) + 3]; } } while (0)
; __device__ __forceinline__ void gdn_prep(KA a, int layer, unsigned char* lds, const int tid_, const int bid_) {
;     ...
;             SUB_LROW(bufA, 1, 0, 1);
; #pragma unroll
;             for (int i = 1; i <= 32; ++i) {
;                 const int nn = (i + 4) / 4 < 8 ? (i + 4) / 4 : 8;
;                 float acc = x[i];
;                 if (i & 1) { SUB_LROW(bufB, i + 1, 0, nn); __builtin_amdgcn_sched_barrier(0); SUB_FROW(bufA, 0, (i + 3) / 4); }
;                 else       { SUB_LROW(bufA, i + 1, 0, nn); __builtin_amdgcn_sched_barrier(0); SUB_FROW(bufB, 0, (i + 3) / 4); }
;                 x[i] = acc;
;                 __builtin_amdgcn_sched_barrier(0);
;             }
	v_pk_fma_f32 v[242:243], v[10:11], v[204:205], v[242:243] neg_lo:[1,0,0] neg_hi:[1,0,0]
	v_pk_fma_f32 v[244:245], v[12:13], v[206:207], v[244:245] neg_lo:[1,0,0] neg_hi:[1,0,0]
	ds_read_b128 v[200:203], v1 offset:39712
	s_waitcnt lgkmcnt(14)
	v_pk_fma_f32 v[242:243], v[14:15], v[246:247], v[242:243] neg_lo:[1,0,0] neg_hi:[1,0,0]
	v_pk_fma_f32 v[244:245], v[16:17], v[248:249], v[244:245] neg_lo:[1,0,0] neg_hi:[1,0,0]
	ds_read_b128 v[204:207], v1 offset:39728
	s_waitcnt lgkmcnt(14)
	v_pk_mul_f32 v[250:251], v[2:3], v[66:67] neg_lo:[1,0] neg_hi:[1,0]
	v_pk_mul_f32 v[252:253], v[4:5], v[68:69] neg_lo:[1,0] neg_hi:[1,0]
	v_pk_add_f32 v[242:243], v[242:243], v[244:245]
	ds_read_b128 v[246:249], v1 offset:39744
	s_waitcnt lgkmcnt(14)
	v_pk_fma_f32 v[250:251], v[6:7], v[70:71], v[250:251] neg_lo:[1,0,0] neg_hi:[1,0,0]
	v_add_f32_e32 v242, v242, v243
	v_pk_fma_f32 v[252:253], v[8:9], v[72:73], v[252:253] neg_lo:[1,0,0] neg_hi:[1,0,0]
	v_add_f32_e32 v16, v16, v242
	ds_read_b128 v[66:69], v1 offset:39760
	s_waitcnt lgkmcnt(14)
	v_pk_fma_f32 v[250:251], v[10:11], v[74:75], v[250:251] neg_lo:[1,0,0] neg_hi:[1,0,0]
	v_pk_fma_f32 v[252:253], v[12:13], v[76:77], v[252:253] neg_lo:[1,0,0] neg_hi:[1,0,0]
	ds_read_b128 v[70:73], v1 offset:39776
	s_waitcnt lgkmcnt(14)
	v_pk_fma_f32 v[250:251], v[14:15], v[78:79], v[250:251] neg_lo:[1,0,0] neg_hi:[1,0,0]
	v_pk_fma_f32 v[252:253], v[16:17], v[80:81], v[252:253] neg_lo:[1,0,0] neg_hi:[1,0,0]
	ds_read_b128 v[74:77], v1 offset:39984
	s_waitcnt lgkmcnt(14)
	v_pk_mul_f32 v[242:243], v[2:3], v[82:83] neg_lo:[1,0] neg_hi:[1,0]
	v_pk_mul_f32 v[244:245], v[4:5], v[84:85] neg_lo:[1,0] neg_hi:[1,0]
	v_pk_add_f32 v[250:251], v[250:251], v[252:253]
	ds_read_b128 v[78:81], v1 offset:40000
	s_waitcnt lgkmcnt(14)
	v_pk_fma_f32 v[242:243], v[6:7], v[86:87], v[242:243] neg_lo:[1,0,0] neg_hi:[1,0,0]
	v_add_f32_e32 v250, v250, v251
	v_pk_fma_f32 v[244:245], v[8:9], v[88:89], v[244:245] neg_lo:[1,0,0] neg_hi:[1,0,0]
	v_add_f32_e32 v17, v17, v250
	ds_read_b128 v[82:85], v1 offset:40016
	s_waitcnt lgkmcnt(14)
	v_pk_fma_f32 v[242:243], v[10:11], v[116:117], v[242:243] neg_lo:[1,0,0] neg_hi:[1,0,0]
	v_pk_fma_f32 v[244:245], v[12:13], v[118:119], v[244:245] neg_lo:[1,0,0] neg_hi:[1,0,0]
	ds_read_b128 v[86:89], v1 offset:40032
	s_waitcnt lgkmcnt(14)
	v_pk_fma_f32 v[242:243], v[14:15], v[120:121], v[242:243] neg_lo:[1,0,0] neg_hi:[1,0,0]
	v_pk_fma_f32 v[244:245], v[16:17], v[122:123], v[244:245] neg_lo:[1,0,0] neg_hi:[1,0,0]
	ds_read_b128 v[116:119], v1 offset:40048
	s_waitcnt lgkmcnt(14)
	v_pk_mul_f32 v[250:251], v[2:3], v[124:125] neg_lo:[1,0] neg_hi:[1,0]
	v_pk_mul_f32 v[252:253], v[4:5], v[126:127] neg_lo:[1,0] neg_hi:[1,0]
	v_pk_add_f32 v[242:243], v[242:243], v[244:245]
	ds_read_b128 v[120:123], v1 offset:40256
	s_waitcnt lgkmcnt(14)
	v_pk_fma_f32 v[250:251], v[6:7], v[128:129], v[250:251] neg_lo:[1,0,0] neg_hi:[1,0,0]
	v_add_f32_e32 v242, v242, v243
	v_pk_fma_f32 v[252:253], v[8:9], v[130:131], v[252:253] neg_lo:[1,0,0] neg_hi:[1,0,0]
	v_add_f32_e32 v18, v18, v242
	ds_read_b128 v[124:127], v1 offset:40272
	s_waitcnt lgkmcnt(14)
	v_pk_fma_f32 v[250:251], v[10:11], v[132:133], v[250:251] neg_lo:[1,0,0] neg_hi:[1,0,0]
	v_pk_fma_f32 v[252:253], v[12:13], v[134:135], v[252:253] neg_lo:[1,0,0] neg_hi:[1,0,0]
	ds_read_b128 v[128:131], v1 offset:40288
	s_waitcnt lgkmcnt(14)
	v_pk_fma_f32 v[250:251], v[14:15], v[136:137], v[250:251] neg_lo:[1,0,0] neg_hi:[1,0,0]
	v_pk_fma_f32 v[252:253], v[16:17], v[138:139], v[252:253] neg_lo:[1,0,0] neg_hi:[1,0,0]
	ds_read_b128 v[132:135], v1 offset:40304
	s_waitcnt lgkmcnt(14)
	v_pk_fma_f32 v[250:251], v[18:19], v[140:141], v[250:251] neg_lo:[1,0,0] neg_hi:[1,0,0]
	v_pk_fma_f32 v[252:253], v[20:21], v[142:143], v[252:253] neg_lo:[1,0,0] neg_hi:[1,0,0]
	ds_read_b128 v[136:139], v1 offset:40320
	s_waitcnt lgkmcnt(14)
	v_pk_mul_f32 v[242:243], v[2:3], v[200:201] neg_lo:[1,0] neg_hi:[1,0]
	v_pk_mul_f32 v[244:245], v[4:5], v[202:203] neg_lo:[1,0] neg_hi:[1,0]
	v_pk_add_f32 v[250:251], v[250:251], v[252:253]
	ds_read_b128 v[140:143], v1 offset:40528
	s_waitcnt lgkmcnt(14)
	v_pk_fma_f32 v[242:243], v[6:7], v[204:205], v[242:243] neg_lo:[1,0,0] neg_hi:[1,0,0]
	v_add_f32_e32 v250, v250, v251
	v_pk_fma_f32 v[244:245], v[8:9], v[206:207], v[244:245] neg_lo:[1,0,0] neg_hi:[1,0,0]
	v_add_f32_e32 v19, v19, v250
	ds_read_b128 v[200:203], v1 offset:40544
	s_waitcnt lgkmcnt(14)
	v_pk_fma_f32 v[242:243], v[10:11], v[246:247], v[242:243] neg_lo:[1,0,0] neg_hi:[1,0,0]
	v_pk_fma_f32 v[244:245], v[12:13], v[248:249], v[244:245] neg_lo:[1,0,0] neg_hi:[1,0,0]
	ds_read_b128 v[204:207], v1 offset:40560
	s_waitcnt lgkmcnt(14)
	v_pk_fma_f32 v[242:243], v[14:15], v[66:67], v[242:243] neg_lo:[1,0,0] neg_hi:[1,0,0]
	v_pk_fma_f32 v[244:245], v[16:17], v[68:69], v[244:245] neg_lo:[1,0,0] neg_hi:[1,0,0]
	ds_read_b128 v[246:249], v1 offset:40576
	s_waitcnt lgkmcnt(14)
	v_pk_fma_f32 v[242:243], v[18:19], v[70:71], v[242:243] neg_lo:[1,0,0] neg_hi:[1,0,0]
	v_pk_fma_f32 v[244:245], v[20:21], v[72:73], v[244:245] neg_lo:[1,0,0] neg_hi:[1,0,0]
	ds_read_b128 v[66:69], v1 offset:40592
	s_waitcnt lgkmcnt(14)
	v_pk_mul_f32 v[250:251], v[2:3], v[74:75] neg_lo:[1,0] neg_hi:[1,0]
	v_pk_mul_f32 v[252:253], v[4:5], v[76:77] neg_lo:[1,0] neg_hi:[1,0]
	v_pk_add_f32 v[242:243], v[242:243], v[244:245]
	ds_read_b128 v[70:73], v1 offset:40608
	s_waitcnt lgkmcnt(14)
	v_pk_fma_f32 v[250:251], v[6:7], v[78:79], v[250:251] neg_lo:[1,0,0] neg_hi:[1,0,0]
	v_add_f32_e32 v242, v242, v243
	v_pk_fma_f32 v[252:253], v[8:9], v[80:81], v[252:253] neg_lo:[1,0,0] neg_hi:[1,0,0]
	v_add_f32_e32 v20, v20, v242
	ds_read_b128 v[74:77], v1 offset:40800
	s_waitcnt lgkmcnt(14)
; #define SUB_LROW(buf, i_, j0_, n_) do { _Pragma("unroll") for (int j4 = 0; j4 < (n_); ++j4) buf[j4] = *(const f32x4*)(Ls + (i_) * 68 + 4 * ((j0_) + j4)); } while (0)
; #define SUB_FROW(buf, j0_, n_) do { _Pragma("unroll") for (int j4 = 0; j4 < (n_); ++j4) { const f32x4 l = buf[j4]; \
;                 acc -= l.x * x[4 * ((j0_) + j4)]; acc -= l.y * x[4 * ((j0_) + j4) + 1]; acc -= l.z * x[4 * ((j0_) + j4) + 2]; acc -= l.w * x[4 * ((j0_) + j4) + 3]; } } while (0)
; __device__ __forceinline__ void gdn_prep(KA a, int layer, unsigned char* lds, const int tid_, const int bid_) {
;     ...
;             SUB_LROW(bufA, 1, 0, 1);
; #pragma unroll
;             for (int i = 1; i <= 32; ++i) {
;                 const int nn = (i + 4) / 4 < 8 ? (i + 4) / 4 : 8;
;                 float acc = x[i];
;                 if (i & 1) { SUB_LROW(bufB, i + 1, 0, nn); __builtin_amdgcn_sched_barrier(0); SUB_FROW(bufA, 0, (i + 3) / 4); }
;                 else       { SUB_LROW(bufA, i + 1, 0, nn); __builtin_amdgcn_sched_barrier(0); SUB_FROW(bufB, 0, (i + 3) / 4); }
;                 x[i] = acc;
;                 __builtin_amdgcn_sched_barrier(0);
;             }
	v_pk_fma_f32 v[250:251], v[10:11], v[82:83], v[250:251] neg_lo:[1,0,0] neg_hi:[1,0,0]
	v_pk_fma_f32 v[252:253], v[12:13], v[84:85], v[252:253] neg_lo:[1,0,0] neg_hi:[1,0,0]
	ds_read_b128 v[78:81], v1 offset:40816
	s_waitcnt lgkmcnt(14)
	v_pk_fma_f32 v[250:251], v[14:15], v[86:87], v[250:251] neg_lo:[1,0,0] neg_hi:[1,0,0]
	v_pk_fma_f32 v[252:253], v[16:17], v[88:89], v[252:253] neg_lo:[1,0,0] neg_hi:[1,0,0]
	ds_read_b128 v[82:85], v1 offset:40832
	s_waitcnt lgkmcnt(14)
	v_pk_fma_f32 v[250:251], v[18:19], v[116:117], v[250:251] neg_lo:[1,0,0] neg_hi:[1,0,0]
	v_pk_fma_f32 v[252:253], v[20:21], v[118:119], v[252:253] neg_lo:[1,0,0] neg_hi:[1,0,0]
	ds_read_b128 v[86:89], v1 offset:40848
	s_waitcnt lgkmcnt(14)
	v_pk_mul_f32 v[242:243], v[2:3], v[120:121] neg_lo:[1,0] neg_hi:[1,0]
	v_pk_mul_f32 v[244:245], v[4:5], v[122:123] neg_lo:[1,0] neg_hi:[1,0]
	v_pk_add_f32 v[250:251], v[250:251], v[252:253]
	ds_read_b128 v[116:119], v1 offset:40864
	s_waitcnt lgkmcnt(14)
	v_pk_fma_f32 v[242:243], v[6:7], v[124:125], v[242:243] neg_lo:[1,0,0] neg_hi:[1,0,0]
	v_add_f32_e32 v250, v250, v251
	v_pk_fma_f32 v[244:245], v[8:9], v[126:127], v[244:245] neg_lo:[1,0,0] neg_hi:[1,0,0]
	v_add_f32_e32 v21, v21, v250
	ds_read_b128 v[120:123], v1 offset:40880
	s_waitcnt lgkmcnt(14)
	v_pk_fma_f32 v[242:243], v[10:11], v[128:129], v[242:243] neg_lo:[1,0,0] neg_hi:[1,0,0]
	v_pk_fma_f32 v[244:245], v[12:13], v[130:131], v[244:245] neg_lo:[1,0,0] neg_hi:[1,0,0]
	ds_read_b128 v[124:127], v1 offset:41072
	s_waitcnt lgkmcnt(14)
	v_pk_fma_f32 v[242:243], v[14:15], v[132:133], v[242:243] neg_lo:[1,0,0] neg_hi:[1,0,0]
	v_pk_fma_f32 v[244:245], v[16:17], v[134:135], v[244:245] neg_lo:[1,0,0] neg_hi:[1,0,0]
	ds_read_b128 v[128:131], v1 offset:41088
	s_waitcnt lgkmcnt(14)
	v_pk_fma_f32 v[242:243], v[18:19], v[136:137], v[242:243] neg_lo:[1,0,0] neg_hi:[1,0,0]
	v_pk_fma_f32 v[244:245], v[20:21], v[138:139], v[244:245] neg_lo:[1,0,0] neg_hi:[1,0,0]
	ds_read_b128 v[132:135], v1 offset:41104
	s_waitcnt lgkmcnt(14)
	v_pk_mul_f32 v[250:251], v[2:3], v[140:141] neg_lo:[1,0] neg_hi:[1,0]
	v_pk_mul_f32 v[252:253], v[4:5], v[142:143] neg_lo:[1,0] neg_hi:[1,0]
	v_pk_add_f32 v[242:243], v[242:243], v[244:245]
	ds_read_b128 v[136:139], v1 offset:41120
	s_waitcnt lgkmcnt(14)
	v_pk_fma_f32 v[250:251], v[6:7], v[200:201], v[250:251] neg_lo:[1,0,0] neg_hi:[1,0,0]
	v_add_f32_e32 v242, v242, v243
	v_pk_fma_f32 v[252:253], v[8:9], v[202:203], v[252:253] neg_lo:[1,0,0] neg_hi:[1,0,0]
	v_add_f32_e32 v22, v22, v242
	ds_read_b128 v[140:143], v1 offset:41136
	s_waitcnt lgkmcnt(14)
	v_pk_fma_f32 v[250:251], v[10:11], v[204:205], v[250:251] neg_lo:[1,0,0] neg_hi:[1,0,0]
	v_pk_fma_f32 v[252:253], v[12:13], v[206:207], v[252:253] neg_lo:[1,0,0] neg_hi:[1,0,0]
	ds_read_b128 v[200:203], v1 offset:41152
	s_waitcnt lgkmcnt(14)
	v_pk_fma_f32 v[250:251], v[14:15], v[246:247], v[250:251] neg_lo:[1,0,0] neg_hi:[1,0,0]
	v_pk_fma_f32 v[252:253], v[16:17], v[248:249], v[252:253] neg_lo:[1,0,0] neg_hi:[1,0,0]
	ds_read_b128 v[204:207], v1 offset:41344
	s_waitcnt lgkmcnt(14)
	v_pk_fma_f32 v[250:251], v[18:19], v[66:67], v[250:251] neg_lo:[1,0,0] neg_hi:[1,0,0]
	v_pk_fma_f32 v[252:253], v[20:21], v[68:69], v[252:253] neg_lo:[1,0,0] neg_hi:[1,0,0]
	ds_read_b128 v[246:249], v1 offset:41360
	s_waitcnt lgkmcnt(14)
	v_pk_fma_f32 v[250:251], v[22:23], v[70:71], v[250:251] neg_lo:[1,0,0] neg_hi:[1,0,0]
	v_pk_fma_f32 v[252:253], v[24:25], v[72:73], v[252:253] neg_lo:[1,0,0] neg_hi:[1,0,0]
	ds_read_b128 v[66:69], v1 offset:41376
	s_waitcnt lgkmcnt(14)
	v_pk_mul_f32 v[242:243], v[2:3], v[74:75] neg_lo:[1,0] neg_hi:[1,0]
	v_pk_mul_f32 v[244:245], v[4:5], v[76:77] neg_lo:[1,0] neg_hi:[1,0]
	v_pk_add_f32 v[250:251], v[250:251], v[252:253]
	ds_read_b128 v[70:73], v1 offset:41392
	s_waitcnt lgkmcnt(14)
	v_pk_fma_f32 v[242:243], v[6:7], v[78:79], v[242:243] neg_lo:[1,0,0] neg_hi:[1,0,0]
	v_add_f32_e32 v250, v250, v251
	v_pk_fma_f32 v[244:245], v[8:9], v[80:81], v[244:245] neg_lo:[1,0,0] neg_hi:[1,0,0]
	v_add_f32_e32 v23, v23, v250
	ds_read_b128 v[74:77], v1 offset:41408
	s_waitcnt lgkmcnt(14)
	v_pk_fma_f32 v[242:243], v[10:11], v[82:83], v[242:243] neg_lo:[1,0,0] neg_hi:[1,0,0]
	v_pk_fma_f32 v[244:245], v[12:13], v[84:85], v[244:245] neg_lo:[1,0,0] neg_hi:[1,0,0]
	ds_read_b128 v[78:81], v1 offset:41424
	s_waitcnt lgkmcnt(14)
	v_pk_fma_f32 v[242:243], v[14:15], v[86:87], v[242:243] neg_lo:[1,0,0] neg_hi:[1,0,0]
	v_pk_fma_f32 v[244:245], v[16:17], v[88:89], v[244:245] neg_lo:[1,0,0] neg_hi:[1,0,0]
	ds_read_b128 v[82:85], v1 offset:41616
	s_waitcnt lgkmcnt(14)
	v_pk_fma_f32 v[242:243], v[18:19], v[116:117], v[242:243] neg_lo:[1,0,0] neg_hi:[1,0,0]
	v_pk_fma_f32 v[244:245], v[20:21], v[118:119], v[244:245] neg_lo:[1,0,0] neg_hi:[1,0,0]
	ds_read_b128 v[86:89], v1 offset:41632
	s_waitcnt lgkmcnt(14)
	v_pk_fma_f32 v[242:243], v[22:23], v[120:121], v[242:243] neg_lo:[1,0,0] neg_hi:[1,0,0]
	v_pk_fma_f32 v[244:245], v[24:25], v[122:123], v[244:245] neg_lo:[1,0,0] neg_hi:[1,0,0]
	ds_read_b128 v[116:119], v1 offset:41648
	s_waitcnt lgkmcnt(14)
	v_pk_mul_f32 v[250:251], v[2:3], v[124:125] neg_lo:[1,0] neg_hi:[1,0]
	v_pk_mul_f32 v[252:253], v[4:5], v[126:127] neg_lo:[1,0] neg_hi:[1,0]
	v_pk_add_f32 v[242:243], v[242:243], v[244:245]
	ds_read_b128 v[120:123], v1 offset:41664
	s_waitcnt lgkmcnt(14)
	v_pk_fma_f32 v[250:251], v[6:7], v[128:129], v[250:251] neg_lo:[1,0,0] neg_hi:[1,0,0]
	v_add_f32_e32 v242, v242, v243
	v_pk_fma_f32 v[252:253], v[8:9], v[130:131], v[252:253] neg_lo:[1,0,0] neg_hi:[1,0,0]
	v_add_f32_e32 v24, v24, v242
	ds_read_b128 v[124:127], v1 offset:41680
	s_waitcnt lgkmcnt(14)
; #define SUB_LROW(buf, i_, j0_, n_) do { _Pragma("unroll") for (int j4 = 0; j4 < (n_); ++j4) buf[j4] = *(const f32x4*)(Ls + (i_) * 68 + 4 * ((j0_) + j4)); } while (0)
; #define SUB_FROW(buf, j0_, n_) do { _Pragma("unroll") for (int j4 = 0; j4 < (n_); ++j4) { const f32x4 l = buf[j4]; \
;                 acc -= l.x * x[4 * ((j0_) + j4)]; acc -= l.y * x[4 * ((j0_) + j4) + 1]; acc -= l.z * x[4 * ((j0_) + j4) + 2]; acc -= l.w * x[4 * ((j0_) + j4) + 3]; } } while (0)
; __device__ __forceinline__ void gdn_prep(KA a, int layer, unsigned char* lds, const int tid_, const int bid_) {
;     ...
;             SUB_LROW(bufA, 1, 0, 1);
; #pragma unroll
;             for (int i = 1; i <= 32; ++i) {
;                 const int nn = (i + 4) / 4 < 8 ? (i + 4) / 4 : 8;
;                 float acc = x[i];
;                 if (i & 1) { SUB_LROW(bufB, i + 1, 0, nn); __builtin_amdgcn_sched_barrier(0); SUB_FROW(bufA, 0, (i + 3) / 4); }
;                 else       { SUB_LROW(bufA, i + 1, 0, nn); __builtin_amdgcn_sched_barrier(0); SUB_FROW(bufB, 0, (i + 3) / 4); }
;                 x[i] = acc;
;                 __builtin_amdgcn_sched_barrier(0);
;             }
	v_pk_fma_f32 v[250:251], v[10:11], v[132:133], v[250:251] neg_lo:[1,0,0] neg_hi:[1,0,0]
	v_pk_fma_f32 v[252:253], v[12:13], v[134:135], v[252:253] neg_lo:[1,0,0] neg_hi:[1,0,0]
	ds_read_b128 v[128:131], v1 offset:41696
	s_waitcnt lgkmcnt(14)
	v_pk_fma_f32 v[250:251], v[14:15], v[136:137], v[250:251] neg_lo:[1,0,0] neg_hi:[1,0,0]
	v_pk_fma_f32 v[252:253], v[16:17], v[138:139], v[252:253] neg_lo:[1,0,0] neg_hi:[1,0,0]
	ds_read_b128 v[132:135], v1 offset:41712
	s_waitcnt lgkmcnt(14)
	v_pk_fma_f32 v[250:251], v[18:19], v[140:141], v[250:251] neg_lo:[1,0,0] neg_hi:[1,0,0]
	v_pk_fma_f32 v[252:253], v[20:21], v[142:143], v[252:253] neg_lo:[1,0,0] neg_hi:[1,0,0]
	ds_read_b128 v[136:139], v1 offset:41888
	s_waitcnt lgkmcnt(14)
	v_pk_fma_f32 v[250:251], v[22:23], v[200:201], v[250:251] neg_lo:[1,0,0] neg_hi:[1,0,0]
	v_pk_fma_f32 v[252:253], v[24:25], v[202:203], v[252:253] neg_lo:[1,0,0] neg_hi:[1,0,0]
	ds_read_b128 v[140:143], v1 offset:41904
	s_waitcnt lgkmcnt(14)
	v_pk_mul_f32 v[242:243], v[2:3], v[204:205] neg_lo:[1,0] neg_hi:[1,0]
	v_pk_mul_f32 v[244:245], v[4:5], v[206:207] neg_lo:[1,0] neg_hi:[1,0]
	v_pk_add_f32 v[250:251], v[250:251], v[252:253]
	ds_read_b128 v[200:203], v1 offset:41920
	s_waitcnt lgkmcnt(14)
	v_pk_fma_f32 v[242:243], v[6:7], v[246:247], v[242:243] neg_lo:[1,0,0] neg_hi:[1,0,0]
	v_add_f32_e32 v250, v250, v251
	v_pk_fma_f32 v[244:245], v[8:9], v[248:249], v[244:245] neg_lo:[1,0,0] neg_hi:[1,0,0]
	v_add_f32_e32 v25, v25, v250
	ds_read_b128 v[204:207], v1 offset:41936
	s_waitcnt lgkmcnt(14)
	v_pk_fma_f32 v[242:243], v[10:11], v[66:67], v[242:243] neg_lo:[1,0,0] neg_hi:[1,0,0]
	v_pk_fma_f32 v[244:245], v[12:13], v[68:69], v[244:245] neg_lo:[1,0,0] neg_hi:[1,0,0]
	ds_read_b128 v[246:249], v1 offset:41952
	s_waitcnt lgkmcnt(14)
	v_pk_fma_f32 v[242:243], v[14:15], v[70:71], v[242:243] neg_lo:[1,0,0] neg_hi:[1,0,0]
	v_pk_fma_f32 v[244:245], v[16:17], v[72:73], v[244:245] neg_lo:[1,0,0] neg_hi:[1,0,0]
	ds_read_b128 v[66:69], v1 offset:41968
	s_waitcnt lgkmcnt(14)
	v_pk_fma_f32 v[242:243], v[18:19], v[74:75], v[242:243] neg_lo:[1,0,0] neg_hi:[1,0,0]
	v_pk_fma_f32 v[244:245], v[20:21], v[76:77], v[244:245] neg_lo:[1,0,0] neg_hi:[1,0,0]
	ds_read_b128 v[70:73], v1 offset:41984
	s_waitcnt lgkmcnt(14)
	v_pk_fma_f32 v[242:243], v[22:23], v[78:79], v[242:243] neg_lo:[1,0,0] neg_hi:[1,0,0]
	v_pk_fma_f32 v[244:245], v[24:25], v[80:81], v[244:245] neg_lo:[1,0,0] neg_hi:[1,0,0]
	ds_read_b128 v[74:77], v1 offset:42160
	s_waitcnt lgkmcnt(14)
	v_pk_mul_f32 v[250:251], v[2:3], v[82:83] neg_lo:[1,0] neg_hi:[1,0]
	v_pk_mul_f32 v[252:253], v[4:5], v[84:85] neg_lo:[1,0] neg_hi:[1,0]
	v_pk_add_f32 v[242:243], v[242:243], v[244:245]
	ds_read_b128 v[78:81], v1 offset:42176
	s_waitcnt lgkmcnt(14)
	v_pk_fma_f32 v[250:251], v[6:7], v[86:87], v[250:251] neg_lo:[1,0,0] neg_hi:[1,0,0]
	v_add_f32_e32 v242, v242, v243
	v_pk_fma_f32 v[252:253], v[8:9], v[88:89], v[252:253] neg_lo:[1,0,0] neg_hi:[1,0,0]
	v_add_f32_e32 v26, v26, v242
	ds_read_b128 v[82:85], v1 offset:42192
	s_waitcnt lgkmcnt(14)
	v_pk_fma_f32 v[250:251], v[10:11], v[116:117], v[250:251] neg_lo:[1,0,0] neg_hi:[1,0,0]
	v_pk_fma_f32 v[252:253], v[12:13], v[118:119], v[252:253] neg_lo:[1,0,0] neg_hi:[1,0,0]
	ds_read_b128 v[86:89], v1 offset:42208
	s_waitcnt lgkmcnt(14)
	v_pk_fma_f32 v[250:251], v[14:15], v[120:121], v[250:251] neg_lo:[1,0,0] neg_hi:[1,0,0]
	v_pk_fma_f32 v[252:253], v[16:17], v[122:123], v[252:253] neg_lo:[1,0,0] neg_hi:[1,0,0]
	ds_read_b128 v[116:119], v1 offset:42224
	s_waitcnt lgkmcnt(14)
	v_pk_fma_f32 v[250:251], v[18:19], v[124:125], v[250:251] neg_lo:[1,0,0] neg_hi:[1,0,0]
	v_pk_fma_f32 v[252:253], v[20:21], v[126:127], v[252:253] neg_lo:[1,0,0] neg_hi:[1,0,0]
	ds_read_b128 v[120:123], v1 offset:42240
	s_waitcnt lgkmcnt(14)
	v_pk_fma_f32 v[250:251], v[22:23], v[128:129], v[250:251] neg_lo:[1,0,0] neg_hi:[1,0,0]
	v_pk_fma_f32 v[252:253], v[24:25], v[130:131], v[252:253] neg_lo:[1,0,0] neg_hi:[1,0,0]
	ds_read_b128 v[124:127], v1 offset:42256
	s_waitcnt lgkmcnt(14)
	v_pk_fma_f32 v[250:251], v[26:27], v[132:133], v[250:251] neg_lo:[1,0,0] neg_hi:[1,0,0]
	v_pk_fma_f32 v[252:253], v[28:29], v[134:135], v[252:253] neg_lo:[1,0,0] neg_hi:[1,0,0]
	ds_read_b128 v[128:131], v1 offset:42432
	s_waitcnt lgkmcnt(14)
	v_pk_mul_f32 v[242:243], v[2:3], v[136:137] neg_lo:[1,0] neg_hi:[1,0]
	v_pk_mul_f32 v[244:245], v[4:5], v[138:139] neg_lo:[1,0] neg_hi:[1,0]
	v_pk_add_f32 v[250:251], v[250:251], v[252:253]
	ds_read_b128 v[132:135], v1 offset:42448
	s_waitcnt lgkmcnt(14)
	v_pk_fma_f32 v[242:243], v[6:7], v[140:141], v[242:243] neg_lo:[1,0,0] neg_hi:[1,0,0]
	v_add_f32_e32 v250, v250, v251
	v_pk_fma_f32 v[244:245], v[8:9], v[142:143], v[244:245] neg_lo:[1,0,0] neg_hi:[1,0,0]
	v_add_f32_e32 v27, v27, v250
	ds_read_b128 v[136:139], v1 offset:42464
	s_waitcnt lgkmcnt(14)
	v_pk_fma_f32 v[242:243], v[10:11], v[200:201], v[242:243] neg_lo:[1,0,0] neg_hi:[1,0,0]
	v_pk_fma_f32 v[244:245], v[12:13], v[202:203], v[244:245] neg_lo:[1,0,0] neg_hi:[1,0,0]
	ds_read_b128 v[140:143], v1 offset:42480
	s_waitcnt lgkmcnt(14)
	v_pk_fma_f32 v[242:243], v[14:15], v[204:205], v[242:243] neg_lo:[1,0,0] neg_hi:[1,0,0]
	v_pk_fma_f32 v[244:245], v[16:17], v[206:207], v[244:245] neg_lo:[1,0,0] neg_hi:[1,0,0]
	ds_read_b128 v[200:203], v1 offset:42496
	s_waitcnt lgkmcnt(14)
	v_pk_fma_f32 v[242:243], v[18:19], v[246:247], v[242:243] neg_lo:[1,0,0] neg_hi:[1,0,0]
	v_pk_fma_f32 v[244:245], v[20:21], v[248:249], v[244:245] neg_lo:[1,0,0] neg_hi:[1,0,0]
	ds_read_b128 v[204:207], v1 offset:42512
	s_waitcnt lgkmcnt(14)
; #define SUB_LROW(buf, i_, j0_, n_) do { _Pragma("unroll") for (int j4 = 0; j4 < (n_); ++j4) buf[j4] = *(const f32x4*)(Ls + (i_) * 68 + 4 * ((j0_) + j4)); } while (0)
; #define SUB_FROW(buf, j0_, n_) do { _Pragma("unroll") for (int j4 = 0; j4 < (n_); ++j4) { const f32x4 l = buf[j4]; \
;                 acc -= l.x * x[4 * ((j0_) + j4)]; acc -= l.y * x[4 * ((j0_) + j4) + 1]; acc -= l.z * x[4 * ((j0_) + j4) + 2]; acc -= l.w * x[4 * ((j0_) + j4) + 3]; } } while (0)
; __device__ __forceinline__ void gdn_prep(KA a, int layer, unsigned char* lds, const int tid_, const int bid_) {
;     ...
;             SUB_LROW(bufA, 1, 0, 1);
; #pragma unroll
;             for (int i = 1; i <= 32; ++i) {
;                 const int nn = (i + 4) / 4 < 8 ? (i + 4) / 4 : 8;
;                 float acc = x[i];
;                 if (i & 1) { SUB_LROW(bufB, i + 1, 0, nn); __builtin_amdgcn_sched_barrier(0); SUB_FROW(bufA, 0, (i + 3) / 4); }
;                 else       { SUB_LROW(bufA, i + 1, 0, nn); __builtin_amdgcn_sched_barrier(0); SUB_FROW(bufB, 0, (i + 3) / 4); }
;                 x[i] = acc;
;                 __builtin_amdgcn_sched_barrier(0);
;             }
	v_pk_fma_f32 v[242:243], v[22:23], v[66:67], v[242:243] neg_lo:[1,0,0] neg_hi:[1,0,0]
	v_pk_fma_f32 v[244:245], v[24:25], v[68:69], v[244:245] neg_lo:[1,0,0] neg_hi:[1,0,0]
	ds_read_b128 v[246:249], v1 offset:42528
	s_waitcnt lgkmcnt(14)
	v_pk_fma_f32 v[242:243], v[26:27], v[70:71], v[242:243] neg_lo:[1,0,0] neg_hi:[1,0,0]
	v_pk_fma_f32 v[244:245], v[28:29], v[72:73], v[244:245] neg_lo:[1,0,0] neg_hi:[1,0,0]
	ds_read_b128 v[66:69], v1 offset:42704
	s_waitcnt lgkmcnt(14)
	v_pk_mul_f32 v[250:251], v[2:3], v[74:75] neg_lo:[1,0] neg_hi:[1,0]
	v_pk_mul_f32 v[252:253], v[4:5], v[76:77] neg_lo:[1,0] neg_hi:[1,0]
	v_pk_add_f32 v[242:243], v[242:243], v[244:245]
	ds_read_b128 v[70:73], v1 offset:42720
	s_waitcnt lgkmcnt(14)
	v_pk_fma_f32 v[250:251], v[6:7], v[78:79], v[250:251] neg_lo:[1,0,0] neg_hi:[1,0,0]
	v_add_f32_e32 v242, v242, v243
	v_pk_fma_f32 v[252:253], v[8:9], v[80:81], v[252:253] neg_lo:[1,0,0] neg_hi:[1,0,0]
	v_add_f32_e32 v28, v28, v242
	ds_read_b128 v[74:77], v1 offset:42736
	s_waitcnt lgkmcnt(14)
	v_pk_fma_f32 v[250:251], v[10:11], v[82:83], v[250:251] neg_lo:[1,0,0] neg_hi:[1,0,0]
	v_pk_fma_f32 v[252:253], v[12:13], v[84:85], v[252:253] neg_lo:[1,0,0] neg_hi:[1,0,0]
	ds_read_b128 v[78:81], v1 offset:42752
	s_waitcnt lgkmcnt(14)
	v_pk_fma_f32 v[250:251], v[14:15], v[86:87], v[250:251] neg_lo:[1,0,0] neg_hi:[1,0,0]
	v_pk_fma_f32 v[252:253], v[16:17], v[88:89], v[252:253] neg_lo:[1,0,0] neg_hi:[1,0,0]
	ds_read_b128 v[82:85], v1 offset:42768
	s_waitcnt lgkmcnt(14)
	v_pk_fma_f32 v[250:251], v[18:19], v[116:117], v[250:251] neg_lo:[1,0,0] neg_hi:[1,0,0]
	v_pk_fma_f32 v[252:253], v[20:21], v[118:119], v[252:253] neg_lo:[1,0,0] neg_hi:[1,0,0]
	ds_read_b128 v[86:89], v1 offset:42784
	s_waitcnt lgkmcnt(14)
	v_pk_fma_f32 v[250:251], v[22:23], v[120:121], v[250:251] neg_lo:[1,0,0] neg_hi:[1,0,0]
	v_pk_fma_f32 v[252:253], v[24:25], v[122:123], v[252:253] neg_lo:[1,0,0] neg_hi:[1,0,0]
	ds_read_b128 v[116:119], v1 offset:42800
	s_waitcnt lgkmcnt(14)
	v_pk_fma_f32 v[250:251], v[26:27], v[124:125], v[250:251] neg_lo:[1,0,0] neg_hi:[1,0,0]
	v_pk_fma_f32 v[252:253], v[28:29], v[126:127], v[252:253] neg_lo:[1,0,0] neg_hi:[1,0,0]
	ds_read_b128 v[120:123], v1 offset:42816
	s_waitcnt lgkmcnt(14)
	v_pk_mul_f32 v[242:243], v[2:3], v[128:129] neg_lo:[1,0] neg_hi:[1,0]
	v_pk_mul_f32 v[244:245], v[4:5], v[130:131] neg_lo:[1,0] neg_hi:[1,0]
	v_pk_add_f32 v[250:251], v[250:251], v[252:253]
	ds_read_b128 v[124:127], v1 offset:42976
	s_waitcnt lgkmcnt(14)
	v_pk_fma_f32 v[242:243], v[6:7], v[132:133], v[242:243] neg_lo:[1,0,0] neg_hi:[1,0,0]
	v_add_f32_e32 v250, v250, v251
	v_pk_fma_f32 v[244:245], v[8:9], v[134:135], v[244:245] neg_lo:[1,0,0] neg_hi:[1,0,0]
	v_add_f32_e32 v29, v29, v250
	ds_read_b128 v[128:131], v1 offset:42992
	s_waitcnt lgkmcnt(14)
	v_pk_fma_f32 v[242:243], v[10:11], v[136:137], v[242:243] neg_lo:[1,0,0] neg_hi:[1,0,0]
	v_pk_fma_f32 v[244:245], v[12:13], v[138:139], v[244:245] neg_lo:[1,0,0] neg_hi:[1,0,0]
	ds_read_b128 v[132:135], v1 offset:43008
	s_waitcnt lgkmcnt(14)
	v_pk_fma_f32 v[242:243], v[14:15], v[140:141], v[242:243] neg_lo:[1,0,0] neg_hi:[1,0,0]
	v_pk_fma_f32 v[244:245], v[16:17], v[142:143], v[244:245] neg_lo:[1,0,0] neg_hi:[1,0,0]
	ds_read_b128 v[136:139], v1 offset:43024
	s_waitcnt lgkmcnt(14)
	v_pk_fma_f32 v[242:243], v[18:19], v[200:201], v[242:243] neg_lo:[1,0,0] neg_hi:[1,0,0]
	v_pk_fma_f32 v[244:245], v[20:21], v[202:203], v[244:245] neg_lo:[1,0,0] neg_hi:[1,0,0]
	ds_read_b128 v[140:143], v1 offset:43040
	s_waitcnt lgkmcnt(14)
	v_pk_fma_f32 v[242:243], v[22:23], v[204:205], v[242:243] neg_lo:[1,0,0] neg_hi:[1,0,0]
	v_pk_fma_f32 v[244:245], v[24:25], v[206:207], v[244:245] neg_lo:[1,0,0] neg_hi:[1,0,0]
	ds_read_b128 v[200:203], v1 offset:43056
	s_waitcnt lgkmcnt(14)
	v_pk_fma_f32 v[242:243], v[26:27], v[246:247], v[242:243] neg_lo:[1,0,0] neg_hi:[1,0,0]
	v_pk_fma_f32 v[244:245], v[28:29], v[248:249], v[244:245] neg_lo:[1,0,0] neg_hi:[1,0,0]
	ds_read_b128 v[204:207], v1 offset:43072
	s_waitcnt lgkmcnt(14)
	v_pk_mul_f32 v[250:251], v[2:3], v[66:67] neg_lo:[1,0] neg_hi:[1,0]
	v_pk_mul_f32 v[252:253], v[4:5], v[68:69] neg_lo:[1,0] neg_hi:[1,0]
	v_pk_add_f32 v[242:243], v[242:243], v[244:245]
	ds_read_b128 v[246:249], v1 offset:43088
	s_waitcnt lgkmcnt(14)
	v_pk_fma_f32 v[250:251], v[6:7], v[70:71], v[250:251] neg_lo:[1,0,0] neg_hi:[1,0,0]
	v_add_f32_e32 v242, v242, v243
	v_pk_fma_f32 v[252:253], v[8:9], v[72:73], v[252:253] neg_lo:[1,0,0] neg_hi:[1,0,0]
	v_add_f32_e32 v30, v30, v242
	ds_read_b128 v[66:69], v1 offset:43248
	s_waitcnt lgkmcnt(14)
	v_pk_fma_f32 v[250:251], v[10:11], v[74:75], v[250:251] neg_lo:[1,0,0] neg_hi:[1,0,0]
	v_pk_fma_f32 v[252:253], v[12:13], v[76:77], v[252:253] neg_lo:[1,0,0] neg_hi:[1,0,0]
	ds_read_b128 v[70:73], v1 offset:43264
	s_waitcnt lgkmcnt(14)
	v_pk_fma_f32 v[250:251], v[14:15], v[78:79], v[250:251] neg_lo:[1,0,0] neg_hi:[1,0,0]
	v_pk_fma_f32 v[252:253], v[16:17], v[80:81], v[252:253] neg_lo:[1,0,0] neg_hi:[1,0,0]
	ds_read_b128 v[74:77], v1 offset:43280
	s_waitcnt lgkmcnt(14)
	v_pk_fma_f32 v[250:251], v[18:19], v[82:83], v[250:251] neg_lo:[1,0,0] neg_hi:[1,0,0]
	v_pk_fma_f32 v[252:253], v[20:21], v[84:85], v[252:253] neg_lo:[1,0,0] neg_hi:[1,0,0]
	ds_read_b128 v[78:81], v1 offset:43296
	s_waitcnt lgkmcnt(14)
	v_pk_fma_f32 v[250:251], v[22:23], v[86:87], v[250:251] neg_lo:[1,0,0] neg_hi:[1,0,0]
	v_pk_fma_f32 v[252:253], v[24:25], v[88:89], v[252:253] neg_lo:[1,0,0] neg_hi:[1,0,0]
	ds_read_b128 v[82:85], v1 offset:43312
	s_waitcnt lgkmcnt(14)
	v_pk_fma_f32 v[250:251], v[26:27], v[116:117], v[250:251] neg_lo:[1,0,0] neg_hi:[1,0,0]
	v_pk_fma_f32 v[252:253], v[28:29], v[118:119], v[252:253] neg_lo:[1,0,0] neg_hi:[1,0,0]
	ds_read_b128 v[86:89], v1 offset:43328
	s_waitcnt lgkmcnt(14)
; #define SUB_LROW(buf, i_, j0_, n_) do { _Pragma("unroll") for (int j4 = 0; j4 < (n_); ++j4) buf[j4] = *(const f32x4*)(Ls + (i_) * 68 + 4 * ((j0_) + j4)); } while (0)
; #define SUB_FROW(buf, j0_, n_) do { _Pragma("unroll") for (int j4 = 0; j4 < (n_); ++j4) { const f32x4 l = buf[j4]; \
;                 acc -= l.x * x[4 * ((j0_) + j4)]; acc -= l.y * x[4 * ((j0_) + j4) + 1]; acc -= l.z * x[4 * ((j0_) + j4) + 2]; acc -= l.w * x[4 * ((j0_) + j4) + 3]; } } while (0)
; __device__ __forceinline__ void gdn_prep(KA a, int layer, unsigned char* lds, const int tid_, const int bid_) {
;     ...
;             SUB_LROW(bufA, 1, 0, 1);
; #pragma unroll
;             for (int i = 1; i <= 32; ++i) {
;                 const int nn = (i + 4) / 4 < 8 ? (i + 4) / 4 : 8;
;                 float acc = x[i];
;                 if (i & 1) { SUB_LROW(bufB, i + 1, 0, nn); __builtin_amdgcn_sched_barrier(0); SUB_FROW(bufA, 0, (i + 3) / 4); }
;                 else       { SUB_LROW(bufA, i + 1, 0, nn); __builtin_amdgcn_sched_barrier(0); SUB_FROW(bufB, 0, (i + 3) / 4); }
;                 x[i] = acc;
;                 __builtin_amdgcn_sched_barrier(0);
;             }
	v_pk_fma_f32 v[250:251], v[30:31], v[120:121], v[250:251] neg_lo:[1,0,0] neg_hi:[1,0,0]
	v_pk_fma_f32 v[252:253], v[32:33], v[122:123], v[252:253] neg_lo:[1,0,0] neg_hi:[1,0,0]
	ds_read_b128 v[116:119], v1 offset:43344
	s_waitcnt lgkmcnt(14)
	v_pk_mul_f32 v[242:243], v[2:3], v[124:125] neg_lo:[1,0] neg_hi:[1,0]
	v_pk_mul_f32 v[244:245], v[4:5], v[126:127] neg_lo:[1,0] neg_hi:[1,0]
	v_pk_add_f32 v[250:251], v[250:251], v[252:253]
	ds_read_b128 v[120:123], v1 offset:43360
	s_waitcnt lgkmcnt(14)
	v_pk_fma_f32 v[242:243], v[6:7], v[128:129], v[242:243] neg_lo:[1,0,0] neg_hi:[1,0,0]
	v_add_f32_e32 v250, v250, v251
	v_pk_fma_f32 v[244:245], v[8:9], v[130:131], v[244:245] neg_lo:[1,0,0] neg_hi:[1,0,0]
	v_add_f32_e32 v31, v31, v250
	ds_read_b128 v[124:127], v1 offset:43520
	s_waitcnt lgkmcnt(14)
	v_pk_fma_f32 v[242:243], v[10:11], v[132:133], v[242:243] neg_lo:[1,0,0] neg_hi:[1,0,0]
	v_pk_fma_f32 v[244:245], v[12:13], v[134:135], v[244:245] neg_lo:[1,0,0] neg_hi:[1,0,0]
	ds_read_b128 v[128:131], v1 offset:43536
	s_waitcnt lgkmcnt(14)
	v_pk_fma_f32 v[242:243], v[14:15], v[136:137], v[242:243] neg_lo:[1,0,0] neg_hi:[1,0,0]
	v_pk_fma_f32 v[244:245], v[16:17], v[138:139], v[244:245] neg_lo:[1,0,0] neg_hi:[1,0,0]
	ds_read_b128 v[132:135], v1 offset:43552
	s_waitcnt lgkmcnt(14)
	v_pk_fma_f32 v[242:243], v[18:19], v[140:141], v[242:243] neg_lo:[1,0,0] neg_hi:[1,0,0]
	v_pk_fma_f32 v[244:245], v[20:21], v[142:143], v[244:245] neg_lo:[1,0,0] neg_hi:[1,0,0]
	ds_read_b128 v[136:139], v1 offset:43568
	s_waitcnt lgkmcnt(14)
	v_pk_fma_f32 v[242:243], v[22:23], v[200:201], v[242:243] neg_lo:[1,0,0] neg_hi:[1,0,0]
	v_pk_fma_f32 v[244:245], v[24:25], v[202:203], v[244:245] neg_lo:[1,0,0] neg_hi:[1,0,0]
	ds_read_b128 v[140:143], v1 offset:43584
	s_waitcnt lgkmcnt(14)
	v_pk_fma_f32 v[242:243], v[26:27], v[204:205], v[242:243] neg_lo:[1,0,0] neg_hi:[1,0,0]
	v_pk_fma_f32 v[244:245], v[28:29], v[206:207], v[244:245] neg_lo:[1,0,0] neg_hi:[1,0,0]
	ds_read_b128 v[200:203], v1 offset:43600
	s_waitcnt lgkmcnt(14)
	v_pk_fma_f32 v[242:243], v[30:31], v[246:247], v[242:243] neg_lo:[1,0,0] neg_hi:[1,0,0]
	v_pk_fma_f32 v[244:245], v[32:33], v[248:249], v[244:245] neg_lo:[1,0,0] neg_hi:[1,0,0]
	ds_read_b128 v[204:207], v1 offset:43616
	s_waitcnt lgkmcnt(14)
	v_pk_mul_f32 v[250:251], v[2:3], v[66:67] neg_lo:[1,0] neg_hi:[1,0]
	v_pk_mul_f32 v[252:253], v[4:5], v[68:69] neg_lo:[1,0] neg_hi:[1,0]
	v_pk_add_f32 v[242:243], v[242:243], v[244:245]
	ds_read_b128 v[246:249], v1 offset:43632
	s_waitcnt lgkmcnt(14)
	v_pk_fma_f32 v[250:251], v[6:7], v[70:71], v[250:251] neg_lo:[1,0,0] neg_hi:[1,0,0]
	v_add_f32_e32 v242, v242, v243
	v_pk_fma_f32 v[252:253], v[8:9], v[72:73], v[252:253] neg_lo:[1,0,0] neg_hi:[1,0,0]
	v_add_f32_e32 v32, v32, v242
	ds_read_b128 v[66:69], v1 offset:43792
	s_waitcnt lgkmcnt(14)
	v_pk_fma_f32 v[250:251], v[10:11], v[74:75], v[250:251] neg_lo:[1,0,0] neg_hi:[1,0,0]
	v_pk_fma_f32 v[252:253], v[12:13], v[76:77], v[252:253] neg_lo:[1,0,0] neg_hi:[1,0,0]
	ds_read_b128 v[70:73], v1 offset:43808
	s_waitcnt lgkmcnt(14)
	v_pk_fma_f32 v[250:251], v[14:15], v[78:79], v[250:251] neg_lo:[1,0,0] neg_hi:[1,0,0]
	v_pk_fma_f32 v[252:253], v[16:17], v[80:81], v[252:253] neg_lo:[1,0,0] neg_hi:[1,0,0]
	ds_read_b128 v[74:77], v1 offset:43824
	s_waitcnt lgkmcnt(14)
	v_pk_fma_f32 v[250:251], v[18:19], v[82:83], v[250:251] neg_lo:[1,0,0] neg_hi:[1,0,0]
	v_pk_fma_f32 v[252:253], v[20:21], v[84:85], v[252:253] neg_lo:[1,0,0] neg_hi:[1,0,0]
	ds_read_b128 v[78:81], v1 offset:43840
	s_waitcnt lgkmcnt(14)
	v_pk_fma_f32 v[250:251], v[22:23], v[86:87], v[250:251] neg_lo:[1,0,0] neg_hi:[1,0,0]
	v_pk_fma_f32 v[252:253], v[24:25], v[88:89], v[252:253] neg_lo:[1,0,0] neg_hi:[1,0,0]
	ds_read_b128 v[82:85], v1 offset:43856
	s_waitcnt lgkmcnt(14)
	v_pk_fma_f32 v[250:251], v[26:27], v[116:117], v[250:251] neg_lo:[1,0,0] neg_hi:[1,0,0]
	v_pk_fma_f32 v[252:253], v[28:29], v[118:119], v[252:253] neg_lo:[1,0,0] neg_hi:[1,0,0]
	ds_read_b128 v[86:89], v1 offset:43872
	s_waitcnt lgkmcnt(14)
	v_pk_fma_f32 v[250:251], v[30:31], v[120:121], v[250:251] neg_lo:[1,0,0] neg_hi:[1,0,0]
	v_pk_fma_f32 v[252:253], v[32:33], v[122:123], v[252:253] neg_lo:[1,0,0] neg_hi:[1,0,0]
	ds_read_b128 v[116:119], v1 offset:43888
	s_waitcnt lgkmcnt(14)
	v_pk_mul_f32 v[242:243], v[2:3], v[124:125] neg_lo:[1,0] neg_hi:[1,0]
	v_pk_mul_f32 v[244:245], v[4:5], v[126:127] neg_lo:[1,0] neg_hi:[1,0]
	v_pk_add_f32 v[250:251], v[250:251], v[252:253]
	ds_read_b128 v[120:123], v1 offset:43904
	s_waitcnt lgkmcnt(14)
	v_pk_fma_f32 v[242:243], v[6:7], v[128:129], v[242:243] neg_lo:[1,0,0] neg_hi:[1,0,0]
	v_add_f32_e32 v250, v250, v251
	v_pk_fma_f32 v[244:245], v[8:9], v[130:131], v[244:245] neg_lo:[1,0,0] neg_hi:[1,0,0]
	v_add_f32_e32 v33, v33, v250
	ds_read_b128 v[124:127], v1 offset:43920
	s_waitcnt lgkmcnt(14)
	v_pk_fma_f32 v[242:243], v[10:11], v[132:133], v[242:243] neg_lo:[1,0,0] neg_hi:[1,0,0]
	v_pk_fma_f32 v[244:245], v[12:13], v[134:135], v[244:245] neg_lo:[1,0,0] neg_hi:[1,0,0]
	ds_read_b128 v[128:131], v1 offset:44064
	s_waitcnt lgkmcnt(14)
	v_pk_fma_f32 v[242:243], v[14:15], v[136:137], v[242:243] neg_lo:[1,0,0] neg_hi:[1,0,0]
	v_pk_fma_f32 v[244:245], v[16:17], v[138:139], v[244:245] neg_lo:[1,0,0] neg_hi:[1,0,0]
	ds_read_b128 v[132:135], v1 offset:44080
	s_waitcnt lgkmcnt(14)
	v_pk_fma_f32 v[242:243], v[18:19], v[140:141], v[242:243] neg_lo:[1,0,0] neg_hi:[1,0,0]
	v_pk_fma_f32 v[244:245], v[20:21], v[142:143], v[244:245] neg_lo:[1,0,0] neg_hi:[1,0,0]
	ds_read_b128 v[136:139], v1 offset:44096
	s_waitcnt lgkmcnt(14)
; #define SUB_LROW(buf, i_, j0_, n_) do { _Pragma("unroll") for (int j4 = 0; j4 < (n_); ++j4) buf[j4] = *(const f32x4*)(Ls + (i_) * 68 + 4 * ((j0_) + j4)); } while (0)
; #define SUB_FROW(buf, j0_, n_) do { _Pragma("unroll") for (int j4 = 0; j4 < (n_); ++j4) { const f32x4 l = buf[j4]; \
;                 acc -= l.x * x[4 * ((j0_) + j4)]; acc -= l.y * x[4 * ((j0_) + j4) + 1]; acc -= l.z * x[4 * ((j0_) + j4) + 2]; acc -= l.w * x[4 * ((j0_) + j4) + 3]; } } while (0)
; __device__ __forceinline__ void gdn_prep(KA a, int layer, unsigned char* lds, const int tid_, const int bid_) {
;     ...
;             SUB_LROW(bufA, 1, 0, 1);
; #pragma unroll
;             for (int i = 1; i <= 32; ++i) {
;                 const int nn = (i + 4) / 4 < 8 ? (i + 4) / 4 : 8;
;                 float acc = x[i];
;                 if (i & 1) { SUB_LROW(bufB, i + 1, 0, nn); __builtin_amdgcn_sched_barrier(0); SUB_FROW(bufA, 0, (i + 3) / 4); }
;                 else       { SUB_LROW(bufA, i + 1, 0, nn); __builtin_amdgcn_sched_barrier(0); SUB_FROW(bufB, 0, (i + 3) / 4); }
;                 x[i] = acc;
;                 __builtin_amdgcn_sched_barrier(0);
;             }
; #pragma unroll
;             for (int i = 33; i < 64; ++i) {
;                 float acc = x[i];
;                 SUB_LROW(bufB, i, 8, (i + 3) / 4 - 8); __builtin_amdgcn_sched_barrier(0);
;                 SUB_FROW(bufA, 0, 8); __builtin_amdgcn_sched_barrier(0);
;                 if (i + 1 < 64) SUB_LROW(bufA, i + 1, 0, 8);
;                 __builtin_amdgcn_sched_barrier(0);
;                 SUB_FROW(bufB, 8, (i + 3) / 4 - 8);
;                 x[i] = acc;
;                 __builtin_amdgcn_sched_barrier(0);
;             }
	v_pk_fma_f32 v[242:243], v[22:23], v[200:201], v[242:243] neg_lo:[1,0,0] neg_hi:[1,0,0]
	v_pk_fma_f32 v[244:245], v[24:25], v[202:203], v[244:245] neg_lo:[1,0,0] neg_hi:[1,0,0]
	ds_read_b128 v[140:143], v1 offset:44112
	s_waitcnt lgkmcnt(14)
	v_pk_fma_f32 v[242:243], v[26:27], v[204:205], v[242:243] neg_lo:[1,0,0] neg_hi:[1,0,0]
	v_pk_fma_f32 v[244:245], v[28:29], v[206:207], v[244:245] neg_lo:[1,0,0] neg_hi:[1,0,0]
	ds_read_b128 v[200:203], v1 offset:44128
	s_waitcnt lgkmcnt(14)
	v_pk_fma_f32 v[242:243], v[30:31], v[246:247], v[242:243] neg_lo:[1,0,0] neg_hi:[1,0,0]
	v_pk_fma_f32 v[244:245], v[32:33], v[248:249], v[244:245] neg_lo:[1,0,0] neg_hi:[1,0,0]
	ds_read_b128 v[204:207], v1 offset:44144
	s_waitcnt lgkmcnt(14)
	v_pk_mul_f32 v[250:251], v[2:3], v[66:67] neg_lo:[1,0] neg_hi:[1,0]
	v_pk_mul_f32 v[252:253], v[4:5], v[68:69] neg_lo:[1,0] neg_hi:[1,0]
	v_pk_add_f32 v[242:243], v[242:243], v[244:245]
	ds_read_b128 v[246:249], v1 offset:44160
	s_waitcnt lgkmcnt(14)
	v_pk_fma_f32 v[250:251], v[6:7], v[70:71], v[250:251] neg_lo:[1,0,0] neg_hi:[1,0,0]
	v_add_f32_e32 v242, v242, v243
	v_pk_fma_f32 v[252:253], v[8:9], v[72:73], v[252:253] neg_lo:[1,0,0] neg_hi:[1,0,0]
	v_add_f32_e32 v34, v34, v242
	ds_read_b128 v[66:69], v1 offset:44176
	s_waitcnt lgkmcnt(14)
	v_pk_fma_f32 v[250:251], v[10:11], v[74:75], v[250:251] neg_lo:[1,0,0] neg_hi:[1,0,0]
	v_pk_fma_f32 v[252:253], v[12:13], v[76:77], v[252:253] neg_lo:[1,0,0] neg_hi:[1,0,0]
	ds_read_b128 v[70:73], v1 offset:44192
	s_waitcnt lgkmcnt(14)
	v_pk_fma_f32 v[250:251], v[14:15], v[78:79], v[250:251] neg_lo:[1,0,0] neg_hi:[1,0,0]
	v_pk_fma_f32 v[252:253], v[16:17], v[80:81], v[252:253] neg_lo:[1,0,0] neg_hi:[1,0,0]
	ds_read_b128 v[74:77], v1 offset:44336
	s_waitcnt lgkmcnt(14)
	v_pk_fma_f32 v[250:251], v[18:19], v[82:83], v[250:251] neg_lo:[1,0,0] neg_hi:[1,0,0]
	v_pk_fma_f32 v[252:253], v[20:21], v[84:85], v[252:253] neg_lo:[1,0,0] neg_hi:[1,0,0]
	ds_read_b128 v[78:81], v1 offset:44352
	s_waitcnt lgkmcnt(14)
	v_pk_fma_f32 v[250:251], v[22:23], v[86:87], v[250:251] neg_lo:[1,0,0] neg_hi:[1,0,0]
	v_pk_fma_f32 v[252:253], v[24:25], v[88:89], v[252:253] neg_lo:[1,0,0] neg_hi:[1,0,0]
	ds_read_b128 v[82:85], v1 offset:44368
	s_waitcnt lgkmcnt(14)
	v_pk_fma_f32 v[250:251], v[26:27], v[116:117], v[250:251] neg_lo:[1,0,0] neg_hi:[1,0,0]
	v_pk_fma_f32 v[252:253], v[28:29], v[118:119], v[252:253] neg_lo:[1,0,0] neg_hi:[1,0,0]
	ds_read_b128 v[86:89], v1 offset:44384
	s_waitcnt lgkmcnt(14)
	v_pk_fma_f32 v[250:251], v[30:31], v[120:121], v[250:251] neg_lo:[1,0,0] neg_hi:[1,0,0]
	v_pk_fma_f32 v[252:253], v[32:33], v[122:123], v[252:253] neg_lo:[1,0,0] neg_hi:[1,0,0]
	ds_read_b128 v[116:119], v1 offset:44400
	s_waitcnt lgkmcnt(14)
	v_pk_fma_f32 v[250:251], v[34:35], v[124:125], v[250:251] neg_lo:[1,0,0] neg_hi:[1,0,0]
	v_pk_fma_f32 v[252:253], v[36:37], v[126:127], v[252:253] neg_lo:[1,0,0] neg_hi:[1,0,0]
	ds_read_b128 v[120:123], v1 offset:44416
	s_waitcnt lgkmcnt(14)
	v_pk_mul_f32 v[242:243], v[2:3], v[128:129] neg_lo:[1,0] neg_hi:[1,0]
	v_pk_mul_f32 v[244:245], v[4:5], v[130:131] neg_lo:[1,0] neg_hi:[1,0]
	v_pk_add_f32 v[250:251], v[250:251], v[252:253]
	ds_read_b128 v[124:127], v1 offset:44432
	s_waitcnt lgkmcnt(14)
	v_pk_fma_f32 v[242:243], v[6:7], v[132:133], v[242:243] neg_lo:[1,0,0] neg_hi:[1,0,0]
	v_add_f32_e32 v250, v250, v251
	v_pk_fma_f32 v[244:245], v[8:9], v[134:135], v[244:245] neg_lo:[1,0,0] neg_hi:[1,0,0]
	v_add_f32_e32 v35, v35, v250
	ds_read_b128 v[128:131], v1 offset:44448
	s_waitcnt lgkmcnt(14)
	v_pk_fma_f32 v[242:243], v[10:11], v[136:137], v[242:243] neg_lo:[1,0,0] neg_hi:[1,0,0]
	v_pk_fma_f32 v[244:245], v[12:13], v[138:139], v[244:245] neg_lo:[1,0,0] neg_hi:[1,0,0]
	ds_read_b128 v[132:135], v1 offset:44464
	s_waitcnt lgkmcnt(14)
	v_pk_fma_f32 v[242:243], v[14:15], v[140:141], v[242:243] neg_lo:[1,0,0] neg_hi:[1,0,0]
	v_pk_fma_f32 v[244:245], v[16:17], v[142:143], v[244:245] neg_lo:[1,0,0] neg_hi:[1,0,0]
	ds_read_b128 v[136:139], v1 offset:44608
	s_waitcnt lgkmcnt(14)
	v_pk_fma_f32 v[242:243], v[18:19], v[200:201], v[242:243] neg_lo:[1,0,0] neg_hi:[1,0,0]
	v_pk_fma_f32 v[244:245], v[20:21], v[202:203], v[244:245] neg_lo:[1,0,0] neg_hi:[1,0,0]
	ds_read_b128 v[140:143], v1 offset:44624
	s_waitcnt lgkmcnt(14)
	v_pk_fma_f32 v[242:243], v[22:23], v[204:205], v[242:243] neg_lo:[1,0,0] neg_hi:[1,0,0]
	v_pk_fma_f32 v[244:245], v[24:25], v[206:207], v[244:245] neg_lo:[1,0,0] neg_hi:[1,0,0]
	ds_read_b128 v[200:203], v1 offset:44640
	s_waitcnt lgkmcnt(14)
	v_pk_fma_f32 v[242:243], v[26:27], v[246:247], v[242:243] neg_lo:[1,0,0] neg_hi:[1,0,0]
	v_pk_fma_f32 v[244:245], v[28:29], v[248:249], v[244:245] neg_lo:[1,0,0] neg_hi:[1,0,0]
	ds_read_b128 v[204:207], v1 offset:44656
	s_waitcnt lgkmcnt(14)
	v_pk_fma_f32 v[242:243], v[30:31], v[66:67], v[242:243] neg_lo:[1,0,0] neg_hi:[1,0,0]
	v_pk_fma_f32 v[244:245], v[32:33], v[68:69], v[244:245] neg_lo:[1,0,0] neg_hi:[1,0,0]
	ds_read_b128 v[246:249], v1 offset:44672
	s_waitcnt lgkmcnt(14)
	v_pk_fma_f32 v[242:243], v[34:35], v[70:71], v[242:243] neg_lo:[1,0,0] neg_hi:[1,0,0]
	v_pk_fma_f32 v[244:245], v[36:37], v[72:73], v[244:245] neg_lo:[1,0,0] neg_hi:[1,0,0]
	ds_read_b128 v[66:69], v1 offset:44688
	s_waitcnt lgkmcnt(14)
	v_pk_mul_f32 v[250:251], v[2:3], v[74:75] neg_lo:[1,0] neg_hi:[1,0]
	v_pk_mul_f32 v[252:253], v[4:5], v[76:77] neg_lo:[1,0] neg_hi:[1,0]
	v_pk_add_f32 v[242:243], v[242:243], v[244:245]
	ds_read_b128 v[70:73], v1 offset:44704
	s_waitcnt lgkmcnt(14)
	v_pk_fma_f32 v[250:251], v[6:7], v[78:79], v[250:251] neg_lo:[1,0,0] neg_hi:[1,0,0]
	v_add_f32_e32 v242, v242, v243
	v_pk_fma_f32 v[252:253], v[8:9], v[80:81], v[252:253] neg_lo:[1,0,0] neg_hi:[1,0,0]
	v_add_f32_e32 v36, v36, v242
	ds_read_b128 v[74:77], v1 offset:44720
	s_waitcnt lgkmcnt(14)
; #define SUB_LROW(buf, i_, j0_, n_) do { _Pragma("unroll") for (int j4 = 0; j4 < (n_); ++j4) buf[j4] = *(const f32x4*)(Ls + (i_) * 68 + 4 * ((j0_) + j4)); } while (0)
; #define SUB_FROW(buf, j0_, n_) do { _Pragma("unroll") for (int j4 = 0; j4 < (n_); ++j4) { const f32x4 l = buf[j4]; \
;                 acc -= l.x * x[4 * ((j0_) + j4)]; acc -= l.y * x[4 * ((j0_) + j4) + 1]; acc -= l.z * x[4 * ((j0_) + j4) + 2]; acc -= l.w * x[4 * ((j0_) + j4) + 3]; } } while (0)
; __device__ __forceinline__ void gdn_prep(KA a, int layer, unsigned char* lds, const int tid_, const int bid_) {
;     ...
;             for (int i = 33; i < 64; ++i) {
;                 float acc = x[i];
;                 SUB_LROW(bufB, i, 8, (i + 3) / 4 - 8); __builtin_amdgcn_sched_barrier(0);
;                 SUB_FROW(bufA, 0, 8); __builtin_amdgcn_sched_barrier(0);
;                 if (i + 1 < 64) SUB_LROW(bufA, i + 1, 0, 8);
;                 __builtin_amdgcn_sched_barrier(0);
;                 SUB_FROW(bufB, 8, (i + 3) / 4 - 8);
;                 x[i] = acc;
;                 __builtin_amdgcn_sched_barrier(0);
;             }
	v_pk_fma_f32 v[250:251], v[10:11], v[82:83], v[250:251] neg_lo:[1,0,0] neg_hi:[1,0,0]
	v_pk_fma_f32 v[252:253], v[12:13], v[84:85], v[252:253] neg_lo:[1,0,0] neg_hi:[1,0,0]
	ds_read_b128 v[78:81], v1 offset:44736
	s_waitcnt lgkmcnt(14)
	v_pk_fma_f32 v[250:251], v[14:15], v[86:87], v[250:251] neg_lo:[1,0,0] neg_hi:[1,0,0]
	v_pk_fma_f32 v[252:253], v[16:17], v[88:89], v[252:253] neg_lo:[1,0,0] neg_hi:[1,0,0]
	ds_read_b128 v[82:85], v1 offset:44880
	s_waitcnt lgkmcnt(14)
	v_pk_fma_f32 v[250:251], v[18:19], v[116:117], v[250:251] neg_lo:[1,0,0] neg_hi:[1,0,0]
	v_pk_fma_f32 v[252:253], v[20:21], v[118:119], v[252:253] neg_lo:[1,0,0] neg_hi:[1,0,0]
	ds_read_b128 v[86:89], v1 offset:44896
	s_waitcnt lgkmcnt(14)
	v_pk_fma_f32 v[250:251], v[22:23], v[120:121], v[250:251] neg_lo:[1,0,0] neg_hi:[1,0,0]
	v_pk_fma_f32 v[252:253], v[24:25], v[122:123], v[252:253] neg_lo:[1,0,0] neg_hi:[1,0,0]
	ds_read_b128 v[116:119], v1 offset:44912
	s_waitcnt lgkmcnt(14)
	v_pk_fma_f32 v[250:251], v[26:27], v[124:125], v[250:251] neg_lo:[1,0,0] neg_hi:[1,0,0]
	v_pk_fma_f32 v[252:253], v[28:29], v[126:127], v[252:253] neg_lo:[1,0,0] neg_hi:[1,0,0]
	ds_read_b128 v[120:123], v1 offset:44928
	s_waitcnt lgkmcnt(14)
	v_pk_fma_f32 v[250:251], v[30:31], v[128:129], v[250:251] neg_lo:[1,0,0] neg_hi:[1,0,0]
	v_pk_fma_f32 v[252:253], v[32:33], v[130:131], v[252:253] neg_lo:[1,0,0] neg_hi:[1,0,0]
	ds_read_b128 v[124:127], v1 offset:44944
	s_waitcnt lgkmcnt(14)
	v_pk_fma_f32 v[250:251], v[34:35], v[132:133], v[250:251] neg_lo:[1,0,0] neg_hi:[1,0,0]
	v_pk_fma_f32 v[252:253], v[36:37], v[134:135], v[252:253] neg_lo:[1,0,0] neg_hi:[1,0,0]
	ds_read_b128 v[128:131], v1 offset:44960
	s_waitcnt lgkmcnt(14)
	v_pk_mul_f32 v[242:243], v[2:3], v[136:137] neg_lo:[1,0] neg_hi:[1,0]
	v_pk_mul_f32 v[244:245], v[4:5], v[138:139] neg_lo:[1,0] neg_hi:[1,0]
	v_pk_add_f32 v[250:251], v[250:251], v[252:253]
	ds_read_b128 v[132:135], v1 offset:44976
	s_waitcnt lgkmcnt(14)
	v_pk_fma_f32 v[242:243], v[6:7], v[140:141], v[242:243] neg_lo:[1,0,0] neg_hi:[1,0,0]
	v_add_f32_e32 v250, v250, v251
	v_pk_fma_f32 v[244:245], v[8:9], v[142:143], v[244:245] neg_lo:[1,0,0] neg_hi:[1,0,0]
	v_add_f32_e32 v37, v37, v250
	ds_read_b128 v[136:139], v1 offset:44992
	s_waitcnt lgkmcnt(14)
	v_pk_fma_f32 v[242:243], v[10:11], v[200:201], v[242:243] neg_lo:[1,0,0] neg_hi:[1,0,0]
	v_pk_fma_f32 v[244:245], v[12:13], v[202:203], v[244:245] neg_lo:[1,0,0] neg_hi:[1,0,0]
	ds_read_b128 v[140:143], v1 offset:45008
	s_waitcnt lgkmcnt(14)
	v_pk_fma_f32 v[242:243], v[14:15], v[204:205], v[242:243] neg_lo:[1,0,0] neg_hi:[1,0,0]
	v_pk_fma_f32 v[244:245], v[16:17], v[206:207], v[244:245] neg_lo:[1,0,0] neg_hi:[1,0,0]
	ds_read_b128 v[200:203], v1 offset:45024
	s_waitcnt lgkmcnt(14)
	v_pk_fma_f32 v[242:243], v[18:19], v[246:247], v[242:243] neg_lo:[1,0,0] neg_hi:[1,0,0]
	v_pk_fma_f32 v[244:245], v[20:21], v[248:249], v[244:245] neg_lo:[1,0,0] neg_hi:[1,0,0]
	ds_read_b128 v[204:207], v1 offset:45152
	s_waitcnt lgkmcnt(14)
	v_pk_fma_f32 v[242:243], v[22:23], v[66:67], v[242:243] neg_lo:[1,0,0] neg_hi:[1,0,0]
	v_pk_fma_f32 v[244:245], v[24:25], v[68:69], v[244:245] neg_lo:[1,0,0] neg_hi:[1,0,0]
	ds_read_b128 v[246:249], v1 offset:45168
	s_waitcnt lgkmcnt(14)
	v_pk_fma_f32 v[242:243], v[26:27], v[70:71], v[242:243] neg_lo:[1,0,0] neg_hi:[1,0,0]
	v_pk_fma_f32 v[244:245], v[28:29], v[72:73], v[244:245] neg_lo:[1,0,0] neg_hi:[1,0,0]
	ds_read_b128 v[66:69], v1 offset:45184
	s_waitcnt lgkmcnt(14)
	v_pk_fma_f32 v[242:243], v[30:31], v[74:75], v[242:243] neg_lo:[1,0,0] neg_hi:[1,0,0]
	v_pk_fma_f32 v[244:245], v[32:33], v[76:77], v[244:245] neg_lo:[1,0,0] neg_hi:[1,0,0]
	ds_read_b128 v[70:73], v1 offset:45200
	s_waitcnt lgkmcnt(14)
	v_pk_fma_f32 v[242:243], v[34:35], v[78:79], v[242:243] neg_lo:[1,0,0] neg_hi:[1,0,0]
	v_pk_fma_f32 v[244:245], v[36:37], v[80:81], v[244:245] neg_lo:[1,0,0] neg_hi:[1,0,0]
	ds_read_b128 v[74:77], v1 offset:45216
	s_waitcnt lgkmcnt(14)
	v_pk_mul_f32 v[250:251], v[2:3], v[82:83] neg_lo:[1,0] neg_hi:[1,0]
	v_pk_mul_f32 v[252:253], v[4:5], v[84:85] neg_lo:[1,0] neg_hi:[1,0]
	v_pk_add_f32 v[242:243], v[242:243], v[244:245]
	ds_read_b128 v[78:81], v1 offset:45232
	s_waitcnt lgkmcnt(14)
	v_pk_fma_f32 v[250:251], v[6:7], v[86:87], v[250:251] neg_lo:[1,0,0] neg_hi:[1,0,0]
	v_add_f32_e32 v242, v242, v243
	v_pk_fma_f32 v[252:253], v[8:9], v[88:89], v[252:253] neg_lo:[1,0,0] neg_hi:[1,0,0]
	v_add_f32_e32 v38, v38, v242
	ds_read_b128 v[82:85], v1 offset:45248
	s_waitcnt lgkmcnt(14)
	v_pk_fma_f32 v[250:251], v[10:11], v[116:117], v[250:251] neg_lo:[1,0,0] neg_hi:[1,0,0]
	v_pk_fma_f32 v[252:253], v[12:13], v[118:119], v[252:253] neg_lo:[1,0,0] neg_hi:[1,0,0]
	ds_read_b128 v[86:89], v1 offset:45264
	s_waitcnt lgkmcnt(14)
	v_pk_fma_f32 v[250:251], v[14:15], v[120:121], v[250:251] neg_lo:[1,0,0] neg_hi:[1,0,0]
	v_pk_fma_f32 v[252:253], v[16:17], v[122:123], v[252:253] neg_lo:[1,0,0] neg_hi:[1,0,0]
	ds_read_b128 v[116:119], v1 offset:45280
	s_waitcnt lgkmcnt(14)
	v_pk_fma_f32 v[250:251], v[18:19], v[124:125], v[250:251] neg_lo:[1,0,0] neg_hi:[1,0,0]
	v_pk_fma_f32 v[252:253], v[20:21], v[126:127], v[252:253] neg_lo:[1,0,0] neg_hi:[1,0,0]
	ds_read_b128 v[120:123], v1 offset:45296
	s_waitcnt lgkmcnt(14)
	v_pk_fma_f32 v[250:251], v[22:23], v[128:129], v[250:251] neg_lo:[1,0,0] neg_hi:[1,0,0]
	v_pk_fma_f32 v[252:253], v[24:25], v[130:131], v[252:253] neg_lo:[1,0,0] neg_hi:[1,0,0]
	ds_read_b128 v[124:127], v1 offset:45424
	s_waitcnt lgkmcnt(14)
	v_pk_fma_f32 v[250:251], v[26:27], v[132:133], v[250:251] neg_lo:[1,0,0] neg_hi:[1,0,0]
	v_pk_fma_f32 v[252:253], v[28:29], v[134:135], v[252:253] neg_lo:[1,0,0] neg_hi:[1,0,0]
	ds_read_b128 v[128:131], v1 offset:45440
	s_waitcnt lgkmcnt(14)
; #define SUB_LROW(buf, i_, j0_, n_) do { _Pragma("unroll") for (int j4 = 0; j4 < (n_); ++j4) buf[j4] = *(const f32x4*)(Ls + (i_) * 68 + 4 * ((j0_) + j4)); } while (0)
; #define SUB_FROW(buf, j0_, n_) do { _Pragma("unroll") for (int j4 = 0; j4 < (n_); ++j4) { const f32x4 l = buf[j4]; \
;                 acc -= l.x * x[4 * ((j0_) + j4)]; acc -= l.y * x[4 * ((j0_) + j4) + 1]; acc -= l.z * x[4 * ((j0_) + j4) + 2]; acc -= l.w * x[4 * ((j0_) + j4) + 3]; } } while (0)
; __device__ __forceinline__ void gdn_prep(KA a, int layer, unsigned char* lds, const int tid_, const int bid_) {
;     ...
;             for (int i = 33; i < 64; ++i) {
;                 float acc = x[i];
;                 SUB_LROW(bufB, i, 8, (i + 3) / 4 - 8); __builtin_amdgcn_sched_barrier(0);
;                 SUB_FROW(bufA, 0, 8); __builtin_amdgcn_sched_barrier(0);
;                 if (i + 1 < 64) SUB_LROW(bufA, i + 1, 0, 8);
;                 __builtin_amdgcn_sched_barrier(0);
;                 SUB_FROW(bufB, 8, (i + 3) / 4 - 8);
;                 x[i] = acc;
;                 __builtin_amdgcn_sched_barrier(0);
;             }
	v_pk_fma_f32 v[250:251], v[30:31], v[136:137], v[250:251] neg_lo:[1,0,0] neg_hi:[1,0,0]
	v_pk_fma_f32 v[252:253], v[32:33], v[138:139], v[252:253] neg_lo:[1,0,0] neg_hi:[1,0,0]
	ds_read_b128 v[132:135], v1 offset:45456
	s_waitcnt lgkmcnt(14)
	v_pk_fma_f32 v[250:251], v[34:35], v[140:141], v[250:251] neg_lo:[1,0,0] neg_hi:[1,0,0]
	v_pk_fma_f32 v[252:253], v[36:37], v[142:143], v[252:253] neg_lo:[1,0,0] neg_hi:[1,0,0]
	ds_read_b128 v[136:139], v1 offset:45472
	s_waitcnt lgkmcnt(14)
	v_pk_fma_f32 v[250:251], v[38:39], v[200:201], v[250:251] neg_lo:[1,0,0] neg_hi:[1,0,0]
	v_pk_fma_f32 v[252:253], v[40:41], v[202:203], v[252:253] neg_lo:[1,0,0] neg_hi:[1,0,0]
	ds_read_b128 v[140:143], v1 offset:45488
	s_waitcnt lgkmcnt(14)
	v_pk_mul_f32 v[242:243], v[2:3], v[204:205] neg_lo:[1,0] neg_hi:[1,0]
	v_pk_mul_f32 v[244:245], v[4:5], v[206:207] neg_lo:[1,0] neg_hi:[1,0]
	v_pk_add_f32 v[250:251], v[250:251], v[252:253]
	ds_read_b128 v[200:203], v1 offset:45504
	s_waitcnt lgkmcnt(14)
	v_pk_fma_f32 v[242:243], v[6:7], v[246:247], v[242:243] neg_lo:[1,0,0] neg_hi:[1,0,0]
	v_add_f32_e32 v250, v250, v251
	v_pk_fma_f32 v[244:245], v[8:9], v[248:249], v[244:245] neg_lo:[1,0,0] neg_hi:[1,0,0]
	v_add_f32_e32 v39, v39, v250
	ds_read_b128 v[204:207], v1 offset:45520
	s_waitcnt lgkmcnt(14)
	v_pk_fma_f32 v[242:243], v[10:11], v[66:67], v[242:243] neg_lo:[1,0,0] neg_hi:[1,0,0]
	v_pk_fma_f32 v[244:245], v[12:13], v[68:69], v[244:245] neg_lo:[1,0,0] neg_hi:[1,0,0]
	ds_read_b128 v[246:249], v1 offset:45536
	s_waitcnt lgkmcnt(14)
	v_pk_fma_f32 v[242:243], v[14:15], v[70:71], v[242:243] neg_lo:[1,0,0] neg_hi:[1,0,0]
	v_pk_fma_f32 v[244:245], v[16:17], v[72:73], v[244:245] neg_lo:[1,0,0] neg_hi:[1,0,0]
	ds_read_b128 v[66:69], v1 offset:45552
	s_waitcnt lgkmcnt(14)
	v_pk_fma_f32 v[242:243], v[18:19], v[74:75], v[242:243] neg_lo:[1,0,0] neg_hi:[1,0,0]
	v_pk_fma_f32 v[244:245], v[20:21], v[76:77], v[244:245] neg_lo:[1,0,0] neg_hi:[1,0,0]
	ds_read_b128 v[70:73], v1 offset:45568
	s_waitcnt lgkmcnt(14)
	v_pk_fma_f32 v[242:243], v[22:23], v[78:79], v[242:243] neg_lo:[1,0,0] neg_hi:[1,0,0]
	v_pk_fma_f32 v[244:245], v[24:25], v[80:81], v[244:245] neg_lo:[1,0,0] neg_hi:[1,0,0]
	ds_read_b128 v[74:77], v1 offset:45696
	s_waitcnt lgkmcnt(14)
	v_pk_fma_f32 v[242:243], v[26:27], v[82:83], v[242:243] neg_lo:[1,0,0] neg_hi:[1,0,0]
	v_pk_fma_f32 v[244:245], v[28:29], v[84:85], v[244:245] neg_lo:[1,0,0] neg_hi:[1,0,0]
	ds_read_b128 v[78:81], v1 offset:45712
	s_waitcnt lgkmcnt(14)
	v_pk_fma_f32 v[242:243], v[30:31], v[86:87], v[242:243] neg_lo:[1,0,0] neg_hi:[1,0,0]
	v_pk_fma_f32 v[244:245], v[32:33], v[88:89], v[244:245] neg_lo:[1,0,0] neg_hi:[1,0,0]
	ds_read_b128 v[82:85], v1 offset:45728
	s_waitcnt lgkmcnt(14)
	v_pk_fma_f32 v[242:243], v[34:35], v[116:117], v[242:243] neg_lo:[1,0,0] neg_hi:[1,0,0]
	v_pk_fma_f32 v[244:245], v[36:37], v[118:119], v[244:245] neg_lo:[1,0,0] neg_hi:[1,0,0]
	ds_read_b128 v[86:89], v1 offset:45744
	s_waitcnt lgkmcnt(14)
	v_pk_fma_f32 v[242:243], v[38:39], v[120:121], v[242:243] neg_lo:[1,0,0] neg_hi:[1,0,0]
	v_pk_fma_f32 v[244:245], v[40:41], v[122:123], v[244:245] neg_lo:[1,0,0] neg_hi:[1,0,0]
	ds_read_b128 v[116:119], v1 offset:45760
	s_waitcnt lgkmcnt(14)
	v_pk_mul_f32 v[250:251], v[2:3], v[124:125] neg_lo:[1,0] neg_hi:[1,0]
	v_pk_mul_f32 v[252:253], v[4:5], v[126:127] neg_lo:[1,0] neg_hi:[1,0]
	v_pk_add_f32 v[242:243], v[242:243], v[244:245]
	ds_read_b128 v[120:123], v1 offset:45776
	s_waitcnt lgkmcnt(14)
	v_pk_fma_f32 v[250:251], v[6:7], v[128:129], v[250:251] neg_lo:[1,0,0] neg_hi:[1,0,0]
	v_add_f32_e32 v242, v242, v243
	v_pk_fma_f32 v[252:253], v[8:9], v[130:131], v[252:253] neg_lo:[1,0,0] neg_hi:[1,0,0]
	v_add_f32_e32 v40, v40, v242
	ds_read_b128 v[124:127], v1 offset:45792
	s_waitcnt lgkmcnt(14)
	v_pk_fma_f32 v[250:251], v[10:11], v[132:133], v[250:251] neg_lo:[1,0,0] neg_hi:[1,0,0]
	v_pk_fma_f32 v[252:253], v[12:13], v[134:135], v[252:253] neg_lo:[1,0,0] neg_hi:[1,0,0]
	ds_read_b128 v[128:131], v1 offset:45808
	s_waitcnt lgkmcnt(14)
	v_pk_fma_f32 v[250:251], v[14:15], v[136:137], v[250:251] neg_lo:[1,0,0] neg_hi:[1,0,0]
	v_pk_fma_f32 v[252:253], v[16:17], v[138:139], v[252:253] neg_lo:[1,0,0] neg_hi:[1,0,0]
	ds_read_b128 v[132:135], v1 offset:45824
	s_waitcnt lgkmcnt(14)
	v_pk_fma_f32 v[250:251], v[18:19], v[140:141], v[250:251] neg_lo:[1,0,0] neg_hi:[1,0,0]
	v_pk_fma_f32 v[252:253], v[20:21], v[142:143], v[252:253] neg_lo:[1,0,0] neg_hi:[1,0,0]
	ds_read_b128 v[136:139], v1 offset:45840
	s_waitcnt lgkmcnt(14)
	v_pk_fma_f32 v[250:251], v[22:23], v[200:201], v[250:251] neg_lo:[1,0,0] neg_hi:[1,0,0]
	v_pk_fma_f32 v[252:253], v[24:25], v[202:203], v[252:253] neg_lo:[1,0,0] neg_hi:[1,0,0]
	ds_read_b128 v[140:143], v1 offset:45968
	s_waitcnt lgkmcnt(14)
	v_pk_fma_f32 v[250:251], v[26:27], v[204:205], v[250:251] neg_lo:[1,0,0] neg_hi:[1,0,0]
	v_pk_fma_f32 v[252:253], v[28:29], v[206:207], v[252:253] neg_lo:[1,0,0] neg_hi:[1,0,0]
	ds_read_b128 v[200:203], v1 offset:45984
	s_waitcnt lgkmcnt(14)
	v_pk_fma_f32 v[250:251], v[30:31], v[246:247], v[250:251] neg_lo:[1,0,0] neg_hi:[1,0,0]
	v_pk_fma_f32 v[252:253], v[32:33], v[248:249], v[252:253] neg_lo:[1,0,0] neg_hi:[1,0,0]
	ds_read_b128 v[204:207], v1 offset:46000
	s_waitcnt lgkmcnt(14)
	v_pk_fma_f32 v[250:251], v[34:35], v[66:67], v[250:251] neg_lo:[1,0,0] neg_hi:[1,0,0]
	v_pk_fma_f32 v[252:253], v[36:37], v[68:69], v[252:253] neg_lo:[1,0,0] neg_hi:[1,0,0]
	ds_read_b128 v[246:249], v1 offset:46016
	s_waitcnt lgkmcnt(14)
	v_pk_fma_f32 v[250:251], v[38:39], v[70:71], v[250:251] neg_lo:[1,0,0] neg_hi:[1,0,0]
	v_pk_fma_f32 v[252:253], v[40:41], v[72:73], v[252:253] neg_lo:[1,0,0] neg_hi:[1,0,0]
	ds_read_b128 v[66:69], v1 offset:46032
	s_waitcnt lgkmcnt(14)
; #define SUB_LROW(buf, i_, j0_, n_) do { _Pragma("unroll") for (int j4 = 0; j4 < (n_); ++j4) buf[j4] = *(const f32x4*)(Ls + (i_) * 68 + 4 * ((j0_) + j4)); } while (0)
; #define SUB_FROW(buf, j0_, n_) do { _Pragma("unroll") for (int j4 = 0; j4 < (n_); ++j4) { const f32x4 l = buf[j4]; \
;                 acc -= l.x * x[4 * ((j0_) + j4)]; acc -= l.y * x[4 * ((j0_) + j4) + 1]; acc -= l.z * x[4 * ((j0_) + j4) + 2]; acc -= l.w * x[4 * ((j0_) + j4) + 3]; } } while (0)
; __device__ __forceinline__ void gdn_prep(KA a, int layer, unsigned char* lds, const int tid_, const int bid_) {
;     ...
;             for (int i = 33; i < 64; ++i) {
;                 float acc = x[i];
;                 SUB_LROW(bufB, i, 8, (i + 3) / 4 - 8); __builtin_amdgcn_sched_barrier(0);
;                 SUB_FROW(bufA, 0, 8); __builtin_amdgcn_sched_barrier(0);
;                 if (i + 1 < 64) SUB_LROW(bufA, i + 1, 0, 8);
;                 __builtin_amdgcn_sched_barrier(0);
;                 SUB_FROW(bufB, 8, (i + 3) / 4 - 8);
;                 x[i] = acc;
;                 __builtin_amdgcn_sched_barrier(0);
;             }
	v_pk_mul_f32 v[242:243], v[2:3], v[74:75] neg_lo:[1,0] neg_hi:[1,0]
	v_pk_mul_f32 v[244:245], v[4:5], v[76:77] neg_lo:[1,0] neg_hi:[1,0]
	v_pk_add_f32 v[250:251], v[250:251], v[252:253]
	ds_read_b128 v[70:73], v1 offset:46048
	s_waitcnt lgkmcnt(14)
	v_pk_fma_f32 v[242:243], v[6:7], v[78:79], v[242:243] neg_lo:[1,0,0] neg_hi:[1,0,0]
	v_add_f32_e32 v250, v250, v251
	v_pk_fma_f32 v[244:245], v[8:9], v[80:81], v[244:245] neg_lo:[1,0,0] neg_hi:[1,0,0]
	v_add_f32_e32 v41, v41, v250
	ds_read_b128 v[74:77], v1 offset:46064
	s_waitcnt lgkmcnt(14)
	v_pk_fma_f32 v[242:243], v[10:11], v[82:83], v[242:243] neg_lo:[1,0,0] neg_hi:[1,0,0]
	v_pk_fma_f32 v[244:245], v[12:13], v[84:85], v[244:245] neg_lo:[1,0,0] neg_hi:[1,0,0]
	ds_read_b128 v[78:81], v1 offset:46080
	s_waitcnt lgkmcnt(14)
	v_pk_fma_f32 v[242:243], v[14:15], v[86:87], v[242:243] neg_lo:[1,0,0] neg_hi:[1,0,0]
	v_pk_fma_f32 v[244:245], v[16:17], v[88:89], v[244:245] neg_lo:[1,0,0] neg_hi:[1,0,0]
	ds_read_b128 v[82:85], v1 offset:46096
	s_waitcnt lgkmcnt(14)
	v_pk_fma_f32 v[242:243], v[18:19], v[116:117], v[242:243] neg_lo:[1,0,0] neg_hi:[1,0,0]
	v_pk_fma_f32 v[244:245], v[20:21], v[118:119], v[244:245] neg_lo:[1,0,0] neg_hi:[1,0,0]
	ds_read_b128 v[86:89], v1 offset:46112
	s_waitcnt lgkmcnt(14)
	v_pk_fma_f32 v[242:243], v[22:23], v[120:121], v[242:243] neg_lo:[1,0,0] neg_hi:[1,0,0]
	v_pk_fma_f32 v[244:245], v[24:25], v[122:123], v[244:245] neg_lo:[1,0,0] neg_hi:[1,0,0]
	ds_read_b128 v[116:119], v1 offset:46128
	s_waitcnt lgkmcnt(14)
	v_pk_fma_f32 v[242:243], v[26:27], v[124:125], v[242:243] neg_lo:[1,0,0] neg_hi:[1,0,0]
	v_pk_fma_f32 v[244:245], v[28:29], v[126:127], v[244:245] neg_lo:[1,0,0] neg_hi:[1,0,0]
	ds_read_b128 v[120:123], v1 offset:46240
	s_waitcnt lgkmcnt(14)
	v_pk_fma_f32 v[242:243], v[30:31], v[128:129], v[242:243] neg_lo:[1,0,0] neg_hi:[1,0,0]
	v_pk_fma_f32 v[244:245], v[32:33], v[130:131], v[244:245] neg_lo:[1,0,0] neg_hi:[1,0,0]
	ds_read_b128 v[124:127], v1 offset:46256
	s_waitcnt lgkmcnt(14)
	v_pk_fma_f32 v[242:243], v[34:35], v[132:133], v[242:243] neg_lo:[1,0,0] neg_hi:[1,0,0]
	v_pk_fma_f32 v[244:245], v[36:37], v[134:135], v[244:245] neg_lo:[1,0,0] neg_hi:[1,0,0]
	ds_read_b128 v[128:131], v1 offset:46272
	s_waitcnt lgkmcnt(14)
	v_pk_fma_f32 v[242:243], v[38:39], v[136:137], v[242:243] neg_lo:[1,0,0] neg_hi:[1,0,0]
	v_pk_fma_f32 v[244:245], v[40:41], v[138:139], v[244:245] neg_lo:[1,0,0] neg_hi:[1,0,0]
	ds_read_b128 v[132:135], v1 offset:46288
	s_waitcnt lgkmcnt(14)
	v_pk_mul_f32 v[250:251], v[2:3], v[140:141] neg_lo:[1,0] neg_hi:[1,0]
	v_pk_mul_f32 v[252:253], v[4:5], v[142:143] neg_lo:[1,0] neg_hi:[1,0]
	v_pk_add_f32 v[242:243], v[242:243], v[244:245]
	ds_read_b128 v[136:139], v1 offset:46304
	s_waitcnt lgkmcnt(14)
	v_pk_fma_f32 v[250:251], v[6:7], v[200:201], v[250:251] neg_lo:[1,0,0] neg_hi:[1,0,0]
	v_add_f32_e32 v242, v242, v243
	v_pk_fma_f32 v[252:253], v[8:9], v[202:203], v[252:253] neg_lo:[1,0,0] neg_hi:[1,0,0]
	v_add_f32_e32 v42, v42, v242
	ds_read_b128 v[140:143], v1 offset:46320
	s_waitcnt lgkmcnt(14)
	v_pk_fma_f32 v[250:251], v[10:11], v[204:205], v[250:251] neg_lo:[1,0,0] neg_hi:[1,0,0]
	v_pk_fma_f32 v[252:253], v[12:13], v[206:207], v[252:253] neg_lo:[1,0,0] neg_hi:[1,0,0]
	ds_read_b128 v[200:203], v1 offset:46336
	s_waitcnt lgkmcnt(14)
	v_pk_fma_f32 v[250:251], v[14:15], v[246:247], v[250:251] neg_lo:[1,0,0] neg_hi:[1,0,0]
	v_pk_fma_f32 v[252:253], v[16:17], v[248:249], v[252:253] neg_lo:[1,0,0] neg_hi:[1,0,0]
	ds_read_b128 v[204:207], v1 offset:46352
	s_waitcnt lgkmcnt(14)
	v_pk_fma_f32 v[250:251], v[18:19], v[66:67], v[250:251] neg_lo:[1,0,0] neg_hi:[1,0,0]
	v_pk_fma_f32 v[252:253], v[20:21], v[68:69], v[252:253] neg_lo:[1,0,0] neg_hi:[1,0,0]
	ds_read_b128 v[246:249], v1 offset:46368
	s_waitcnt lgkmcnt(14)
	v_pk_fma_f32 v[250:251], v[22:23], v[70:71], v[250:251] neg_lo:[1,0,0] neg_hi:[1,0,0]
	v_pk_fma_f32 v[252:253], v[24:25], v[72:73], v[252:253] neg_lo:[1,0,0] neg_hi:[1,0,0]
	ds_read_b128 v[66:69], v1 offset:46384
	s_waitcnt lgkmcnt(14)
	v_pk_fma_f32 v[250:251], v[26:27], v[74:75], v[250:251] neg_lo:[1,0,0] neg_hi:[1,0,0]
	v_pk_fma_f32 v[252:253], v[28:29], v[76:77], v[252:253] neg_lo:[1,0,0] neg_hi:[1,0,0]
	ds_read_b128 v[70:73], v1 offset:46400
	s_waitcnt lgkmcnt(14)
	v_pk_fma_f32 v[250:251], v[30:31], v[78:79], v[250:251] neg_lo:[1,0,0] neg_hi:[1,0,0]
	v_pk_fma_f32 v[252:253], v[32:33], v[80:81], v[252:253] neg_lo:[1,0,0] neg_hi:[1,0,0]
	ds_read_b128 v[74:77], v1 offset:46512
	s_waitcnt lgkmcnt(14)
	v_pk_fma_f32 v[250:251], v[34:35], v[82:83], v[250:251] neg_lo:[1,0,0] neg_hi:[1,0,0]
	v_pk_fma_f32 v[252:253], v[36:37], v[84:85], v[252:253] neg_lo:[1,0,0] neg_hi:[1,0,0]
	ds_read_b128 v[78:81], v1 offset:46528
	s_waitcnt lgkmcnt(14)
	v_pk_fma_f32 v[250:251], v[38:39], v[86:87], v[250:251] neg_lo:[1,0,0] neg_hi:[1,0,0]
	v_pk_fma_f32 v[252:253], v[40:41], v[88:89], v[252:253] neg_lo:[1,0,0] neg_hi:[1,0,0]
	ds_read_b128 v[82:85], v1 offset:46544
	s_waitcnt lgkmcnt(14)
	v_pk_fma_f32 v[250:251], v[42:43], v[116:117], v[250:251] neg_lo:[1,0,0] neg_hi:[1,0,0]
	v_pk_fma_f32 v[252:253], v[44:45], v[118:119], v[252:253] neg_lo:[1,0,0] neg_hi:[1,0,0]
	ds_read_b128 v[86:89], v1 offset:46560
	s_waitcnt lgkmcnt(14)
	v_pk_mul_f32 v[242:243], v[2:3], v[120:121] neg_lo:[1,0] neg_hi:[1,0]
	v_pk_mul_f32 v[244:245], v[4:5], v[122:123] neg_lo:[1,0] neg_hi:[1,0]
	v_pk_add_f32 v[250:251], v[250:251], v[252:253]
	ds_read_b128 v[116:119], v1 offset:46576
	s_waitcnt lgkmcnt(14)
	v_pk_fma_f32 v[242:243], v[6:7], v[124:125], v[242:243] neg_lo:[1,0,0] neg_hi:[1,0,0]
	v_add_f32_e32 v250, v250, v251
	v_pk_fma_f32 v[244:245], v[8:9], v[126:127], v[244:245] neg_lo:[1,0,0] neg_hi:[1,0,0]
	v_add_f32_e32 v43, v43, v250
	ds_read_b128 v[120:123], v1 offset:46592
	s_waitcnt lgkmcnt(14)
; #define SUB_LROW(buf, i_, j0_, n_) do { _Pragma("unroll") for (int j4 = 0; j4 < (n_); ++j4) buf[j4] = *(const f32x4*)(Ls + (i_) * 68 + 4 * ((j0_) + j4)); } while (0)
; #define SUB_FROW(buf, j0_, n_) do { _Pragma("unroll") for (int j4 = 0; j4 < (n_); ++j4) { const f32x4 l = buf[j4]; \
;                 acc -= l.x * x[4 * ((j0_) + j4)]; acc -= l.y * x[4 * ((j0_) + j4) + 1]; acc -= l.z * x[4 * ((j0_) + j4) + 2]; acc -= l.w * x[4 * ((j0_) + j4) + 3]; } } while (0)
; __device__ __forceinline__ void gdn_prep(KA a, int layer, unsigned char* lds, const int tid_, const int bid_) {
;     ...
;             for (int i = 33; i < 64; ++i) {
;                 float acc = x[i];
;                 SUB_LROW(bufB, i, 8, (i + 3) / 4 - 8); __builtin_amdgcn_sched_barrier(0);
;                 SUB_FROW(bufA, 0, 8); __builtin_amdgcn_sched_barrier(0);
;                 if (i + 1 < 64) SUB_LROW(bufA, i + 1, 0, 8);
;                 __builtin_amdgcn_sched_barrier(0);
;                 SUB_FROW(bufB, 8, (i + 3) / 4 - 8);
;                 x[i] = acc;
;                 __builtin_amdgcn_sched_barrier(0);
;             }
	v_pk_fma_f32 v[242:243], v[10:11], v[128:129], v[242:243] neg_lo:[1,0,0] neg_hi:[1,0,0]
	v_pk_fma_f32 v[244:245], v[12:13], v[130:131], v[244:245] neg_lo:[1,0,0] neg_hi:[1,0,0]
	ds_read_b128 v[124:127], v1 offset:46608
	s_waitcnt lgkmcnt(14)
	v_pk_fma_f32 v[242:243], v[14:15], v[132:133], v[242:243] neg_lo:[1,0,0] neg_hi:[1,0,0]
	v_pk_fma_f32 v[244:245], v[16:17], v[134:135], v[244:245] neg_lo:[1,0,0] neg_hi:[1,0,0]
	ds_read_b128 v[128:131], v1 offset:46624
	s_waitcnt lgkmcnt(14)
	v_pk_fma_f32 v[242:243], v[18:19], v[136:137], v[242:243] neg_lo:[1,0,0] neg_hi:[1,0,0]
	v_pk_fma_f32 v[244:245], v[20:21], v[138:139], v[244:245] neg_lo:[1,0,0] neg_hi:[1,0,0]
	ds_read_b128 v[132:135], v1 offset:46640
	s_waitcnt lgkmcnt(14)
	v_pk_fma_f32 v[242:243], v[22:23], v[140:141], v[242:243] neg_lo:[1,0,0] neg_hi:[1,0,0]
	v_pk_fma_f32 v[244:245], v[24:25], v[142:143], v[244:245] neg_lo:[1,0,0] neg_hi:[1,0,0]
	ds_read_b128 v[136:139], v1 offset:46656
	s_waitcnt lgkmcnt(14)
	v_pk_fma_f32 v[242:243], v[26:27], v[200:201], v[242:243] neg_lo:[1,0,0] neg_hi:[1,0,0]
	v_pk_fma_f32 v[244:245], v[28:29], v[202:203], v[244:245] neg_lo:[1,0,0] neg_hi:[1,0,0]
	ds_read_b128 v[140:143], v1 offset:46672
	s_waitcnt lgkmcnt(14)
	v_pk_fma_f32 v[242:243], v[30:31], v[204:205], v[242:243] neg_lo:[1,0,0] neg_hi:[1,0,0]
	v_pk_fma_f32 v[244:245], v[32:33], v[206:207], v[244:245] neg_lo:[1,0,0] neg_hi:[1,0,0]
	ds_read_b128 v[200:203], v1 offset:46784
	s_waitcnt lgkmcnt(14)
	v_pk_fma_f32 v[242:243], v[34:35], v[246:247], v[242:243] neg_lo:[1,0,0] neg_hi:[1,0,0]
	v_pk_fma_f32 v[244:245], v[36:37], v[248:249], v[244:245] neg_lo:[1,0,0] neg_hi:[1,0,0]
	ds_read_b128 v[204:207], v1 offset:46800
	s_waitcnt lgkmcnt(14)
	v_pk_fma_f32 v[242:243], v[38:39], v[66:67], v[242:243] neg_lo:[1,0,0] neg_hi:[1,0,0]
	v_pk_fma_f32 v[244:245], v[40:41], v[68:69], v[244:245] neg_lo:[1,0,0] neg_hi:[1,0,0]
	ds_read_b128 v[246:249], v1 offset:46816
	s_waitcnt lgkmcnt(14)
	v_pk_fma_f32 v[242:243], v[42:43], v[70:71], v[242:243] neg_lo:[1,0,0] neg_hi:[1,0,0]
	v_pk_fma_f32 v[244:245], v[44:45], v[72:73], v[244:245] neg_lo:[1,0,0] neg_hi:[1,0,0]
	ds_read_b128 v[66:69], v1 offset:46832
	s_waitcnt lgkmcnt(14)
	v_pk_mul_f32 v[250:251], v[2:3], v[74:75] neg_lo:[1,0] neg_hi:[1,0]
	v_pk_mul_f32 v[252:253], v[4:5], v[76:77] neg_lo:[1,0] neg_hi:[1,0]
	v_pk_add_f32 v[242:243], v[242:243], v[244:245]
	ds_read_b128 v[70:73], v1 offset:46848
	s_waitcnt lgkmcnt(14)
	v_pk_fma_f32 v[250:251], v[6:7], v[78:79], v[250:251] neg_lo:[1,0,0] neg_hi:[1,0,0]
	v_add_f32_e32 v242, v242, v243
	v_pk_fma_f32 v[252:253], v[8:9], v[80:81], v[252:253] neg_lo:[1,0,0] neg_hi:[1,0,0]
	v_add_f32_e32 v44, v44, v242
	ds_read_b128 v[74:77], v1 offset:46864
	s_waitcnt lgkmcnt(14)
	v_pk_fma_f32 v[250:251], v[10:11], v[82:83], v[250:251] neg_lo:[1,0,0] neg_hi:[1,0,0]
	v_pk_fma_f32 v[252:253], v[12:13], v[84:85], v[252:253] neg_lo:[1,0,0] neg_hi:[1,0,0]
	ds_read_b128 v[78:81], v1 offset:46880
	s_waitcnt lgkmcnt(14)
	v_pk_fma_f32 v[250:251], v[14:15], v[86:87], v[250:251] neg_lo:[1,0,0] neg_hi:[1,0,0]
	v_pk_fma_f32 v[252:253], v[16:17], v[88:89], v[252:253] neg_lo:[1,0,0] neg_hi:[1,0,0]
	ds_read_b128 v[82:85], v1 offset:46896
	s_waitcnt lgkmcnt(14)
	v_pk_fma_f32 v[250:251], v[18:19], v[116:117], v[250:251] neg_lo:[1,0,0] neg_hi:[1,0,0]
	v_pk_fma_f32 v[252:253], v[20:21], v[118:119], v[252:253] neg_lo:[1,0,0] neg_hi:[1,0,0]
	ds_read_b128 v[86:89], v1 offset:46912
	s_waitcnt lgkmcnt(14)
	v_pk_fma_f32 v[250:251], v[22:23], v[120:121], v[250:251] neg_lo:[1,0,0] neg_hi:[1,0,0]
	v_pk_fma_f32 v[252:253], v[24:25], v[122:123], v[252:253] neg_lo:[1,0,0] neg_hi:[1,0,0]
	ds_read_b128 v[116:119], v1 offset:46928
	s_waitcnt lgkmcnt(14)
	v_pk_fma_f32 v[250:251], v[26:27], v[124:125], v[250:251] neg_lo:[1,0,0] neg_hi:[1,0,0]
	v_pk_fma_f32 v[252:253], v[28:29], v[126:127], v[252:253] neg_lo:[1,0,0] neg_hi:[1,0,0]
	ds_read_b128 v[120:123], v1 offset:46944
	s_waitcnt lgkmcnt(14)
	v_pk_fma_f32 v[250:251], v[30:31], v[128:129], v[250:251] neg_lo:[1,0,0] neg_hi:[1,0,0]
	v_pk_fma_f32 v[252:253], v[32:33], v[130:131], v[252:253] neg_lo:[1,0,0] neg_hi:[1,0,0]
	ds_read_b128 v[124:127], v1 offset:47056
	s_waitcnt lgkmcnt(14)
	v_pk_fma_f32 v[250:251], v[34:35], v[132:133], v[250:251] neg_lo:[1,0,0] neg_hi:[1,0,0]
	v_pk_fma_f32 v[252:253], v[36:37], v[134:135], v[252:253] neg_lo:[1,0,0] neg_hi:[1,0,0]
	ds_read_b128 v[128:131], v1 offset:47072
	s_waitcnt lgkmcnt(14)
	v_pk_fma_f32 v[250:251], v[38:39], v[136:137], v[250:251] neg_lo:[1,0,0] neg_hi:[1,0,0]
	v_pk_fma_f32 v[252:253], v[40:41], v[138:139], v[252:253] neg_lo:[1,0,0] neg_hi:[1,0,0]
	ds_read_b128 v[132:135], v1 offset:47088
	s_waitcnt lgkmcnt(14)
	v_pk_fma_f32 v[250:251], v[42:43], v[140:141], v[250:251] neg_lo:[1,0,0] neg_hi:[1,0,0]
	v_pk_fma_f32 v[252:253], v[44:45], v[142:143], v[252:253] neg_lo:[1,0,0] neg_hi:[1,0,0]
	ds_read_b128 v[136:139], v1 offset:47104
	s_waitcnt lgkmcnt(14)
	v_pk_mul_f32 v[242:243], v[2:3], v[200:201] neg_lo:[1,0] neg_hi:[1,0]
	v_pk_mul_f32 v[244:245], v[4:5], v[202:203] neg_lo:[1,0] neg_hi:[1,0]
	v_pk_add_f32 v[250:251], v[250:251], v[252:253]
	ds_read_b128 v[140:143], v1 offset:47120
	s_waitcnt lgkmcnt(14)
	v_pk_fma_f32 v[242:243], v[6:7], v[204:205], v[242:243] neg_lo:[1,0,0] neg_hi:[1,0,0]
	v_add_f32_e32 v250, v250, v251
	v_pk_fma_f32 v[244:245], v[8:9], v[206:207], v[244:245] neg_lo:[1,0,0] neg_hi:[1,0,0]
	v_add_f32_e32 v45, v45, v250
	ds_read_b128 v[200:203], v1 offset:47136
	s_waitcnt lgkmcnt(14)
	v_pk_fma_f32 v[242:243], v[10:11], v[246:247], v[242:243] neg_lo:[1,0,0] neg_hi:[1,0,0]
	v_pk_fma_f32 v[244:245], v[12:13], v[248:249], v[244:245] neg_lo:[1,0,0] neg_hi:[1,0,0]
	ds_read_b128 v[204:207], v1 offset:47152
	s_waitcnt lgkmcnt(14)
; #define SUB_LROW(buf, i_, j0_, n_) do { _Pragma("unroll") for (int j4 = 0; j4 < (n_); ++j4) buf[j4] = *(const f32x4*)(Ls + (i_) * 68 + 4 * ((j0_) + j4)); } while (0)
; #define SUB_FROW(buf, j0_, n_) do { _Pragma("unroll") for (int j4 = 0; j4 < (n_); ++j4) { const f32x4 l = buf[j4]; \
;                 acc -= l.x * x[4 * ((j0_) + j4)]; acc -= l.y * x[4 * ((j0_) + j4) + 1]; acc -= l.z * x[4 * ((j0_) + j4) + 2]; acc -= l.w * x[4 * ((j0_) + j4) + 3]; } } while (0)
; __device__ __forceinline__ void gdn_prep(KA a, int layer, unsigned char* lds, const int tid_, const int bid_) {
;     ...
;             for (int i = 33; i < 64; ++i) {
;                 float acc = x[i];
;                 SUB_LROW(bufB, i, 8, (i + 3) / 4 - 8); __builtin_amdgcn_sched_barrier(0);
;                 SUB_FROW(bufA, 0, 8); __builtin_amdgcn_sched_barrier(0);
;                 if (i + 1 < 64) SUB_LROW(bufA, i + 1, 0, 8);
;                 __builtin_amdgcn_sched_barrier(0);
;                 SUB_FROW(bufB, 8, (i + 3) / 4 - 8);
;                 x[i] = acc;
;                 __builtin_amdgcn_sched_barrier(0);
;             }
	v_pk_fma_f32 v[242:243], v[14:15], v[66:67], v[242:243] neg_lo:[1,0,0] neg_hi:[1,0,0]
	v_pk_fma_f32 v[244:245], v[16:17], v[68:69], v[244:245] neg_lo:[1,0,0] neg_hi:[1,0,0]
	ds_read_b128 v[246:249], v1 offset:47168
	s_waitcnt lgkmcnt(14)
	v_pk_fma_f32 v[242:243], v[18:19], v[70:71], v[242:243] neg_lo:[1,0,0] neg_hi:[1,0,0]
	v_pk_fma_f32 v[244:245], v[20:21], v[72:73], v[244:245] neg_lo:[1,0,0] neg_hi:[1,0,0]
	ds_read_b128 v[66:69], v1 offset:47184
	s_waitcnt lgkmcnt(14)
	v_pk_fma_f32 v[242:243], v[22:23], v[74:75], v[242:243] neg_lo:[1,0,0] neg_hi:[1,0,0]
	v_pk_fma_f32 v[244:245], v[24:25], v[76:77], v[244:245] neg_lo:[1,0,0] neg_hi:[1,0,0]
	ds_read_b128 v[70:73], v1 offset:47200
	s_waitcnt lgkmcnt(14)
	v_pk_fma_f32 v[242:243], v[26:27], v[78:79], v[242:243] neg_lo:[1,0,0] neg_hi:[1,0,0]
	v_pk_fma_f32 v[244:245], v[28:29], v[80:81], v[244:245] neg_lo:[1,0,0] neg_hi:[1,0,0]
	ds_read_b128 v[74:77], v1 offset:47216
	s_waitcnt lgkmcnt(14)
	v_pk_fma_f32 v[242:243], v[30:31], v[82:83], v[242:243] neg_lo:[1,0,0] neg_hi:[1,0,0]
	v_pk_fma_f32 v[244:245], v[32:33], v[84:85], v[244:245] neg_lo:[1,0,0] neg_hi:[1,0,0]
	ds_read_b128 v[78:81], v1 offset:47232
	s_waitcnt lgkmcnt(14)
	v_pk_fma_f32 v[242:243], v[34:35], v[86:87], v[242:243] neg_lo:[1,0,0] neg_hi:[1,0,0]
	v_pk_fma_f32 v[244:245], v[36:37], v[88:89], v[244:245] neg_lo:[1,0,0] neg_hi:[1,0,0]
	ds_read_b128 v[82:85], v1 offset:47328
	s_waitcnt lgkmcnt(14)
	v_pk_fma_f32 v[242:243], v[38:39], v[116:117], v[242:243] neg_lo:[1,0,0] neg_hi:[1,0,0]
	v_pk_fma_f32 v[244:245], v[40:41], v[118:119], v[244:245] neg_lo:[1,0,0] neg_hi:[1,0,0]
	ds_read_b128 v[86:89], v1 offset:47344
	s_waitcnt lgkmcnt(14)
	v_pk_fma_f32 v[242:243], v[42:43], v[120:121], v[242:243] neg_lo:[1,0,0] neg_hi:[1,0,0]
	v_pk_fma_f32 v[244:245], v[44:45], v[122:123], v[244:245] neg_lo:[1,0,0] neg_hi:[1,0,0]
	ds_read_b128 v[116:119], v1 offset:47360
	s_waitcnt lgkmcnt(14)
	v_pk_mul_f32 v[250:251], v[2:3], v[124:125] neg_lo:[1,0] neg_hi:[1,0]
	v_pk_mul_f32 v[252:253], v[4:5], v[126:127] neg_lo:[1,0] neg_hi:[1,0]
	v_pk_add_f32 v[242:243], v[242:243], v[244:245]
	ds_read_b128 v[120:123], v1 offset:47376
	s_waitcnt lgkmcnt(14)
	v_pk_fma_f32 v[250:251], v[6:7], v[128:129], v[250:251] neg_lo:[1,0,0] neg_hi:[1,0,0]
	v_add_f32_e32 v242, v242, v243
	v_pk_fma_f32 v[252:253], v[8:9], v[130:131], v[252:253] neg_lo:[1,0,0] neg_hi:[1,0,0]
	v_add_f32_e32 v46, v46, v242
	ds_read_b128 v[124:127], v1 offset:47392
	s_waitcnt lgkmcnt(14)
	v_pk_fma_f32 v[250:251], v[10:11], v[132:133], v[250:251] neg_lo:[1,0,0] neg_hi:[1,0,0]
	v_pk_fma_f32 v[252:253], v[12:13], v[134:135], v[252:253] neg_lo:[1,0,0] neg_hi:[1,0,0]
	ds_read_b128 v[128:131], v1 offset:47408
	s_waitcnt lgkmcnt(14)
	v_pk_fma_f32 v[250:251], v[14:15], v[136:137], v[250:251] neg_lo:[1,0,0] neg_hi:[1,0,0]
	v_pk_fma_f32 v[252:253], v[16:17], v[138:139], v[252:253] neg_lo:[1,0,0] neg_hi:[1,0,0]
	ds_read_b128 v[132:135], v1 offset:47424
	s_waitcnt lgkmcnt(14)
	v_pk_fma_f32 v[250:251], v[18:19], v[140:141], v[250:251] neg_lo:[1,0,0] neg_hi:[1,0,0]
	v_pk_fma_f32 v[252:253], v[20:21], v[142:143], v[252:253] neg_lo:[1,0,0] neg_hi:[1,0,0]
	ds_read_b128 v[136:139], v1 offset:47440
	s_waitcnt lgkmcnt(14)
	v_pk_fma_f32 v[250:251], v[22:23], v[200:201], v[250:251] neg_lo:[1,0,0] neg_hi:[1,0,0]
	v_pk_fma_f32 v[252:253], v[24:25], v[202:203], v[252:253] neg_lo:[1,0,0] neg_hi:[1,0,0]
	ds_read_b128 v[140:143], v1 offset:47456
	s_waitcnt lgkmcnt(14)
	v_pk_fma_f32 v[250:251], v[26:27], v[204:205], v[250:251] neg_lo:[1,0,0] neg_hi:[1,0,0]
	v_pk_fma_f32 v[252:253], v[28:29], v[206:207], v[252:253] neg_lo:[1,0,0] neg_hi:[1,0,0]
	ds_read_b128 v[200:203], v1 offset:47472
	s_waitcnt lgkmcnt(14)
	v_pk_fma_f32 v[250:251], v[30:31], v[246:247], v[250:251] neg_lo:[1,0,0] neg_hi:[1,0,0]
	v_pk_fma_f32 v[252:253], v[32:33], v[248:249], v[252:253] neg_lo:[1,0,0] neg_hi:[1,0,0]
	ds_read_b128 v[204:207], v1 offset:47488
	s_waitcnt lgkmcnt(14)
	v_pk_fma_f32 v[250:251], v[34:35], v[66:67], v[250:251] neg_lo:[1,0,0] neg_hi:[1,0,0]
	v_pk_fma_f32 v[252:253], v[36:37], v[68:69], v[252:253] neg_lo:[1,0,0] neg_hi:[1,0,0]
	ds_read_b128 v[246:249], v1 offset:47504
	s_waitcnt lgkmcnt(14)
	v_pk_fma_f32 v[250:251], v[38:39], v[70:71], v[250:251] neg_lo:[1,0,0] neg_hi:[1,0,0]
	v_pk_fma_f32 v[252:253], v[40:41], v[72:73], v[252:253] neg_lo:[1,0,0] neg_hi:[1,0,0]
	ds_read_b128 v[66:69], v1 offset:47600
	s_waitcnt lgkmcnt(14)
	v_pk_fma_f32 v[250:251], v[42:43], v[74:75], v[250:251] neg_lo:[1,0,0] neg_hi:[1,0,0]
	v_pk_fma_f32 v[252:253], v[44:45], v[76:77], v[252:253] neg_lo:[1,0,0] neg_hi:[1,0,0]
	ds_read_b128 v[70:73], v1 offset:47616
	s_waitcnt lgkmcnt(14)
	v_pk_fma_f32 v[250:251], v[46:47], v[78:79], v[250:251] neg_lo:[1,0,0] neg_hi:[1,0,0]
	v_pk_fma_f32 v[252:253], v[48:49], v[80:81], v[252:253] neg_lo:[1,0,0] neg_hi:[1,0,0]
	ds_read_b128 v[74:77], v1 offset:47632
	s_waitcnt lgkmcnt(14)
	v_pk_mul_f32 v[242:243], v[2:3], v[82:83] neg_lo:[1,0] neg_hi:[1,0]
	v_pk_mul_f32 v[244:245], v[4:5], v[84:85] neg_lo:[1,0] neg_hi:[1,0]
	v_pk_add_f32 v[250:251], v[250:251], v[252:253]
	ds_read_b128 v[78:81], v1 offset:47648
	s_waitcnt lgkmcnt(14)
	v_pk_fma_f32 v[242:243], v[6:7], v[86:87], v[242:243] neg_lo:[1,0,0] neg_hi:[1,0,0]
	v_add_f32_e32 v250, v250, v251
	v_pk_fma_f32 v[244:245], v[8:9], v[88:89], v[244:245] neg_lo:[1,0,0] neg_hi:[1,0,0]
	v_add_f32_e32 v47, v47, v250
	ds_read_b128 v[82:85], v1 offset:47664
	s_waitcnt lgkmcnt(14)
	v_pk_fma_f32 v[242:243], v[10:11], v[116:117], v[242:243] neg_lo:[1,0,0] neg_hi:[1,0,0]
	v_pk_fma_f32 v[244:245], v[12:13], v[118:119], v[244:245] neg_lo:[1,0,0] neg_hi:[1,0,0]
	ds_read_b128 v[86:89], v1 offset:47680
	s_waitcnt lgkmcnt(14)
; #define SUB_LROW(buf, i_, j0_, n_) do { _Pragma("unroll") for (int j4 = 0; j4 < (n_); ++j4) buf[j4] = *(const f32x4*)(Ls + (i_) * 68 + 4 * ((j0_) + j4)); } while (0)
; #define SUB_FROW(buf, j0_, n_) do { _Pragma("unroll") for (int j4 = 0; j4 < (n_); ++j4) { const f32x4 l = buf[j4]; \
;                 acc -= l.x * x[4 * ((j0_) + j4)]; acc -= l.y * x[4 * ((j0_) + j4) + 1]; acc -= l.z * x[4 * ((j0_) + j4) + 2]; acc -= l.w * x[4 * ((j0_) + j4) + 3]; } } while (0)
; __device__ __forceinline__ void gdn_prep(KA a, int layer, unsigned char* lds, const int tid_, const int bid_) {
;     ...
;             for (int i = 33; i < 64; ++i) {
;                 float acc = x[i];
;                 SUB_LROW(bufB, i, 8, (i + 3) / 4 - 8); __builtin_amdgcn_sched_barrier(0);
;                 SUB_FROW(bufA, 0, 8); __builtin_amdgcn_sched_barrier(0);
;                 if (i + 1 < 64) SUB_LROW(bufA, i + 1, 0, 8);
;                 __builtin_amdgcn_sched_barrier(0);
;                 SUB_FROW(bufB, 8, (i + 3) / 4 - 8);
;                 x[i] = acc;
;                 __builtin_amdgcn_sched_barrier(0);
;             }
	v_pk_fma_f32 v[242:243], v[14:15], v[120:121], v[242:243] neg_lo:[1,0,0] neg_hi:[1,0,0]
	v_pk_fma_f32 v[244:245], v[16:17], v[122:123], v[244:245] neg_lo:[1,0,0] neg_hi:[1,0,0]
	ds_read_b128 v[116:119], v1 offset:47696
	s_waitcnt lgkmcnt(14)
	v_pk_fma_f32 v[242:243], v[18:19], v[124:125], v[242:243] neg_lo:[1,0,0] neg_hi:[1,0,0]
	v_pk_fma_f32 v[244:245], v[20:21], v[126:127], v[244:245] neg_lo:[1,0,0] neg_hi:[1,0,0]
	ds_read_b128 v[120:123], v1 offset:47712
	s_waitcnt lgkmcnt(14)
	v_pk_fma_f32 v[242:243], v[22:23], v[128:129], v[242:243] neg_lo:[1,0,0] neg_hi:[1,0,0]
	v_pk_fma_f32 v[244:245], v[24:25], v[130:131], v[244:245] neg_lo:[1,0,0] neg_hi:[1,0,0]
	ds_read_b128 v[124:127], v1 offset:47728
	s_waitcnt lgkmcnt(14)
	v_pk_fma_f32 v[242:243], v[26:27], v[132:133], v[242:243] neg_lo:[1,0,0] neg_hi:[1,0,0]
	v_pk_fma_f32 v[244:245], v[28:29], v[134:135], v[244:245] neg_lo:[1,0,0] neg_hi:[1,0,0]
	ds_read_b128 v[128:131], v1 offset:47744
	s_waitcnt lgkmcnt(14)
	v_pk_fma_f32 v[242:243], v[30:31], v[136:137], v[242:243] neg_lo:[1,0,0] neg_hi:[1,0,0]
	v_pk_fma_f32 v[244:245], v[32:33], v[138:139], v[244:245] neg_lo:[1,0,0] neg_hi:[1,0,0]
	ds_read_b128 v[132:135], v1 offset:47760
	s_waitcnt lgkmcnt(14)
	v_pk_fma_f32 v[242:243], v[34:35], v[140:141], v[242:243] neg_lo:[1,0,0] neg_hi:[1,0,0]
	v_pk_fma_f32 v[244:245], v[36:37], v[142:143], v[244:245] neg_lo:[1,0,0] neg_hi:[1,0,0]
	ds_read_b128 v[136:139], v1 offset:47776
	s_waitcnt lgkmcnt(14)
	v_pk_fma_f32 v[242:243], v[38:39], v[200:201], v[242:243] neg_lo:[1,0,0] neg_hi:[1,0,0]
	v_pk_fma_f32 v[244:245], v[40:41], v[202:203], v[244:245] neg_lo:[1,0,0] neg_hi:[1,0,0]
	ds_read_b128 v[140:143], v1 offset:47872
	s_waitcnt lgkmcnt(14)
	v_pk_fma_f32 v[242:243], v[42:43], v[204:205], v[242:243] neg_lo:[1,0,0] neg_hi:[1,0,0]
	v_pk_fma_f32 v[244:245], v[44:45], v[206:207], v[244:245] neg_lo:[1,0,0] neg_hi:[1,0,0]
	ds_read_b128 v[200:203], v1 offset:47888
	s_waitcnt lgkmcnt(14)
	v_pk_fma_f32 v[242:243], v[46:47], v[246:247], v[242:243] neg_lo:[1,0,0] neg_hi:[1,0,0]
	v_pk_fma_f32 v[244:245], v[48:49], v[248:249], v[244:245] neg_lo:[1,0,0] neg_hi:[1,0,0]
	ds_read_b128 v[204:207], v1 offset:47904
	s_waitcnt lgkmcnt(14)
	v_pk_mul_f32 v[250:251], v[2:3], v[66:67] neg_lo:[1,0] neg_hi:[1,0]
	v_pk_mul_f32 v[252:253], v[4:5], v[68:69] neg_lo:[1,0] neg_hi:[1,0]
	v_pk_add_f32 v[242:243], v[242:243], v[244:245]
	ds_read_b128 v[246:249], v1 offset:47920
	s_waitcnt lgkmcnt(14)
	v_pk_fma_f32 v[250:251], v[6:7], v[70:71], v[250:251] neg_lo:[1,0,0] neg_hi:[1,0,0]
	v_add_f32_e32 v242, v242, v243
	v_pk_fma_f32 v[252:253], v[8:9], v[72:73], v[252:253] neg_lo:[1,0,0] neg_hi:[1,0,0]
	v_add_f32_e32 v48, v48, v242
	ds_read_b128 v[66:69], v1 offset:47936
	s_waitcnt lgkmcnt(14)
	v_pk_fma_f32 v[250:251], v[10:11], v[74:75], v[250:251] neg_lo:[1,0,0] neg_hi:[1,0,0]
	v_pk_fma_f32 v[252:253], v[12:13], v[76:77], v[252:253] neg_lo:[1,0,0] neg_hi:[1,0,0]
	ds_read_b128 v[70:73], v1 offset:47952
	s_waitcnt lgkmcnt(14)
	v_pk_fma_f32 v[250:251], v[14:15], v[78:79], v[250:251] neg_lo:[1,0,0] neg_hi:[1,0,0]
	v_pk_fma_f32 v[252:253], v[16:17], v[80:81], v[252:253] neg_lo:[1,0,0] neg_hi:[1,0,0]
	ds_read_b128 v[74:77], v1 offset:47968
	s_waitcnt lgkmcnt(14)
	v_pk_fma_f32 v[250:251], v[18:19], v[82:83], v[250:251] neg_lo:[1,0,0] neg_hi:[1,0,0]
	v_pk_fma_f32 v[252:253], v[20:21], v[84:85], v[252:253] neg_lo:[1,0,0] neg_hi:[1,0,0]
	ds_read_b128 v[78:81], v1 offset:47984
	s_waitcnt lgkmcnt(14)
	v_pk_fma_f32 v[250:251], v[22:23], v[86:87], v[250:251] neg_lo:[1,0,0] neg_hi:[1,0,0]
	v_pk_fma_f32 v[252:253], v[24:25], v[88:89], v[252:253] neg_lo:[1,0,0] neg_hi:[1,0,0]
	ds_read_b128 v[82:85], v1 offset:48000
	s_waitcnt lgkmcnt(14)
	v_pk_fma_f32 v[250:251], v[26:27], v[116:117], v[250:251] neg_lo:[1,0,0] neg_hi:[1,0,0]
	v_pk_fma_f32 v[252:253], v[28:29], v[118:119], v[252:253] neg_lo:[1,0,0] neg_hi:[1,0,0]
	ds_read_b128 v[86:89], v1 offset:48016
	s_waitcnt lgkmcnt(14)
	v_pk_fma_f32 v[250:251], v[30:31], v[120:121], v[250:251] neg_lo:[1,0,0] neg_hi:[1,0,0]
	v_pk_fma_f32 v[252:253], v[32:33], v[122:123], v[252:253] neg_lo:[1,0,0] neg_hi:[1,0,0]
	ds_read_b128 v[116:119], v1 offset:48032
	s_waitcnt lgkmcnt(14)
	v_pk_fma_f32 v[250:251], v[34:35], v[124:125], v[250:251] neg_lo:[1,0,0] neg_hi:[1,0,0]
	v_pk_fma_f32 v[252:253], v[36:37], v[126:127], v[252:253] neg_lo:[1,0,0] neg_hi:[1,0,0]
	ds_read_b128 v[120:123], v1 offset:48048
	s_waitcnt lgkmcnt(14)
	v_pk_fma_f32 v[250:251], v[38:39], v[128:129], v[250:251] neg_lo:[1,0,0] neg_hi:[1,0,0]
	v_pk_fma_f32 v[252:253], v[40:41], v[130:131], v[252:253] neg_lo:[1,0,0] neg_hi:[1,0,0]
	ds_read_b128 v[124:127], v1 offset:48144
	s_waitcnt lgkmcnt(14)
	v_pk_fma_f32 v[250:251], v[42:43], v[132:133], v[250:251] neg_lo:[1,0,0] neg_hi:[1,0,0]
	v_pk_fma_f32 v[252:253], v[44:45], v[134:135], v[252:253] neg_lo:[1,0,0] neg_hi:[1,0,0]
	ds_read_b128 v[128:131], v1 offset:48160
	s_waitcnt lgkmcnt(14)
	v_pk_fma_f32 v[250:251], v[46:47], v[136:137], v[250:251] neg_lo:[1,0,0] neg_hi:[1,0,0]
	v_pk_fma_f32 v[252:253], v[48:49], v[138:139], v[252:253] neg_lo:[1,0,0] neg_hi:[1,0,0]
	ds_read_b128 v[132:135], v1 offset:48176
	s_waitcnt lgkmcnt(14)
	v_pk_mul_f32 v[242:243], v[2:3], v[140:141] neg_lo:[1,0] neg_hi:[1,0]
	v_pk_mul_f32 v[244:245], v[4:5], v[142:143] neg_lo:[1,0] neg_hi:[1,0]
	v_pk_add_f32 v[250:251], v[250:251], v[252:253]
	ds_read_b128 v[136:139], v1 offset:48192
	s_waitcnt lgkmcnt(14)
	v_pk_fma_f32 v[242:243], v[6:7], v[200:201], v[242:243] neg_lo:[1,0,0] neg_hi:[1,0,0]
	v_add_f32_e32 v250, v250, v251
	v_pk_fma_f32 v[244:245], v[8:9], v[202:203], v[244:245] neg_lo:[1,0,0] neg_hi:[1,0,0]
	v_add_f32_e32 v49, v49, v250
	ds_read_b128 v[140:143], v1 offset:48208
	s_waitcnt lgkmcnt(14)
; #define SUB_LROW(buf, i_, j0_, n_) do { _Pragma("unroll") for (int j4 = 0; j4 < (n_); ++j4) buf[j4] = *(const f32x4*)(Ls + (i_) * 68 + 4 * ((j0_) + j4)); } while (0)
; #define SUB_FROW(buf, j0_, n_) do { _Pragma("unroll") for (int j4 = 0; j4 < (n_); ++j4) { const f32x4 l = buf[j4]; \
;                 acc -= l.x * x[4 * ((j0_) + j4)]; acc -= l.y * x[4 * ((j0_) + j4) + 1]; acc -= l.z * x[4 * ((j0_) + j4) + 2]; acc -= l.w * x[4 * ((j0_) + j4) + 3]; } } while (0)
; __device__ __forceinline__ void gdn_prep(KA a, int layer, unsigned char* lds, const int tid_, const int bid_) {
;     ...
;             for (int i = 33; i < 64; ++i) {
;                 float acc = x[i];
;                 SUB_LROW(bufB, i, 8, (i + 3) / 4 - 8); __builtin_amdgcn_sched_barrier(0);
;                 SUB_FROW(bufA, 0, 8); __builtin_amdgcn_sched_barrier(0);
;                 if (i + 1 < 64) SUB_LROW(bufA, i + 1, 0, 8);
;                 __builtin_amdgcn_sched_barrier(0);
;                 SUB_FROW(bufB, 8, (i + 3) / 4 - 8);
;                 x[i] = acc;
;                 __builtin_amdgcn_sched_barrier(0);
;             }
	v_pk_fma_f32 v[242:243], v[10:11], v[204:205], v[242:243] neg_lo:[1,0,0] neg_hi:[1,0,0]
	v_pk_fma_f32 v[244:245], v[12:13], v[206:207], v[244:245] neg_lo:[1,0,0] neg_hi:[1,0,0]
	ds_read_b128 v[200:203], v1 offset:48224
	s_waitcnt lgkmcnt(14)
	v_pk_fma_f32 v[242:243], v[14:15], v[246:247], v[242:243] neg_lo:[1,0,0] neg_hi:[1,0,0]
	v_pk_fma_f32 v[244:245], v[16:17], v[248:249], v[244:245] neg_lo:[1,0,0] neg_hi:[1,0,0]
	ds_read_b128 v[204:207], v1 offset:48240
	s_waitcnt lgkmcnt(14)
	v_pk_fma_f32 v[242:243], v[18:19], v[66:67], v[242:243] neg_lo:[1,0,0] neg_hi:[1,0,0]
	v_pk_fma_f32 v[244:245], v[20:21], v[68:69], v[244:245] neg_lo:[1,0,0] neg_hi:[1,0,0]
	ds_read_b128 v[246:249], v1 offset:48256
	s_waitcnt lgkmcnt(14)
	v_pk_fma_f32 v[242:243], v[22:23], v[70:71], v[242:243] neg_lo:[1,0,0] neg_hi:[1,0,0]
	v_pk_fma_f32 v[244:245], v[24:25], v[72:73], v[244:245] neg_lo:[1,0,0] neg_hi:[1,0,0]
	ds_read_b128 v[66:69], v1 offset:48272
	s_waitcnt lgkmcnt(14)
	v_pk_fma_f32 v[242:243], v[26:27], v[74:75], v[242:243] neg_lo:[1,0,0] neg_hi:[1,0,0]
	v_pk_fma_f32 v[244:245], v[28:29], v[76:77], v[244:245] neg_lo:[1,0,0] neg_hi:[1,0,0]
	ds_read_b128 v[70:73], v1 offset:48288
	s_waitcnt lgkmcnt(14)
	v_pk_fma_f32 v[242:243], v[30:31], v[78:79], v[242:243] neg_lo:[1,0,0] neg_hi:[1,0,0]
	v_pk_fma_f32 v[244:245], v[32:33], v[80:81], v[244:245] neg_lo:[1,0,0] neg_hi:[1,0,0]
	ds_read_b128 v[74:77], v1 offset:48304
	s_waitcnt lgkmcnt(14)
	v_pk_fma_f32 v[242:243], v[34:35], v[82:83], v[242:243] neg_lo:[1,0,0] neg_hi:[1,0,0]
	v_pk_fma_f32 v[244:245], v[36:37], v[84:85], v[244:245] neg_lo:[1,0,0] neg_hi:[1,0,0]
	ds_read_b128 v[78:81], v1 offset:48320
	s_waitcnt lgkmcnt(14)
	v_pk_fma_f32 v[242:243], v[38:39], v[86:87], v[242:243] neg_lo:[1,0,0] neg_hi:[1,0,0]
	v_pk_fma_f32 v[244:245], v[40:41], v[88:89], v[244:245] neg_lo:[1,0,0] neg_hi:[1,0,0]
	ds_read_b128 v[82:85], v1 offset:48336
	s_waitcnt lgkmcnt(14)
	v_pk_fma_f32 v[242:243], v[42:43], v[116:117], v[242:243] neg_lo:[1,0,0] neg_hi:[1,0,0]
	v_pk_fma_f32 v[244:245], v[44:45], v[118:119], v[244:245] neg_lo:[1,0,0] neg_hi:[1,0,0]
	ds_read_b128 v[86:89], v1 offset:48416
	s_waitcnt lgkmcnt(14)
	v_pk_fma_f32 v[242:243], v[46:47], v[120:121], v[242:243] neg_lo:[1,0,0] neg_hi:[1,0,0]
	v_pk_fma_f32 v[244:245], v[48:49], v[122:123], v[244:245] neg_lo:[1,0,0] neg_hi:[1,0,0]
	ds_read_b128 v[116:119], v1 offset:48432
	s_waitcnt lgkmcnt(14)
	v_pk_mul_f32 v[250:251], v[2:3], v[124:125] neg_lo:[1,0] neg_hi:[1,0]
	v_pk_mul_f32 v[252:253], v[4:5], v[126:127] neg_lo:[1,0] neg_hi:[1,0]
	v_pk_add_f32 v[242:243], v[242:243], v[244:245]
	ds_read_b128 v[120:123], v1 offset:48448
	s_waitcnt lgkmcnt(14)
	v_pk_fma_f32 v[250:251], v[6:7], v[128:129], v[250:251] neg_lo:[1,0,0] neg_hi:[1,0,0]
	v_add_f32_e32 v242, v242, v243
	v_pk_fma_f32 v[252:253], v[8:9], v[130:131], v[252:253] neg_lo:[1,0,0] neg_hi:[1,0,0]
	v_add_f32_e32 v50, v50, v242
	ds_read_b128 v[124:127], v1 offset:48464
	s_waitcnt lgkmcnt(14)
	v_pk_fma_f32 v[250:251], v[10:11], v[132:133], v[250:251] neg_lo:[1,0,0] neg_hi:[1,0,0]
	v_pk_fma_f32 v[252:253], v[12:13], v[134:135], v[252:253] neg_lo:[1,0,0] neg_hi:[1,0,0]
	ds_read_b128 v[128:131], v1 offset:48480
	s_waitcnt lgkmcnt(14)
	v_pk_fma_f32 v[250:251], v[14:15], v[136:137], v[250:251] neg_lo:[1,0,0] neg_hi:[1,0,0]
	v_pk_fma_f32 v[252:253], v[16:17], v[138:139], v[252:253] neg_lo:[1,0,0] neg_hi:[1,0,0]
	ds_read_b128 v[132:135], v1 offset:48496
	s_waitcnt lgkmcnt(14)
	v_pk_fma_f32 v[250:251], v[18:19], v[140:141], v[250:251] neg_lo:[1,0,0] neg_hi:[1,0,0]
	v_pk_fma_f32 v[252:253], v[20:21], v[142:143], v[252:253] neg_lo:[1,0,0] neg_hi:[1,0,0]
	ds_read_b128 v[136:139], v1 offset:48512
	s_waitcnt lgkmcnt(14)
	v_pk_fma_f32 v[250:251], v[22:23], v[200:201], v[250:251] neg_lo:[1,0,0] neg_hi:[1,0,0]
	v_pk_fma_f32 v[252:253], v[24:25], v[202:203], v[252:253] neg_lo:[1,0,0] neg_hi:[1,0,0]
	ds_read_b128 v[140:143], v1 offset:48528
	s_waitcnt lgkmcnt(14)
	v_pk_fma_f32 v[250:251], v[26:27], v[204:205], v[250:251] neg_lo:[1,0,0] neg_hi:[1,0,0]
	v_pk_fma_f32 v[252:253], v[28:29], v[206:207], v[252:253] neg_lo:[1,0,0] neg_hi:[1,0,0]
	ds_read_b128 v[200:203], v1 offset:48544
	s_waitcnt lgkmcnt(14)
	v_pk_fma_f32 v[250:251], v[30:31], v[246:247], v[250:251] neg_lo:[1,0,0] neg_hi:[1,0,0]
	v_pk_fma_f32 v[252:253], v[32:33], v[248:249], v[252:253] neg_lo:[1,0,0] neg_hi:[1,0,0]
	ds_read_b128 v[204:207], v1 offset:48560
	s_waitcnt lgkmcnt(14)
	v_pk_fma_f32 v[250:251], v[34:35], v[66:67], v[250:251] neg_lo:[1,0,0] neg_hi:[1,0,0]
	v_pk_fma_f32 v[252:253], v[36:37], v[68:69], v[252:253] neg_lo:[1,0,0] neg_hi:[1,0,0]
	ds_read_b128 v[246:249], v1 offset:48576
	s_waitcnt lgkmcnt(14)
	v_pk_fma_f32 v[250:251], v[38:39], v[70:71], v[250:251] neg_lo:[1,0,0] neg_hi:[1,0,0]
	v_pk_fma_f32 v[252:253], v[40:41], v[72:73], v[252:253] neg_lo:[1,0,0] neg_hi:[1,0,0]
	ds_read_b128 v[66:69], v1 offset:48592
	s_waitcnt lgkmcnt(14)
	v_pk_fma_f32 v[250:251], v[42:43], v[74:75], v[250:251] neg_lo:[1,0,0] neg_hi:[1,0,0]
	v_pk_fma_f32 v[252:253], v[44:45], v[76:77], v[252:253] neg_lo:[1,0,0] neg_hi:[1,0,0]
	ds_read_b128 v[70:73], v1 offset:48608
	s_waitcnt lgkmcnt(14)
	v_pk_fma_f32 v[250:251], v[46:47], v[78:79], v[250:251] neg_lo:[1,0,0] neg_hi:[1,0,0]
	v_pk_fma_f32 v[252:253], v[48:49], v[80:81], v[252:253] neg_lo:[1,0,0] neg_hi:[1,0,0]
	ds_read_b128 v[74:77], v1 offset:48688
	s_waitcnt lgkmcnt(14)
	v_pk_fma_f32 v[250:251], v[50:51], v[82:83], v[250:251] neg_lo:[1,0,0] neg_hi:[1,0,0]
	v_pk_fma_f32 v[252:253], v[52:53], v[84:85], v[252:253] neg_lo:[1,0,0] neg_hi:[1,0,0]
	ds_read_b128 v[78:81], v1 offset:48704
	s_waitcnt lgkmcnt(14)
; #define SUB_LROW(buf, i_, j0_, n_) do { _Pragma("unroll") for (int j4 = 0; j4 < (n_); ++j4) buf[j4] = *(const f32x4*)(Ls + (i_) * 68 + 4 * ((j0_) + j4)); } while (0)
; #define SUB_FROW(buf, j0_, n_) do { _Pragma("unroll") for (int j4 = 0; j4 < (n_); ++j4) { const f32x4 l = buf[j4]; \
;                 acc -= l.x * x[4 * ((j0_) + j4)]; acc -= l.y * x[4 * ((j0_) + j4) + 1]; acc -= l.z * x[4 * ((j0_) + j4) + 2]; acc -= l.w * x[4 * ((j0_) + j4) + 3]; } } while (0)
; __device__ __forceinline__ void gdn_prep(KA a, int layer, unsigned char* lds, const int tid_, const int bid_) {
;     ...
;             for (int i = 33; i < 64; ++i) {
;                 float acc = x[i];
;                 SUB_LROW(bufB, i, 8, (i + 3) / 4 - 8); __builtin_amdgcn_sched_barrier(0);
;                 SUB_FROW(bufA, 0, 8); __builtin_amdgcn_sched_barrier(0);
;                 if (i + 1 < 64) SUB_LROW(bufA, i + 1, 0, 8);
;                 __builtin_amdgcn_sched_barrier(0);
;                 SUB_FROW(bufB, 8, (i + 3) / 4 - 8);
;                 x[i] = acc;
;                 __builtin_amdgcn_sched_barrier(0);
;             }
	v_pk_mul_f32 v[242:243], v[2:3], v[86:87] neg_lo:[1,0] neg_hi:[1,0]
	v_pk_mul_f32 v[244:245], v[4:5], v[88:89] neg_lo:[1,0] neg_hi:[1,0]
	v_pk_add_f32 v[250:251], v[250:251], v[252:253]
	ds_read_b128 v[82:85], v1 offset:48720
	s_waitcnt lgkmcnt(14)
	v_pk_fma_f32 v[242:243], v[6:7], v[116:117], v[242:243] neg_lo:[1,0,0] neg_hi:[1,0,0]
	v_add_f32_e32 v250, v250, v251
	v_pk_fma_f32 v[244:245], v[8:9], v[118:119], v[244:245] neg_lo:[1,0,0] neg_hi:[1,0,0]
	v_add_f32_e32 v51, v51, v250
	ds_read_b128 v[86:89], v1 offset:48736
	s_waitcnt lgkmcnt(14)
	v_pk_fma_f32 v[242:243], v[10:11], v[120:121], v[242:243] neg_lo:[1,0,0] neg_hi:[1,0,0]
	v_pk_fma_f32 v[244:245], v[12:13], v[122:123], v[244:245] neg_lo:[1,0,0] neg_hi:[1,0,0]
	ds_read_b128 v[116:119], v1 offset:48752
	s_waitcnt lgkmcnt(14)
	v_pk_fma_f32 v[242:243], v[14:15], v[124:125], v[242:243] neg_lo:[1,0,0] neg_hi:[1,0,0]
	v_pk_fma_f32 v[244:245], v[16:17], v[126:127], v[244:245] neg_lo:[1,0,0] neg_hi:[1,0,0]
	ds_read_b128 v[120:123], v1 offset:48768
	s_waitcnt lgkmcnt(14)
	v_pk_fma_f32 v[242:243], v[18:19], v[128:129], v[242:243] neg_lo:[1,0,0] neg_hi:[1,0,0]
	v_pk_fma_f32 v[244:245], v[20:21], v[130:131], v[244:245] neg_lo:[1,0,0] neg_hi:[1,0,0]
	ds_read_b128 v[124:127], v1 offset:48784
	s_waitcnt lgkmcnt(14)
	v_pk_fma_f32 v[242:243], v[22:23], v[132:133], v[242:243] neg_lo:[1,0,0] neg_hi:[1,0,0]
	v_pk_fma_f32 v[244:245], v[24:25], v[134:135], v[244:245] neg_lo:[1,0,0] neg_hi:[1,0,0]
	ds_read_b128 v[128:131], v1 offset:48800
	s_waitcnt lgkmcnt(14)
	v_pk_fma_f32 v[242:243], v[26:27], v[136:137], v[242:243] neg_lo:[1,0,0] neg_hi:[1,0,0]
	v_pk_fma_f32 v[244:245], v[28:29], v[138:139], v[244:245] neg_lo:[1,0,0] neg_hi:[1,0,0]
	ds_read_b128 v[132:135], v1 offset:48816
	s_waitcnt lgkmcnt(14)
	v_pk_fma_f32 v[242:243], v[30:31], v[140:141], v[242:243] neg_lo:[1,0,0] neg_hi:[1,0,0]
	v_pk_fma_f32 v[244:245], v[32:33], v[142:143], v[244:245] neg_lo:[1,0,0] neg_hi:[1,0,0]
	ds_read_b128 v[136:139], v1 offset:48832
	s_waitcnt lgkmcnt(14)
	v_pk_fma_f32 v[242:243], v[34:35], v[200:201], v[242:243] neg_lo:[1,0,0] neg_hi:[1,0,0]
	v_pk_fma_f32 v[244:245], v[36:37], v[202:203], v[244:245] neg_lo:[1,0,0] neg_hi:[1,0,0]
	ds_read_b128 v[140:143], v1 offset:48848
	s_waitcnt lgkmcnt(14)
	v_pk_fma_f32 v[242:243], v[38:39], v[204:205], v[242:243] neg_lo:[1,0,0] neg_hi:[1,0,0]
	v_pk_fma_f32 v[244:245], v[40:41], v[206:207], v[244:245] neg_lo:[1,0,0] neg_hi:[1,0,0]
	ds_read_b128 v[200:203], v1 offset:48864
	s_waitcnt lgkmcnt(14)
	v_pk_fma_f32 v[242:243], v[42:43], v[246:247], v[242:243] neg_lo:[1,0,0] neg_hi:[1,0,0]
	v_pk_fma_f32 v[244:245], v[44:45], v[248:249], v[244:245] neg_lo:[1,0,0] neg_hi:[1,0,0]
	ds_read_b128 v[204:207], v1 offset:48880
	s_waitcnt lgkmcnt(14)
	v_pk_fma_f32 v[242:243], v[46:47], v[66:67], v[242:243] neg_lo:[1,0,0] neg_hi:[1,0,0]
	v_pk_fma_f32 v[244:245], v[48:49], v[68:69], v[244:245] neg_lo:[1,0,0] neg_hi:[1,0,0]
	ds_read_b128 v[246:249], v1 offset:48960
	s_waitcnt lgkmcnt(14)
	v_pk_fma_f32 v[242:243], v[50:51], v[70:71], v[242:243] neg_lo:[1,0,0] neg_hi:[1,0,0]
	v_pk_fma_f32 v[244:245], v[52:53], v[72:73], v[244:245] neg_lo:[1,0,0] neg_hi:[1,0,0]
	ds_read_b128 v[66:69], v1 offset:48976
	s_waitcnt lgkmcnt(14)
	v_pk_mul_f32 v[250:251], v[2:3], v[74:75] neg_lo:[1,0] neg_hi:[1,0]
	v_pk_mul_f32 v[252:253], v[4:5], v[76:77] neg_lo:[1,0] neg_hi:[1,0]
	v_pk_add_f32 v[242:243], v[242:243], v[244:245]
	ds_read_b128 v[70:73], v1 offset:48992
	s_waitcnt lgkmcnt(14)
	v_pk_fma_f32 v[250:251], v[6:7], v[78:79], v[250:251] neg_lo:[1,0,0] neg_hi:[1,0,0]
	v_add_f32_e32 v242, v242, v243
	v_pk_fma_f32 v[252:253], v[8:9], v[80:81], v[252:253] neg_lo:[1,0,0] neg_hi:[1,0,0]
	v_add_f32_e32 v52, v52, v242
	ds_read_b128 v[74:77], v1 offset:49008
	s_waitcnt lgkmcnt(14)
	v_pk_fma_f32 v[250:251], v[10:11], v[82:83], v[250:251] neg_lo:[1,0,0] neg_hi:[1,0,0]
	v_pk_fma_f32 v[252:253], v[12:13], v[84:85], v[252:253] neg_lo:[1,0,0] neg_hi:[1,0,0]
	ds_read_b128 v[78:81], v1 offset:49024
	s_waitcnt lgkmcnt(14)
	v_pk_fma_f32 v[250:251], v[14:15], v[86:87], v[250:251] neg_lo:[1,0,0] neg_hi:[1,0,0]
	v_pk_fma_f32 v[252:253], v[16:17], v[88:89], v[252:253] neg_lo:[1,0,0] neg_hi:[1,0,0]
	ds_read_b128 v[82:85], v1 offset:49040
	s_waitcnt lgkmcnt(14)
	v_pk_fma_f32 v[250:251], v[18:19], v[116:117], v[250:251] neg_lo:[1,0,0] neg_hi:[1,0,0]
	v_pk_fma_f32 v[252:253], v[20:21], v[118:119], v[252:253] neg_lo:[1,0,0] neg_hi:[1,0,0]
	ds_read_b128 v[86:89], v1 offset:49056
	s_waitcnt lgkmcnt(14)
	v_pk_fma_f32 v[250:251], v[22:23], v[120:121], v[250:251] neg_lo:[1,0,0] neg_hi:[1,0,0]
	v_pk_fma_f32 v[252:253], v[24:25], v[122:123], v[252:253] neg_lo:[1,0,0] neg_hi:[1,0,0]
	ds_read_b128 v[116:119], v1 offset:49072
	s_waitcnt lgkmcnt(14)
	v_pk_fma_f32 v[250:251], v[26:27], v[124:125], v[250:251] neg_lo:[1,0,0] neg_hi:[1,0,0]
	v_pk_fma_f32 v[252:253], v[28:29], v[126:127], v[252:253] neg_lo:[1,0,0] neg_hi:[1,0,0]
	ds_read_b128 v[120:123], v1 offset:49088
	s_waitcnt lgkmcnt(14)
	v_pk_fma_f32 v[250:251], v[30:31], v[128:129], v[250:251] neg_lo:[1,0,0] neg_hi:[1,0,0]
	v_pk_fma_f32 v[252:253], v[32:33], v[130:131], v[252:253] neg_lo:[1,0,0] neg_hi:[1,0,0]
	ds_read_b128 v[124:127], v1 offset:49104
	s_waitcnt lgkmcnt(14)
	v_pk_fma_f32 v[250:251], v[34:35], v[132:133], v[250:251] neg_lo:[1,0,0] neg_hi:[1,0,0]
	v_pk_fma_f32 v[252:253], v[36:37], v[134:135], v[252:253] neg_lo:[1,0,0] neg_hi:[1,0,0]
	ds_read_b128 v[128:131], v1 offset:49120
	s_waitcnt lgkmcnt(14)
	v_pk_fma_f32 v[250:251], v[38:39], v[136:137], v[250:251] neg_lo:[1,0,0] neg_hi:[1,0,0]
	v_pk_fma_f32 v[252:253], v[40:41], v[138:139], v[252:253] neg_lo:[1,0,0] neg_hi:[1,0,0]
	ds_read_b128 v[132:135], v1 offset:49136
	s_waitcnt lgkmcnt(14)
; #define SUB_LROW(buf, i_, j0_, n_) do { _Pragma("unroll") for (int j4 = 0; j4 < (n_); ++j4) buf[j4] = *(const f32x4*)(Ls + (i_) * 68 + 4 * ((j0_) + j4)); } while (0)
; #define SUB_FROW(buf, j0_, n_) do { _Pragma("unroll") for (int j4 = 0; j4 < (n_); ++j4) { const f32x4 l = buf[j4]; \
;                 acc -= l.x * x[4 * ((j0_) + j4)]; acc -= l.y * x[4 * ((j0_) + j4) + 1]; acc -= l.z * x[4 * ((j0_) + j4) + 2]; acc -= l.w * x[4 * ((j0_) + j4) + 3]; } } while (0)
; __device__ __forceinline__ void gdn_prep(KA a, int layer, unsigned char* lds, const int tid_, const int bid_) {
;     ...
;             for (int i = 33; i < 64; ++i) {
;                 float acc = x[i];
;                 SUB_LROW(bufB, i, 8, (i + 3) / 4 - 8); __builtin_amdgcn_sched_barrier(0);
;                 SUB_FROW(bufA, 0, 8); __builtin_amdgcn_sched_barrier(0);
;                 if (i + 1 < 64) SUB_LROW(bufA, i + 1, 0, 8);
;                 __builtin_amdgcn_sched_barrier(0);
;                 SUB_FROW(bufB, 8, (i + 3) / 4 - 8);
;                 x[i] = acc;
;                 __builtin_amdgcn_sched_barrier(0);
;             }
	v_pk_fma_f32 v[250:251], v[42:43], v[140:141], v[250:251] neg_lo:[1,0,0] neg_hi:[1,0,0]
	v_pk_fma_f32 v[252:253], v[44:45], v[142:143], v[252:253] neg_lo:[1,0,0] neg_hi:[1,0,0]
	ds_read_b128 v[136:139], v1 offset:49152
	s_waitcnt lgkmcnt(14)
	v_pk_fma_f32 v[250:251], v[46:47], v[200:201], v[250:251] neg_lo:[1,0,0] neg_hi:[1,0,0]
	v_pk_fma_f32 v[252:253], v[48:49], v[202:203], v[252:253] neg_lo:[1,0,0] neg_hi:[1,0,0]
	ds_read_b128 v[140:143], v1 offset:49232
	s_waitcnt lgkmcnt(14)
	v_pk_fma_f32 v[250:251], v[50:51], v[204:205], v[250:251] neg_lo:[1,0,0] neg_hi:[1,0,0]
	v_pk_fma_f32 v[252:253], v[52:53], v[206:207], v[252:253] neg_lo:[1,0,0] neg_hi:[1,0,0]
	ds_read_b128 v[200:203], v1 offset:49248
	s_waitcnt lgkmcnt(14)
	v_pk_mul_f32 v[242:243], v[2:3], v[246:247] neg_lo:[1,0] neg_hi:[1,0]
	v_pk_mul_f32 v[244:245], v[4:5], v[248:249] neg_lo:[1,0] neg_hi:[1,0]
	v_pk_add_f32 v[250:251], v[250:251], v[252:253]
	ds_read_b128 v[204:207], v1 offset:49264
	s_waitcnt lgkmcnt(14)
	v_pk_fma_f32 v[242:243], v[6:7], v[66:67], v[242:243] neg_lo:[1,0,0] neg_hi:[1,0,0]
	v_add_f32_e32 v250, v250, v251
	v_pk_fma_f32 v[244:245], v[8:9], v[68:69], v[244:245] neg_lo:[1,0,0] neg_hi:[1,0,0]
	v_add_f32_e32 v53, v53, v250
	ds_read_b128 v[246:249], v1 offset:49280
	s_waitcnt lgkmcnt(14)
	v_pk_fma_f32 v[242:243], v[10:11], v[70:71], v[242:243] neg_lo:[1,0,0] neg_hi:[1,0,0]
	v_pk_fma_f32 v[244:245], v[12:13], v[72:73], v[244:245] neg_lo:[1,0,0] neg_hi:[1,0,0]
	ds_read_b128 v[66:69], v1 offset:49296
	s_waitcnt lgkmcnt(14)
	v_pk_fma_f32 v[242:243], v[14:15], v[74:75], v[242:243] neg_lo:[1,0,0] neg_hi:[1,0,0]
	v_pk_fma_f32 v[244:245], v[16:17], v[76:77], v[244:245] neg_lo:[1,0,0] neg_hi:[1,0,0]
	ds_read_b128 v[70:73], v1 offset:49312
	s_waitcnt lgkmcnt(14)
	v_pk_fma_f32 v[242:243], v[18:19], v[78:79], v[242:243] neg_lo:[1,0,0] neg_hi:[1,0,0]
	v_pk_fma_f32 v[244:245], v[20:21], v[80:81], v[244:245] neg_lo:[1,0,0] neg_hi:[1,0,0]
	ds_read_b128 v[74:77], v1 offset:49328
	s_waitcnt lgkmcnt(14)
	v_pk_fma_f32 v[242:243], v[22:23], v[82:83], v[242:243] neg_lo:[1,0,0] neg_hi:[1,0,0]
	v_pk_fma_f32 v[244:245], v[24:25], v[84:85], v[244:245] neg_lo:[1,0,0] neg_hi:[1,0,0]
	ds_read_b128 v[78:81], v1 offset:49344
	s_waitcnt lgkmcnt(14)
	v_pk_fma_f32 v[242:243], v[26:27], v[86:87], v[242:243] neg_lo:[1,0,0] neg_hi:[1,0,0]
	v_pk_fma_f32 v[244:245], v[28:29], v[88:89], v[244:245] neg_lo:[1,0,0] neg_hi:[1,0,0]
	ds_read_b128 v[82:85], v1 offset:49360
	s_waitcnt lgkmcnt(14)
	v_pk_fma_f32 v[242:243], v[30:31], v[116:117], v[242:243] neg_lo:[1,0,0] neg_hi:[1,0,0]
	v_pk_fma_f32 v[244:245], v[32:33], v[118:119], v[244:245] neg_lo:[1,0,0] neg_hi:[1,0,0]
	ds_read_b128 v[86:89], v1 offset:49376
	s_waitcnt lgkmcnt(14)
	v_pk_fma_f32 v[242:243], v[34:35], v[120:121], v[242:243] neg_lo:[1,0,0] neg_hi:[1,0,0]
	v_pk_fma_f32 v[244:245], v[36:37], v[122:123], v[244:245] neg_lo:[1,0,0] neg_hi:[1,0,0]
	ds_read_b128 v[116:119], v1 offset:49392
	s_waitcnt lgkmcnt(14)
	v_pk_fma_f32 v[242:243], v[38:39], v[124:125], v[242:243] neg_lo:[1,0,0] neg_hi:[1,0,0]
	v_pk_fma_f32 v[244:245], v[40:41], v[126:127], v[244:245] neg_lo:[1,0,0] neg_hi:[1,0,0]
	ds_read_b128 v[120:123], v1 offset:49408
	s_waitcnt lgkmcnt(14)
	v_pk_fma_f32 v[242:243], v[42:43], v[128:129], v[242:243] neg_lo:[1,0,0] neg_hi:[1,0,0]
	v_pk_fma_f32 v[244:245], v[44:45], v[130:131], v[244:245] neg_lo:[1,0,0] neg_hi:[1,0,0]
	ds_read_b128 v[124:127], v1 offset:49424
	s_waitcnt lgkmcnt(14)
	v_pk_fma_f32 v[242:243], v[46:47], v[132:133], v[242:243] neg_lo:[1,0,0] neg_hi:[1,0,0]
	v_pk_fma_f32 v[244:245], v[48:49], v[134:135], v[244:245] neg_lo:[1,0,0] neg_hi:[1,0,0]
	ds_read_b128 v[128:131], v1 offset:49440
	s_waitcnt lgkmcnt(14)
	v_pk_fma_f32 v[242:243], v[50:51], v[136:137], v[242:243] neg_lo:[1,0,0] neg_hi:[1,0,0]
	v_pk_fma_f32 v[244:245], v[52:53], v[138:139], v[244:245] neg_lo:[1,0,0] neg_hi:[1,0,0]
	ds_read_b128 v[132:135], v1 offset:49504
	s_waitcnt lgkmcnt(14)
	v_pk_mul_f32 v[250:251], v[2:3], v[140:141] neg_lo:[1,0] neg_hi:[1,0]
	v_pk_mul_f32 v[252:253], v[4:5], v[142:143] neg_lo:[1,0] neg_hi:[1,0]
	v_pk_add_f32 v[242:243], v[242:243], v[244:245]
	ds_read_b128 v[136:139], v1 offset:49520
	s_waitcnt lgkmcnt(14)
	v_pk_fma_f32 v[250:251], v[6:7], v[200:201], v[250:251] neg_lo:[1,0,0] neg_hi:[1,0,0]
	v_add_f32_e32 v242, v242, v243
	v_pk_fma_f32 v[252:253], v[8:9], v[202:203], v[252:253] neg_lo:[1,0,0] neg_hi:[1,0,0]
	v_add_f32_e32 v54, v54, v242
	ds_read_b128 v[140:143], v1 offset:49536
	s_waitcnt lgkmcnt(14)
	v_pk_fma_f32 v[250:251], v[10:11], v[204:205], v[250:251] neg_lo:[1,0,0] neg_hi:[1,0,0]
	v_pk_fma_f32 v[252:253], v[12:13], v[206:207], v[252:253] neg_lo:[1,0,0] neg_hi:[1,0,0]
	ds_read_b128 v[200:203], v1 offset:49552
	s_waitcnt lgkmcnt(14)
	v_pk_fma_f32 v[250:251], v[14:15], v[246:247], v[250:251] neg_lo:[1,0,0] neg_hi:[1,0,0]
	v_pk_fma_f32 v[252:253], v[16:17], v[248:249], v[252:253] neg_lo:[1,0,0] neg_hi:[1,0,0]
	ds_read_b128 v[204:207], v1 offset:49568
	s_waitcnt lgkmcnt(14)
	v_pk_fma_f32 v[250:251], v[18:19], v[66:67], v[250:251] neg_lo:[1,0,0] neg_hi:[1,0,0]
	v_pk_fma_f32 v[252:253], v[20:21], v[68:69], v[252:253] neg_lo:[1,0,0] neg_hi:[1,0,0]
	ds_read_b128 v[246:249], v1 offset:49584
	s_waitcnt lgkmcnt(14)
	v_pk_fma_f32 v[250:251], v[22:23], v[70:71], v[250:251] neg_lo:[1,0,0] neg_hi:[1,0,0]
	v_pk_fma_f32 v[252:253], v[24:25], v[72:73], v[252:253] neg_lo:[1,0,0] neg_hi:[1,0,0]
	ds_read_b128 v[66:69], v1 offset:49600
	s_waitcnt lgkmcnt(14)
	v_pk_fma_f32 v[250:251], v[26:27], v[74:75], v[250:251] neg_lo:[1,0,0] neg_hi:[1,0,0]
	v_pk_fma_f32 v[252:253], v[28:29], v[76:77], v[252:253] neg_lo:[1,0,0] neg_hi:[1,0,0]
	ds_read_b128 v[70:73], v1 offset:49616
	s_waitcnt lgkmcnt(14)
; #define SUB_LROW(buf, i_, j0_, n_) do { _Pragma("unroll") for (int j4 = 0; j4 < (n_); ++j4) buf[j4] = *(const f32x4*)(Ls + (i_) * 68 + 4 * ((j0_) + j4)); } while (0)
; #define SUB_FROW(buf, j0_, n_) do { _Pragma("unroll") for (int j4 = 0; j4 < (n_); ++j4) { const f32x4 l = buf[j4]; \
;                 acc -= l.x * x[4 * ((j0_) + j4)]; acc -= l.y * x[4 * ((j0_) + j4) + 1]; acc -= l.z * x[4 * ((j0_) + j4) + 2]; acc -= l.w * x[4 * ((j0_) + j4) + 3]; } } while (0)
; __device__ __forceinline__ void gdn_prep(KA a, int layer, unsigned char* lds, const int tid_, const int bid_) {
;     ...
;             for (int i = 33; i < 64; ++i) {
;                 float acc = x[i];
;                 SUB_LROW(bufB, i, 8, (i + 3) / 4 - 8); __builtin_amdgcn_sched_barrier(0);
;                 SUB_FROW(bufA, 0, 8); __builtin_amdgcn_sched_barrier(0);
;                 if (i + 1 < 64) SUB_LROW(bufA, i + 1, 0, 8);
;                 __builtin_amdgcn_sched_barrier(0);
;                 SUB_FROW(bufB, 8, (i + 3) / 4 - 8);
;                 x[i] = acc;
;                 __builtin_amdgcn_sched_barrier(0);
;             }
	v_pk_fma_f32 v[250:251], v[30:31], v[78:79], v[250:251] neg_lo:[1,0,0] neg_hi:[1,0,0]
	v_pk_fma_f32 v[252:253], v[32:33], v[80:81], v[252:253] neg_lo:[1,0,0] neg_hi:[1,0,0]
	ds_read_b128 v[74:77], v1 offset:49632
	s_waitcnt lgkmcnt(14)
	v_pk_fma_f32 v[250:251], v[34:35], v[82:83], v[250:251] neg_lo:[1,0,0] neg_hi:[1,0,0]
	v_pk_fma_f32 v[252:253], v[36:37], v[84:85], v[252:253] neg_lo:[1,0,0] neg_hi:[1,0,0]
	ds_read_b128 v[78:81], v1 offset:49648
	s_waitcnt lgkmcnt(14)
	v_pk_fma_f32 v[250:251], v[38:39], v[86:87], v[250:251] neg_lo:[1,0,0] neg_hi:[1,0,0]
	v_pk_fma_f32 v[252:253], v[40:41], v[88:89], v[252:253] neg_lo:[1,0,0] neg_hi:[1,0,0]
	ds_read_b128 v[82:85], v1 offset:49664
	s_waitcnt lgkmcnt(14)
	v_pk_fma_f32 v[250:251], v[42:43], v[116:117], v[250:251] neg_lo:[1,0,0] neg_hi:[1,0,0]
	v_pk_fma_f32 v[252:253], v[44:45], v[118:119], v[252:253] neg_lo:[1,0,0] neg_hi:[1,0,0]
	ds_read_b128 v[86:89], v1 offset:49680
	s_waitcnt lgkmcnt(14)
	v_pk_fma_f32 v[250:251], v[46:47], v[120:121], v[250:251] neg_lo:[1,0,0] neg_hi:[1,0,0]
	v_pk_fma_f32 v[252:253], v[48:49], v[122:123], v[252:253] neg_lo:[1,0,0] neg_hi:[1,0,0]
	ds_read_b128 v[116:119], v1 offset:49696
	s_waitcnt lgkmcnt(14)
	v_pk_fma_f32 v[250:251], v[50:51], v[124:125], v[250:251] neg_lo:[1,0,0] neg_hi:[1,0,0]
	v_pk_fma_f32 v[252:253], v[52:53], v[126:127], v[252:253] neg_lo:[1,0,0] neg_hi:[1,0,0]
	ds_read_b128 v[120:123], v1 offset:49712
	s_waitcnt lgkmcnt(14)
	v_pk_fma_f32 v[250:251], v[54:55], v[128:129], v[250:251] neg_lo:[1,0,0] neg_hi:[1,0,0]
	v_pk_fma_f32 v[252:253], v[56:57], v[130:131], v[252:253] neg_lo:[1,0,0] neg_hi:[1,0,0]
	ds_read_b128 v[124:127], v1 offset:49776
	s_waitcnt lgkmcnt(14)
	v_pk_mul_f32 v[242:243], v[2:3], v[132:133] neg_lo:[1,0] neg_hi:[1,0]
	v_pk_mul_f32 v[244:245], v[4:5], v[134:135] neg_lo:[1,0] neg_hi:[1,0]
	v_pk_add_f32 v[250:251], v[250:251], v[252:253]
	ds_read_b128 v[128:131], v1 offset:49792
	s_waitcnt lgkmcnt(14)
	v_pk_fma_f32 v[242:243], v[6:7], v[136:137], v[242:243] neg_lo:[1,0,0] neg_hi:[1,0,0]
	v_add_f32_e32 v250, v250, v251
	v_pk_fma_f32 v[244:245], v[8:9], v[138:139], v[244:245] neg_lo:[1,0,0] neg_hi:[1,0,0]
	v_add_f32_e32 v55, v55, v250
	ds_read_b128 v[132:135], v1 offset:49808
	s_waitcnt lgkmcnt(14)
	v_pk_fma_f32 v[242:243], v[10:11], v[140:141], v[242:243] neg_lo:[1,0,0] neg_hi:[1,0,0]
	v_pk_fma_f32 v[244:245], v[12:13], v[142:143], v[244:245] neg_lo:[1,0,0] neg_hi:[1,0,0]
	ds_read_b128 v[136:139], v1 offset:49824
	s_waitcnt lgkmcnt(14)
	v_pk_fma_f32 v[242:243], v[14:15], v[200:201], v[242:243] neg_lo:[1,0,0] neg_hi:[1,0,0]
	v_pk_fma_f32 v[244:245], v[16:17], v[202:203], v[244:245] neg_lo:[1,0,0] neg_hi:[1,0,0]
	ds_read_b128 v[140:143], v1 offset:49840
	s_waitcnt lgkmcnt(14)
	v_pk_fma_f32 v[242:243], v[18:19], v[204:205], v[242:243] neg_lo:[1,0,0] neg_hi:[1,0,0]
	v_pk_fma_f32 v[244:245], v[20:21], v[206:207], v[244:245] neg_lo:[1,0,0] neg_hi:[1,0,0]
	ds_read_b128 v[200:203], v1 offset:49856
	s_waitcnt lgkmcnt(14)
	v_pk_fma_f32 v[242:243], v[22:23], v[246:247], v[242:243] neg_lo:[1,0,0] neg_hi:[1,0,0]
	v_pk_fma_f32 v[244:245], v[24:25], v[248:249], v[244:245] neg_lo:[1,0,0] neg_hi:[1,0,0]
	ds_read_b128 v[204:207], v1 offset:49872
	s_waitcnt lgkmcnt(14)
	v_pk_fma_f32 v[242:243], v[26:27], v[66:67], v[242:243] neg_lo:[1,0,0] neg_hi:[1,0,0]
	v_pk_fma_f32 v[244:245], v[28:29], v[68:69], v[244:245] neg_lo:[1,0,0] neg_hi:[1,0,0]
	ds_read_b128 v[246:249], v1 offset:49888
	s_waitcnt lgkmcnt(14)
	v_pk_fma_f32 v[242:243], v[30:31], v[70:71], v[242:243] neg_lo:[1,0,0] neg_hi:[1,0,0]
	v_pk_fma_f32 v[244:245], v[32:33], v[72:73], v[244:245] neg_lo:[1,0,0] neg_hi:[1,0,0]
	ds_read_b128 v[66:69], v1 offset:49904
	s_waitcnt lgkmcnt(14)
	v_pk_fma_f32 v[242:243], v[34:35], v[74:75], v[242:243] neg_lo:[1,0,0] neg_hi:[1,0,0]
	v_pk_fma_f32 v[244:245], v[36:37], v[76:77], v[244:245] neg_lo:[1,0,0] neg_hi:[1,0,0]
	ds_read_b128 v[70:73], v1 offset:49920
	s_waitcnt lgkmcnt(14)
	v_pk_fma_f32 v[242:243], v[38:39], v[78:79], v[242:243] neg_lo:[1,0,0] neg_hi:[1,0,0]
	v_pk_fma_f32 v[244:245], v[40:41], v[80:81], v[244:245] neg_lo:[1,0,0] neg_hi:[1,0,0]
	ds_read_b128 v[74:77], v1 offset:49936
	s_waitcnt lgkmcnt(14)
	v_pk_fma_f32 v[242:243], v[42:43], v[82:83], v[242:243] neg_lo:[1,0,0] neg_hi:[1,0,0]
	v_pk_fma_f32 v[244:245], v[44:45], v[84:85], v[244:245] neg_lo:[1,0,0] neg_hi:[1,0,0]
	ds_read_b128 v[78:81], v1 offset:49952
	s_waitcnt lgkmcnt(14)
	v_pk_fma_f32 v[242:243], v[46:47], v[86:87], v[242:243] neg_lo:[1,0,0] neg_hi:[1,0,0]
	v_pk_fma_f32 v[244:245], v[48:49], v[88:89], v[244:245] neg_lo:[1,0,0] neg_hi:[1,0,0]
	ds_read_b128 v[82:85], v1 offset:49968
	s_waitcnt lgkmcnt(14)
	v_pk_fma_f32 v[242:243], v[50:51], v[116:117], v[242:243] neg_lo:[1,0,0] neg_hi:[1,0,0]
	v_pk_fma_f32 v[244:245], v[52:53], v[118:119], v[244:245] neg_lo:[1,0,0] neg_hi:[1,0,0]
	ds_read_b128 v[86:89], v1 offset:49984
	s_waitcnt lgkmcnt(14)
	v_pk_fma_f32 v[242:243], v[54:55], v[120:121], v[242:243] neg_lo:[1,0,0] neg_hi:[1,0,0]
	v_pk_fma_f32 v[244:245], v[56:57], v[122:123], v[244:245] neg_lo:[1,0,0] neg_hi:[1,0,0]
	ds_read_b128 v[116:119], v1 offset:50048
	s_waitcnt lgkmcnt(14)
	v_pk_mul_f32 v[250:251], v[2:3], v[124:125] neg_lo:[1,0] neg_hi:[1,0]
	v_pk_mul_f32 v[252:253], v[4:5], v[126:127] neg_lo:[1,0] neg_hi:[1,0]
	v_pk_add_f32 v[242:243], v[242:243], v[244:245]
	ds_read_b128 v[120:123], v1 offset:50064
	s_waitcnt lgkmcnt(14)
	v_pk_fma_f32 v[250:251], v[6:7], v[128:129], v[250:251] neg_lo:[1,0,0] neg_hi:[1,0,0]
	v_add_f32_e32 v242, v242, v243
	v_pk_fma_f32 v[252:253], v[8:9], v[130:131], v[252:253] neg_lo:[1,0,0] neg_hi:[1,0,0]
	v_add_f32_e32 v56, v56, v242
	ds_read_b128 v[124:127], v1 offset:50080
	s_waitcnt lgkmcnt(14)
; #define SUB_LROW(buf, i_, j0_, n_) do { _Pragma("unroll") for (int j4 = 0; j4 < (n_); ++j4) buf[j4] = *(const f32x4*)(Ls + (i_) * 68 + 4 * ((j0_) + j4)); } while (0)
; #define SUB_FROW(buf, j0_, n_) do { _Pragma("unroll") for (int j4 = 0; j4 < (n_); ++j4) { const f32x4 l = buf[j4]; \
;                 acc -= l.x * x[4 * ((j0_) + j4)]; acc -= l.y * x[4 * ((j0_) + j4) + 1]; acc -= l.z * x[4 * ((j0_) + j4) + 2]; acc -= l.w * x[4 * ((j0_) + j4) + 3]; } } while (0)
; __device__ __forceinline__ void gdn_prep(KA a, int layer, unsigned char* lds, const int tid_, const int bid_) {
;     ...
;             for (int i = 33; i < 64; ++i) {
;                 float acc = x[i];
;                 SUB_LROW(bufB, i, 8, (i + 3) / 4 - 8); __builtin_amdgcn_sched_barrier(0);
;                 SUB_FROW(bufA, 0, 8); __builtin_amdgcn_sched_barrier(0);
;                 if (i + 1 < 64) SUB_LROW(bufA, i + 1, 0, 8);
;                 __builtin_amdgcn_sched_barrier(0);
;                 SUB_FROW(bufB, 8, (i + 3) / 4 - 8);
;                 x[i] = acc;
;                 __builtin_amdgcn_sched_barrier(0);
;             }
	v_pk_fma_f32 v[250:251], v[10:11], v[132:133], v[250:251] neg_lo:[1,0,0] neg_hi:[1,0,0]
	v_pk_fma_f32 v[252:253], v[12:13], v[134:135], v[252:253] neg_lo:[1,0,0] neg_hi:[1,0,0]
	ds_read_b128 v[128:131], v1 offset:50096
	s_waitcnt lgkmcnt(14)
	v_pk_fma_f32 v[250:251], v[14:15], v[136:137], v[250:251] neg_lo:[1,0,0] neg_hi:[1,0,0]
	v_pk_fma_f32 v[252:253], v[16:17], v[138:139], v[252:253] neg_lo:[1,0,0] neg_hi:[1,0,0]
	ds_read_b128 v[132:135], v1 offset:50112
	s_waitcnt lgkmcnt(14)
	v_pk_fma_f32 v[250:251], v[18:19], v[140:141], v[250:251] neg_lo:[1,0,0] neg_hi:[1,0,0]
	v_pk_fma_f32 v[252:253], v[20:21], v[142:143], v[252:253] neg_lo:[1,0,0] neg_hi:[1,0,0]
	ds_read_b128 v[136:139], v1 offset:50128
	s_waitcnt lgkmcnt(14)
	v_pk_fma_f32 v[250:251], v[22:23], v[200:201], v[250:251] neg_lo:[1,0,0] neg_hi:[1,0,0]
	v_pk_fma_f32 v[252:253], v[24:25], v[202:203], v[252:253] neg_lo:[1,0,0] neg_hi:[1,0,0]
	ds_read_b128 v[140:143], v1 offset:50144
	s_waitcnt lgkmcnt(14)
	v_pk_fma_f32 v[250:251], v[26:27], v[204:205], v[250:251] neg_lo:[1,0,0] neg_hi:[1,0,0]
	v_pk_fma_f32 v[252:253], v[28:29], v[206:207], v[252:253] neg_lo:[1,0,0] neg_hi:[1,0,0]
	ds_read_b128 v[200:203], v1 offset:50160
	s_waitcnt lgkmcnt(14)
	v_pk_fma_f32 v[250:251], v[30:31], v[246:247], v[250:251] neg_lo:[1,0,0] neg_hi:[1,0,0]
	v_pk_fma_f32 v[252:253], v[32:33], v[248:249], v[252:253] neg_lo:[1,0,0] neg_hi:[1,0,0]
	ds_read_b128 v[204:207], v1 offset:50176
	s_waitcnt lgkmcnt(14)
	v_pk_fma_f32 v[250:251], v[34:35], v[66:67], v[250:251] neg_lo:[1,0,0] neg_hi:[1,0,0]
	v_pk_fma_f32 v[252:253], v[36:37], v[68:69], v[252:253] neg_lo:[1,0,0] neg_hi:[1,0,0]
	ds_read_b128 v[246:249], v1 offset:50192
	s_waitcnt lgkmcnt(14)
	v_pk_fma_f32 v[250:251], v[38:39], v[70:71], v[250:251] neg_lo:[1,0,0] neg_hi:[1,0,0]
	v_pk_fma_f32 v[252:253], v[40:41], v[72:73], v[252:253] neg_lo:[1,0,0] neg_hi:[1,0,0]
	ds_read_b128 v[66:69], v1 offset:50208
	s_waitcnt lgkmcnt(14)
	v_pk_fma_f32 v[250:251], v[42:43], v[74:75], v[250:251] neg_lo:[1,0,0] neg_hi:[1,0,0]
	v_pk_fma_f32 v[252:253], v[44:45], v[76:77], v[252:253] neg_lo:[1,0,0] neg_hi:[1,0,0]
	ds_read_b128 v[70:73], v1 offset:50224
	s_waitcnt lgkmcnt(14)
	v_pk_fma_f32 v[250:251], v[46:47], v[78:79], v[250:251] neg_lo:[1,0,0] neg_hi:[1,0,0]
	v_pk_fma_f32 v[252:253], v[48:49], v[80:81], v[252:253] neg_lo:[1,0,0] neg_hi:[1,0,0]
	ds_read_b128 v[74:77], v1 offset:50240
	s_waitcnt lgkmcnt(14)
	v_pk_fma_f32 v[250:251], v[50:51], v[82:83], v[250:251] neg_lo:[1,0,0] neg_hi:[1,0,0]
	v_pk_fma_f32 v[252:253], v[52:53], v[84:85], v[252:253] neg_lo:[1,0,0] neg_hi:[1,0,0]
	ds_read_b128 v[78:81], v1 offset:50256
	s_waitcnt lgkmcnt(14)
	v_pk_fma_f32 v[250:251], v[54:55], v[86:87], v[250:251] neg_lo:[1,0,0] neg_hi:[1,0,0]
	v_pk_fma_f32 v[252:253], v[56:57], v[88:89], v[252:253] neg_lo:[1,0,0] neg_hi:[1,0,0]
	ds_read_b128 v[82:85], v1 offset:50320
	s_waitcnt lgkmcnt(14)
	v_pk_mul_f32 v[242:243], v[2:3], v[116:117] neg_lo:[1,0] neg_hi:[1,0]
	v_pk_mul_f32 v[244:245], v[4:5], v[118:119] neg_lo:[1,0] neg_hi:[1,0]
	v_pk_add_f32 v[250:251], v[250:251], v[252:253]
	ds_read_b128 v[86:89], v1 offset:50336
	s_waitcnt lgkmcnt(14)
	v_pk_fma_f32 v[242:243], v[6:7], v[120:121], v[242:243] neg_lo:[1,0,0] neg_hi:[1,0,0]
	v_add_f32_e32 v250, v250, v251
	v_pk_fma_f32 v[244:245], v[8:9], v[122:123], v[244:245] neg_lo:[1,0,0] neg_hi:[1,0,0]
	v_add_f32_e32 v57, v57, v250
	ds_read_b128 v[116:119], v1 offset:50352
	s_waitcnt lgkmcnt(14)
	v_pk_fma_f32 v[242:243], v[10:11], v[124:125], v[242:243] neg_lo:[1,0,0] neg_hi:[1,0,0]
	v_pk_fma_f32 v[244:245], v[12:13], v[126:127], v[244:245] neg_lo:[1,0,0] neg_hi:[1,0,0]
	ds_read_b128 v[120:123], v1 offset:50368
	s_waitcnt lgkmcnt(14)
	v_pk_fma_f32 v[242:243], v[14:15], v[128:129], v[242:243] neg_lo:[1,0,0] neg_hi:[1,0,0]
	v_pk_fma_f32 v[244:245], v[16:17], v[130:131], v[244:245] neg_lo:[1,0,0] neg_hi:[1,0,0]
	ds_read_b128 v[124:127], v1 offset:50384
	s_waitcnt lgkmcnt(14)
	v_pk_fma_f32 v[242:243], v[18:19], v[132:133], v[242:243] neg_lo:[1,0,0] neg_hi:[1,0,0]
	v_pk_fma_f32 v[244:245], v[20:21], v[134:135], v[244:245] neg_lo:[1,0,0] neg_hi:[1,0,0]
	ds_read_b128 v[128:131], v1 offset:50400
	s_waitcnt lgkmcnt(14)
	v_pk_fma_f32 v[242:243], v[22:23], v[136:137], v[242:243] neg_lo:[1,0,0] neg_hi:[1,0,0]
	v_pk_fma_f32 v[244:245], v[24:25], v[138:139], v[244:245] neg_lo:[1,0,0] neg_hi:[1,0,0]
	ds_read_b128 v[132:135], v1 offset:50416
	s_waitcnt lgkmcnt(14)
	v_pk_fma_f32 v[242:243], v[26:27], v[140:141], v[242:243] neg_lo:[1,0,0] neg_hi:[1,0,0]
	v_pk_fma_f32 v[244:245], v[28:29], v[142:143], v[244:245] neg_lo:[1,0,0] neg_hi:[1,0,0]
	ds_read_b128 v[136:139], v1 offset:50432
	s_waitcnt lgkmcnt(14)
	v_pk_fma_f32 v[242:243], v[30:31], v[200:201], v[242:243] neg_lo:[1,0,0] neg_hi:[1,0,0]
	v_pk_fma_f32 v[244:245], v[32:33], v[202:203], v[244:245] neg_lo:[1,0,0] neg_hi:[1,0,0]
	ds_read_b128 v[140:143], v1 offset:50448
	s_waitcnt lgkmcnt(14)
	v_pk_fma_f32 v[242:243], v[34:35], v[204:205], v[242:243] neg_lo:[1,0,0] neg_hi:[1,0,0]
	v_pk_fma_f32 v[244:245], v[36:37], v[206:207], v[244:245] neg_lo:[1,0,0] neg_hi:[1,0,0]
	ds_read_b128 v[200:203], v1 offset:50464
	s_waitcnt lgkmcnt(14)
	v_pk_fma_f32 v[242:243], v[38:39], v[246:247], v[242:243] neg_lo:[1,0,0] neg_hi:[1,0,0]
	v_pk_fma_f32 v[244:245], v[40:41], v[248:249], v[244:245] neg_lo:[1,0,0] neg_hi:[1,0,0]
	ds_read_b128 v[204:207], v1 offset:50480
	s_waitcnt lgkmcnt(14)
	v_pk_fma_f32 v[242:243], v[42:43], v[66:67], v[242:243] neg_lo:[1,0,0] neg_hi:[1,0,0]
	v_pk_fma_f32 v[244:245], v[44:45], v[68:69], v[244:245] neg_lo:[1,0,0] neg_hi:[1,0,0]
	ds_read_b128 v[246:249], v1 offset:50496
	s_waitcnt lgkmcnt(14)
; #define SUB_LROW(buf, i_, j0_, n_) do { _Pragma("unroll") for (int j4 = 0; j4 < (n_); ++j4) buf[j4] = *(const f32x4*)(Ls + (i_) * 68 + 4 * ((j0_) + j4)); } while (0)
; #define SUB_FROW(buf, j0_, n_) do { _Pragma("unroll") for (int j4 = 0; j4 < (n_); ++j4) { const f32x4 l = buf[j4]; \
;                 acc -= l.x * x[4 * ((j0_) + j4)]; acc -= l.y * x[4 * ((j0_) + j4) + 1]; acc -= l.z * x[4 * ((j0_) + j4) + 2]; acc -= l.w * x[4 * ((j0_) + j4) + 3]; } } while (0)
; __device__ __forceinline__ void gdn_prep(KA a, int layer, unsigned char* lds, const int tid_, const int bid_) {
;     ...
;             for (int i = 33; i < 64; ++i) {
;                 float acc = x[i];
;                 SUB_LROW(bufB, i, 8, (i + 3) / 4 - 8); __builtin_amdgcn_sched_barrier(0);
;                 SUB_FROW(bufA, 0, 8); __builtin_amdgcn_sched_barrier(0);
;                 if (i + 1 < 64) SUB_LROW(bufA, i + 1, 0, 8);
;                 __builtin_amdgcn_sched_barrier(0);
;                 SUB_FROW(bufB, 8, (i + 3) / 4 - 8);
;                 x[i] = acc;
;                 __builtin_amdgcn_sched_barrier(0);
;             }
	v_pk_fma_f32 v[242:243], v[46:47], v[70:71], v[242:243] neg_lo:[1,0,0] neg_hi:[1,0,0]
	v_pk_fma_f32 v[244:245], v[48:49], v[72:73], v[244:245] neg_lo:[1,0,0] neg_hi:[1,0,0]
	ds_read_b128 v[66:69], v1 offset:50512
	s_waitcnt lgkmcnt(14)
	v_pk_fma_f32 v[242:243], v[50:51], v[74:75], v[242:243] neg_lo:[1,0,0] neg_hi:[1,0,0]
	v_pk_fma_f32 v[244:245], v[52:53], v[76:77], v[244:245] neg_lo:[1,0,0] neg_hi:[1,0,0]
	ds_read_b128 v[70:73], v1 offset:50528
	s_waitcnt lgkmcnt(14)
	v_pk_fma_f32 v[242:243], v[54:55], v[78:79], v[242:243] neg_lo:[1,0,0] neg_hi:[1,0,0]
	v_pk_fma_f32 v[244:245], v[56:57], v[80:81], v[244:245] neg_lo:[1,0,0] neg_hi:[1,0,0]
	ds_read_b128 v[74:77], v1 offset:50544
	s_waitcnt lgkmcnt(14)
	v_pk_mul_f32 v[250:251], v[2:3], v[82:83] neg_lo:[1,0] neg_hi:[1,0]
	v_pk_mul_f32 v[252:253], v[4:5], v[84:85] neg_lo:[1,0] neg_hi:[1,0]
	v_pk_add_f32 v[242:243], v[242:243], v[244:245]
	ds_read_b128 v[78:81], v1 offset:50592
	s_waitcnt lgkmcnt(14)
	v_pk_fma_f32 v[250:251], v[6:7], v[86:87], v[250:251] neg_lo:[1,0,0] neg_hi:[1,0,0]
	v_add_f32_e32 v242, v242, v243
	v_pk_fma_f32 v[252:253], v[8:9], v[88:89], v[252:253] neg_lo:[1,0,0] neg_hi:[1,0,0]
	v_add_f32_e32 v58, v58, v242
	ds_read_b128 v[82:85], v1 offset:50608
	s_waitcnt lgkmcnt(14)
	v_pk_fma_f32 v[250:251], v[10:11], v[116:117], v[250:251] neg_lo:[1,0,0] neg_hi:[1,0,0]
	v_pk_fma_f32 v[252:253], v[12:13], v[118:119], v[252:253] neg_lo:[1,0,0] neg_hi:[1,0,0]
	ds_read_b128 v[86:89], v1 offset:50624
	s_waitcnt lgkmcnt(14)
	v_pk_fma_f32 v[250:251], v[14:15], v[120:121], v[250:251] neg_lo:[1,0,0] neg_hi:[1,0,0]
	v_pk_fma_f32 v[252:253], v[16:17], v[122:123], v[252:253] neg_lo:[1,0,0] neg_hi:[1,0,0]
	ds_read_b128 v[116:119], v1 offset:50640
	s_waitcnt lgkmcnt(14)
	v_pk_fma_f32 v[250:251], v[18:19], v[124:125], v[250:251] neg_lo:[1,0,0] neg_hi:[1,0,0]
	v_pk_fma_f32 v[252:253], v[20:21], v[126:127], v[252:253] neg_lo:[1,0,0] neg_hi:[1,0,0]
	ds_read_b128 v[120:123], v1 offset:50656
	s_waitcnt lgkmcnt(14)
	v_pk_fma_f32 v[250:251], v[22:23], v[128:129], v[250:251] neg_lo:[1,0,0] neg_hi:[1,0,0]
	v_pk_fma_f32 v[252:253], v[24:25], v[130:131], v[252:253] neg_lo:[1,0,0] neg_hi:[1,0,0]
	ds_read_b128 v[124:127], v1 offset:50672
	s_waitcnt lgkmcnt(14)
	v_pk_fma_f32 v[250:251], v[26:27], v[132:133], v[250:251] neg_lo:[1,0,0] neg_hi:[1,0,0]
	v_pk_fma_f32 v[252:253], v[28:29], v[134:135], v[252:253] neg_lo:[1,0,0] neg_hi:[1,0,0]
	ds_read_b128 v[128:131], v1 offset:50688
	s_waitcnt lgkmcnt(14)
	v_pk_fma_f32 v[250:251], v[30:31], v[136:137], v[250:251] neg_lo:[1,0,0] neg_hi:[1,0,0]
	v_pk_fma_f32 v[252:253], v[32:33], v[138:139], v[252:253] neg_lo:[1,0,0] neg_hi:[1,0,0]
	ds_read_b128 v[132:135], v1 offset:50704
	s_waitcnt lgkmcnt(14)
	v_pk_fma_f32 v[250:251], v[34:35], v[140:141], v[250:251] neg_lo:[1,0,0] neg_hi:[1,0,0]
	v_pk_fma_f32 v[252:253], v[36:37], v[142:143], v[252:253] neg_lo:[1,0,0] neg_hi:[1,0,0]
	ds_read_b128 v[136:139], v1 offset:50720
	s_waitcnt lgkmcnt(14)
	v_pk_fma_f32 v[250:251], v[38:39], v[200:201], v[250:251] neg_lo:[1,0,0] neg_hi:[1,0,0]
	v_pk_fma_f32 v[252:253], v[40:41], v[202:203], v[252:253] neg_lo:[1,0,0] neg_hi:[1,0,0]
	ds_read_b128 v[140:143], v1 offset:50736
	s_waitcnt lgkmcnt(14)
	v_pk_fma_f32 v[250:251], v[42:43], v[204:205], v[250:251] neg_lo:[1,0,0] neg_hi:[1,0,0]
	v_pk_fma_f32 v[252:253], v[44:45], v[206:207], v[252:253] neg_lo:[1,0,0] neg_hi:[1,0,0]
	ds_read_b128 v[200:203], v1 offset:50752
	s_waitcnt lgkmcnt(14)
	v_pk_fma_f32 v[250:251], v[46:47], v[246:247], v[250:251] neg_lo:[1,0,0] neg_hi:[1,0,0]
	v_pk_fma_f32 v[252:253], v[48:49], v[248:249], v[252:253] neg_lo:[1,0,0] neg_hi:[1,0,0]
	ds_read_b128 v[204:207], v1 offset:50768
	s_waitcnt lgkmcnt(14)
	v_pk_fma_f32 v[250:251], v[50:51], v[66:67], v[250:251] neg_lo:[1,0,0] neg_hi:[1,0,0]
	v_pk_fma_f32 v[252:253], v[52:53], v[68:69], v[252:253] neg_lo:[1,0,0] neg_hi:[1,0,0]
	ds_read_b128 v[246:249], v1 offset:50784
	s_waitcnt lgkmcnt(14)
	v_pk_fma_f32 v[250:251], v[54:55], v[70:71], v[250:251] neg_lo:[1,0,0] neg_hi:[1,0,0]
	v_pk_fma_f32 v[252:253], v[56:57], v[72:73], v[252:253] neg_lo:[1,0,0] neg_hi:[1,0,0]
	ds_read_b128 v[66:69], v1 offset:50800
	s_waitcnt lgkmcnt(14)
	v_pk_fma_f32 v[250:251], v[58:59], v[74:75], v[250:251] neg_lo:[1,0,0] neg_hi:[1,0,0]
	v_pk_fma_f32 v[252:253], v[60:61], v[76:77], v[252:253] neg_lo:[1,0,0] neg_hi:[1,0,0]
	ds_read_b128 v[70:73], v1 offset:50816
	s_waitcnt lgkmcnt(14)
	v_pk_mul_f32 v[242:243], v[2:3], v[78:79] neg_lo:[1,0] neg_hi:[1,0]
	v_pk_mul_f32 v[244:245], v[4:5], v[80:81] neg_lo:[1,0] neg_hi:[1,0]
	v_pk_add_f32 v[250:251], v[250:251], v[252:253]
	ds_read_b128 v[74:77], v1 offset:50864
	s_waitcnt lgkmcnt(14)
	v_pk_fma_f32 v[242:243], v[6:7], v[82:83], v[242:243] neg_lo:[1,0,0] neg_hi:[1,0,0]
	v_add_f32_e32 v250, v250, v251
	v_pk_fma_f32 v[244:245], v[8:9], v[84:85], v[244:245] neg_lo:[1,0,0] neg_hi:[1,0,0]
	v_add_f32_e32 v59, v59, v250
	ds_read_b128 v[78:81], v1 offset:50880
	s_waitcnt lgkmcnt(14)
	v_pk_fma_f32 v[242:243], v[10:11], v[86:87], v[242:243] neg_lo:[1,0,0] neg_hi:[1,0,0]
	v_pk_fma_f32 v[244:245], v[12:13], v[88:89], v[244:245] neg_lo:[1,0,0] neg_hi:[1,0,0]
	ds_read_b128 v[82:85], v1 offset:50896
	s_waitcnt lgkmcnt(14)
	v_pk_fma_f32 v[242:243], v[14:15], v[116:117], v[242:243] neg_lo:[1,0,0] neg_hi:[1,0,0]
	v_pk_fma_f32 v[244:245], v[16:17], v[118:119], v[244:245] neg_lo:[1,0,0] neg_hi:[1,0,0]
	ds_read_b128 v[86:89], v1 offset:50912
	s_waitcnt lgkmcnt(14)
	v_pk_fma_f32 v[242:243], v[18:19], v[120:121], v[242:243] neg_lo:[1,0,0] neg_hi:[1,0,0]
	v_pk_fma_f32 v[244:245], v[20:21], v[122:123], v[244:245] neg_lo:[1,0,0] neg_hi:[1,0,0]
	ds_read_b128 v[116:119], v1 offset:50928
	s_waitcnt lgkmcnt(14)
; #define SUB_LROW(buf, i_, j0_, n_) do { _Pragma("unroll") for (int j4 = 0; j4 < (n_); ++j4) buf[j4] = *(const f32x4*)(Ls + (i_) * 68 + 4 * ((j0_) + j4)); } while (0)
; #define SUB_FROW(buf, j0_, n_) do { _Pragma("unroll") for (int j4 = 0; j4 < (n_); ++j4) { const f32x4 l = buf[j4]; \
;                 acc -= l.x * x[4 * ((j0_) + j4)]; acc -= l.y * x[4 * ((j0_) + j4) + 1]; acc -= l.z * x[4 * ((j0_) + j4) + 2]; acc -= l.w * x[4 * ((j0_) + j4) + 3]; } } while (0)
; __device__ __forceinline__ void gdn_prep(KA a, int layer, unsigned char* lds, const int tid_, const int bid_) {
;     ...
;             for (int i = 33; i < 64; ++i) {
;                 float acc = x[i];
;                 SUB_LROW(bufB, i, 8, (i + 3) / 4 - 8); __builtin_amdgcn_sched_barrier(0);
;                 SUB_FROW(bufA, 0, 8); __builtin_amdgcn_sched_barrier(0);
;                 if (i + 1 < 64) SUB_LROW(bufA, i + 1, 0, 8);
;                 __builtin_amdgcn_sched_barrier(0);
;                 SUB_FROW(bufB, 8, (i + 3) / 4 - 8);
;                 x[i] = acc;
;                 __builtin_amdgcn_sched_barrier(0);
;             }
	v_pk_fma_f32 v[242:243], v[22:23], v[124:125], v[242:243] neg_lo:[1,0,0] neg_hi:[1,0,0]
	v_pk_fma_f32 v[244:245], v[24:25], v[126:127], v[244:245] neg_lo:[1,0,0] neg_hi:[1,0,0]
	ds_read_b128 v[120:123], v1 offset:50944
	s_waitcnt lgkmcnt(14)
	v_pk_fma_f32 v[242:243], v[26:27], v[128:129], v[242:243] neg_lo:[1,0,0] neg_hi:[1,0,0]
	v_pk_fma_f32 v[244:245], v[28:29], v[130:131], v[244:245] neg_lo:[1,0,0] neg_hi:[1,0,0]
	ds_read_b128 v[124:127], v1 offset:50960
	s_waitcnt lgkmcnt(14)
	v_pk_fma_f32 v[242:243], v[30:31], v[132:133], v[242:243] neg_lo:[1,0,0] neg_hi:[1,0,0]
	v_pk_fma_f32 v[244:245], v[32:33], v[134:135], v[244:245] neg_lo:[1,0,0] neg_hi:[1,0,0]
	ds_read_b128 v[128:131], v1 offset:50976
	s_waitcnt lgkmcnt(14)
	v_pk_fma_f32 v[242:243], v[34:35], v[136:137], v[242:243] neg_lo:[1,0,0] neg_hi:[1,0,0]
	v_pk_fma_f32 v[244:245], v[36:37], v[138:139], v[244:245] neg_lo:[1,0,0] neg_hi:[1,0,0]
	ds_read_b128 v[132:135], v1 offset:50992
	s_waitcnt lgkmcnt(14)
	v_pk_fma_f32 v[242:243], v[38:39], v[140:141], v[242:243] neg_lo:[1,0,0] neg_hi:[1,0,0]
	v_pk_fma_f32 v[244:245], v[40:41], v[142:143], v[244:245] neg_lo:[1,0,0] neg_hi:[1,0,0]
	ds_read_b128 v[136:139], v1 offset:51008
	s_waitcnt lgkmcnt(14)
	v_pk_fma_f32 v[242:243], v[42:43], v[200:201], v[242:243] neg_lo:[1,0,0] neg_hi:[1,0,0]
	v_pk_fma_f32 v[244:245], v[44:45], v[202:203], v[244:245] neg_lo:[1,0,0] neg_hi:[1,0,0]
	ds_read_b128 v[140:143], v1 offset:51024
	s_waitcnt lgkmcnt(14)
	v_pk_fma_f32 v[242:243], v[46:47], v[204:205], v[242:243] neg_lo:[1,0,0] neg_hi:[1,0,0]
	v_pk_fma_f32 v[244:245], v[48:49], v[206:207], v[244:245] neg_lo:[1,0,0] neg_hi:[1,0,0]
	ds_read_b128 v[200:203], v1 offset:51040
	s_waitcnt lgkmcnt(14)
	v_pk_fma_f32 v[242:243], v[50:51], v[246:247], v[242:243] neg_lo:[1,0,0] neg_hi:[1,0,0]
	v_pk_fma_f32 v[244:245], v[52:53], v[248:249], v[244:245] neg_lo:[1,0,0] neg_hi:[1,0,0]
	ds_read_b128 v[204:207], v1 offset:51056
	s_waitcnt lgkmcnt(14)
	v_pk_fma_f32 v[242:243], v[54:55], v[66:67], v[242:243] neg_lo:[1,0,0] neg_hi:[1,0,0]
	v_pk_fma_f32 v[244:245], v[56:57], v[68:69], v[244:245] neg_lo:[1,0,0] neg_hi:[1,0,0]
	ds_read_b128 v[246:249], v1 offset:51072
	s_waitcnt lgkmcnt(14)
	v_pk_fma_f32 v[242:243], v[58:59], v[70:71], v[242:243] neg_lo:[1,0,0] neg_hi:[1,0,0]
	v_pk_fma_f32 v[244:245], v[60:61], v[72:73], v[244:245] neg_lo:[1,0,0] neg_hi:[1,0,0]
	ds_read_b128 v[66:69], v1 offset:51088
	s_waitcnt lgkmcnt(14)
	v_pk_mul_f32 v[250:251], v[2:3], v[74:75] neg_lo:[1,0] neg_hi:[1,0]
	v_pk_mul_f32 v[252:253], v[4:5], v[76:77] neg_lo:[1,0] neg_hi:[1,0]
	v_pk_add_f32 v[242:243], v[242:243], v[244:245]
	ds_read_b128 v[70:73], v1 offset:51136
	s_waitcnt lgkmcnt(14)
	v_pk_fma_f32 v[250:251], v[6:7], v[78:79], v[250:251] neg_lo:[1,0,0] neg_hi:[1,0,0]
	v_add_f32_e32 v242, v242, v243
	v_pk_fma_f32 v[252:253], v[8:9], v[80:81], v[252:253] neg_lo:[1,0,0] neg_hi:[1,0,0]
	v_add_f32_e32 v60, v60, v242
	ds_read_b128 v[74:77], v1 offset:51152
	s_waitcnt lgkmcnt(14)
	v_pk_fma_f32 v[250:251], v[10:11], v[82:83], v[250:251] neg_lo:[1,0,0] neg_hi:[1,0,0]
	v_pk_fma_f32 v[252:253], v[12:13], v[84:85], v[252:253] neg_lo:[1,0,0] neg_hi:[1,0,0]
	ds_read_b128 v[78:81], v1 offset:51168
	s_waitcnt lgkmcnt(14)
	v_pk_fma_f32 v[250:251], v[14:15], v[86:87], v[250:251] neg_lo:[1,0,0] neg_hi:[1,0,0]
	v_pk_fma_f32 v[252:253], v[16:17], v[88:89], v[252:253] neg_lo:[1,0,0] neg_hi:[1,0,0]
	ds_read_b128 v[82:85], v1 offset:51184
	s_waitcnt lgkmcnt(14)
	v_pk_fma_f32 v[250:251], v[18:19], v[116:117], v[250:251] neg_lo:[1,0,0] neg_hi:[1,0,0]
	v_pk_fma_f32 v[252:253], v[20:21], v[118:119], v[252:253] neg_lo:[1,0,0] neg_hi:[1,0,0]
	ds_read_b128 v[86:89], v1 offset:51200
	s_waitcnt lgkmcnt(14)
	v_pk_fma_f32 v[250:251], v[22:23], v[120:121], v[250:251] neg_lo:[1,0,0] neg_hi:[1,0,0]
	v_pk_fma_f32 v[252:253], v[24:25], v[122:123], v[252:253] neg_lo:[1,0,0] neg_hi:[1,0,0]
	ds_read_b128 v[116:119], v1 offset:51216
	s_waitcnt lgkmcnt(14)
	v_pk_fma_f32 v[250:251], v[26:27], v[124:125], v[250:251] neg_lo:[1,0,0] neg_hi:[1,0,0]
	v_pk_fma_f32 v[252:253], v[28:29], v[126:127], v[252:253] neg_lo:[1,0,0] neg_hi:[1,0,0]
	ds_read_b128 v[120:123], v1 offset:51232
	s_waitcnt lgkmcnt(14)
	v_pk_fma_f32 v[250:251], v[30:31], v[128:129], v[250:251] neg_lo:[1,0,0] neg_hi:[1,0,0]
	v_pk_fma_f32 v[252:253], v[32:33], v[130:131], v[252:253] neg_lo:[1,0,0] neg_hi:[1,0,0]
	ds_read_b128 v[124:127], v1 offset:51248
	s_waitcnt lgkmcnt(14)
	v_pk_fma_f32 v[250:251], v[34:35], v[132:133], v[250:251] neg_lo:[1,0,0] neg_hi:[1,0,0]
	v_pk_fma_f32 v[252:253], v[36:37], v[134:135], v[252:253] neg_lo:[1,0,0] neg_hi:[1,0,0]
	ds_read_b128 v[128:131], v1 offset:51264
	s_waitcnt lgkmcnt(14)
	v_pk_fma_f32 v[250:251], v[38:39], v[136:137], v[250:251] neg_lo:[1,0,0] neg_hi:[1,0,0]
	v_pk_fma_f32 v[252:253], v[40:41], v[138:139], v[252:253] neg_lo:[1,0,0] neg_hi:[1,0,0]
	ds_read_b128 v[132:135], v1 offset:51280
	s_waitcnt lgkmcnt(14)
	v_pk_fma_f32 v[250:251], v[42:43], v[140:141], v[250:251] neg_lo:[1,0,0] neg_hi:[1,0,0]
	v_pk_fma_f32 v[252:253], v[44:45], v[142:143], v[252:253] neg_lo:[1,0,0] neg_hi:[1,0,0]
	ds_read_b128 v[136:139], v1 offset:51296
	s_waitcnt lgkmcnt(14)
	v_pk_fma_f32 v[250:251], v[46:47], v[200:201], v[250:251] neg_lo:[1,0,0] neg_hi:[1,0,0]
	v_pk_fma_f32 v[252:253], v[48:49], v[202:203], v[252:253] neg_lo:[1,0,0] neg_hi:[1,0,0]
	ds_read_b128 v[140:143], v1 offset:51312
	s_waitcnt lgkmcnt(14)
	v_pk_fma_f32 v[250:251], v[50:51], v[204:205], v[250:251] neg_lo:[1,0,0] neg_hi:[1,0,0]
	v_pk_fma_f32 v[252:253], v[52:53], v[206:207], v[252:253] neg_lo:[1,0,0] neg_hi:[1,0,0]
	ds_read_b128 v[200:203], v1 offset:51328
	s_waitcnt lgkmcnt(14)
; #define SUB_LROW(buf, i_, j0_, n_) do { _Pragma("unroll") for (int j4 = 0; j4 < (n_); ++j4) buf[j4] = *(const f32x4*)(Ls + (i_) * 68 + 4 * ((j0_) + j4)); } while (0)
; #define SUB_FROW(buf, j0_, n_) do { _Pragma("unroll") for (int j4 = 0; j4 < (n_); ++j4) { const f32x4 l = buf[j4]; \
;                 acc -= l.x * x[4 * ((j0_) + j4)]; acc -= l.y * x[4 * ((j0_) + j4) + 1]; acc -= l.z * x[4 * ((j0_) + j4) + 2]; acc -= l.w * x[4 * ((j0_) + j4) + 3]; } } while (0)
; __device__ __forceinline__ void gdn_prep(KA a, int layer, unsigned char* lds, const int tid_, const int bid_) {
;     ...
;             for (int i = 33; i < 64; ++i) {
;                 float acc = x[i];
;                 SUB_LROW(bufB, i, 8, (i + 3) / 4 - 8); __builtin_amdgcn_sched_barrier(0);
;                 SUB_FROW(bufA, 0, 8); __builtin_amdgcn_sched_barrier(0);
;                 if (i + 1 < 64) SUB_LROW(bufA, i + 1, 0, 8);
;                 __builtin_amdgcn_sched_barrier(0);
;                 SUB_FROW(bufB, 8, (i + 3) / 4 - 8);
;                 x[i] = acc;
;                 __builtin_amdgcn_sched_barrier(0);
;             }
	v_pk_fma_f32 v[250:251], v[54:55], v[246:247], v[250:251] neg_lo:[1,0,0] neg_hi:[1,0,0]
	v_pk_fma_f32 v[252:253], v[56:57], v[248:249], v[252:253] neg_lo:[1,0,0] neg_hi:[1,0,0]
	ds_read_b128 v[204:207], v1 offset:51344
	s_waitcnt lgkmcnt(14)
	v_pk_fma_f32 v[250:251], v[58:59], v[66:67], v[250:251] neg_lo:[1,0,0] neg_hi:[1,0,0]
	v_pk_fma_f32 v[252:253], v[60:61], v[68:69], v[252:253] neg_lo:[1,0,0] neg_hi:[1,0,0]
	ds_read_b128 v[246:249], v1 offset:51360
	s_waitcnt lgkmcnt(14)
	v_pk_mul_f32 v[242:243], v[2:3], v[70:71] neg_lo:[1,0] neg_hi:[1,0]
	v_pk_mul_f32 v[244:245], v[4:5], v[72:73] neg_lo:[1,0] neg_hi:[1,0]
	v_pk_add_f32 v[250:251], v[250:251], v[252:253]
	ds_read_b128 v[66:69], v1 offset:51408
	s_waitcnt lgkmcnt(14)
	v_pk_fma_f32 v[242:243], v[6:7], v[74:75], v[242:243] neg_lo:[1,0,0] neg_hi:[1,0,0]
	v_add_f32_e32 v250, v250, v251
	v_pk_fma_f32 v[244:245], v[8:9], v[76:77], v[244:245] neg_lo:[1,0,0] neg_hi:[1,0,0]
	v_add_f32_e32 v61, v61, v250
	ds_read_b128 v[70:73], v1 offset:51424
	s_waitcnt lgkmcnt(14)
	v_pk_fma_f32 v[242:243], v[10:11], v[78:79], v[242:243] neg_lo:[1,0,0] neg_hi:[1,0,0]
	v_pk_fma_f32 v[244:245], v[12:13], v[80:81], v[244:245] neg_lo:[1,0,0] neg_hi:[1,0,0]
	ds_read_b128 v[74:77], v1 offset:51440
	s_waitcnt lgkmcnt(14)
	v_pk_fma_f32 v[242:243], v[14:15], v[82:83], v[242:243] neg_lo:[1,0,0] neg_hi:[1,0,0]
	v_pk_fma_f32 v[244:245], v[16:17], v[84:85], v[244:245] neg_lo:[1,0,0] neg_hi:[1,0,0]
	ds_read_b128 v[78:81], v1 offset:51456
	s_waitcnt lgkmcnt(14)
	v_pk_fma_f32 v[242:243], v[18:19], v[86:87], v[242:243] neg_lo:[1,0,0] neg_hi:[1,0,0]
	v_pk_fma_f32 v[244:245], v[20:21], v[88:89], v[244:245] neg_lo:[1,0,0] neg_hi:[1,0,0]
	ds_read_b128 v[82:85], v1 offset:51472
	s_waitcnt lgkmcnt(14)
	v_pk_fma_f32 v[242:243], v[22:23], v[116:117], v[242:243] neg_lo:[1,0,0] neg_hi:[1,0,0]
	v_pk_fma_f32 v[244:245], v[24:25], v[118:119], v[244:245] neg_lo:[1,0,0] neg_hi:[1,0,0]
	ds_read_b128 v[86:89], v1 offset:51488
	s_waitcnt lgkmcnt(14)
	v_pk_fma_f32 v[242:243], v[26:27], v[120:121], v[242:243] neg_lo:[1,0,0] neg_hi:[1,0,0]
	v_pk_fma_f32 v[244:245], v[28:29], v[122:123], v[244:245] neg_lo:[1,0,0] neg_hi:[1,0,0]
	ds_read_b128 v[116:119], v1 offset:51504
	s_waitcnt lgkmcnt(14)
	v_pk_fma_f32 v[242:243], v[30:31], v[124:125], v[242:243] neg_lo:[1,0,0] neg_hi:[1,0,0]
	v_pk_fma_f32 v[244:245], v[32:33], v[126:127], v[244:245] neg_lo:[1,0,0] neg_hi:[1,0,0]
	ds_read_b128 v[120:123], v1 offset:51520
	s_waitcnt lgkmcnt(14)
	v_pk_fma_f32 v[242:243], v[34:35], v[128:129], v[242:243] neg_lo:[1,0,0] neg_hi:[1,0,0]
	v_pk_fma_f32 v[244:245], v[36:37], v[130:131], v[244:245] neg_lo:[1,0,0] neg_hi:[1,0,0]
	ds_read_b128 v[124:127], v1 offset:51536
	s_waitcnt lgkmcnt(14)
	v_pk_fma_f32 v[242:243], v[38:39], v[132:133], v[242:243] neg_lo:[1,0,0] neg_hi:[1,0,0]
	v_pk_fma_f32 v[244:245], v[40:41], v[134:135], v[244:245] neg_lo:[1,0,0] neg_hi:[1,0,0]
	ds_read_b128 v[128:131], v1 offset:51552
	s_waitcnt lgkmcnt(14)
	v_pk_fma_f32 v[242:243], v[42:43], v[136:137], v[242:243] neg_lo:[1,0,0] neg_hi:[1,0,0]
	v_pk_fma_f32 v[244:245], v[44:45], v[138:139], v[244:245] neg_lo:[1,0,0] neg_hi:[1,0,0]
	ds_read_b128 v[132:135], v1 offset:51568
	s_waitcnt lgkmcnt(14)
	v_pk_fma_f32 v[242:243], v[46:47], v[140:141], v[242:243] neg_lo:[1,0,0] neg_hi:[1,0,0]
	v_pk_fma_f32 v[244:245], v[48:49], v[142:143], v[244:245] neg_lo:[1,0,0] neg_hi:[1,0,0]
	ds_read_b128 v[136:139], v1 offset:51584
	s_waitcnt lgkmcnt(14)
	v_pk_fma_f32 v[242:243], v[50:51], v[200:201], v[242:243] neg_lo:[1,0,0] neg_hi:[1,0,0]
	v_pk_fma_f32 v[244:245], v[52:53], v[202:203], v[244:245] neg_lo:[1,0,0] neg_hi:[1,0,0]
	ds_read_b128 v[140:143], v1 offset:51600
	s_waitcnt lgkmcnt(14)
	v_pk_fma_f32 v[242:243], v[54:55], v[204:205], v[242:243] neg_lo:[1,0,0] neg_hi:[1,0,0]
	v_pk_fma_f32 v[244:245], v[56:57], v[206:207], v[244:245] neg_lo:[1,0,0] neg_hi:[1,0,0]
	ds_read_b128 v[200:203], v1 offset:51616
	s_waitcnt lgkmcnt(14)
	v_pk_fma_f32 v[242:243], v[58:59], v[246:247], v[242:243] neg_lo:[1,0,0] neg_hi:[1,0,0]
	v_pk_fma_f32 v[244:245], v[60:61], v[248:249], v[244:245] neg_lo:[1,0,0] neg_hi:[1,0,0]
	ds_read_b128 v[204:207], v1 offset:51632
	s_waitcnt lgkmcnt(14)
	v_pk_mul_f32 v[250:251], v[2:3], v[66:67] neg_lo:[1,0] neg_hi:[1,0]
	v_pk_mul_f32 v[252:253], v[4:5], v[68:69] neg_lo:[1,0] neg_hi:[1,0]
	v_pk_add_f32 v[242:243], v[242:243], v[244:245]
	ds_read_b128 v[246:249], v1 offset:51648
	s_waitcnt lgkmcnt(14)
	v_pk_fma_f32 v[250:251], v[6:7], v[70:71], v[250:251] neg_lo:[1,0,0] neg_hi:[1,0,0]
	v_add_f32_e32 v242, v242, v243
	v_pk_fma_f32 v[252:253], v[8:9], v[72:73], v[252:253] neg_lo:[1,0,0] neg_hi:[1,0,0]
	v_add_f32_e32 v62, v62, v242
	ds_read_b128 v[66:69], v1 offset:51680
	s_waitcnt lgkmcnt(14)
	v_pk_fma_f32 v[250:251], v[10:11], v[74:75], v[250:251] neg_lo:[1,0,0] neg_hi:[1,0,0]
	v_pk_fma_f32 v[252:253], v[12:13], v[76:77], v[252:253] neg_lo:[1,0,0] neg_hi:[1,0,0]
	ds_read_b128 v[70:73], v1 offset:51696
	s_waitcnt lgkmcnt(14)
	v_pk_fma_f32 v[250:251], v[14:15], v[78:79], v[250:251] neg_lo:[1,0,0] neg_hi:[1,0,0]
	v_pk_fma_f32 v[252:253], v[16:17], v[80:81], v[252:253] neg_lo:[1,0,0] neg_hi:[1,0,0]
	ds_read_b128 v[74:77], v1 offset:51712
	s_waitcnt lgkmcnt(14)
	v_pk_fma_f32 v[250:251], v[18:19], v[82:83], v[250:251] neg_lo:[1,0,0] neg_hi:[1,0,0]
	v_pk_fma_f32 v[252:253], v[20:21], v[84:85], v[252:253] neg_lo:[1,0,0] neg_hi:[1,0,0]
	ds_read_b128 v[78:81], v1 offset:51728
	s_waitcnt lgkmcnt(14)
	v_pk_fma_f32 v[250:251], v[22:23], v[86:87], v[250:251] neg_lo:[1,0,0] neg_hi:[1,0,0]
	v_pk_fma_f32 v[252:253], v[24:25], v[88:89], v[252:253] neg_lo:[1,0,0] neg_hi:[1,0,0]
	ds_read_b128 v[82:85], v1 offset:51744
	s_waitcnt lgkmcnt(14)
; #define SUB_LROW(buf, i_, j0_, n_) do { _Pragma("unroll") for (int j4 = 0; j4 < (n_); ++j4) buf[j4] = *(const f32x4*)(Ls + (i_) * 68 + 4 * ((j0_) + j4)); } while (0)
; #define SUB_FROW(buf, j0_, n_) do { _Pragma("unroll") for (int j4 = 0; j4 < (n_); ++j4) { const f32x4 l = buf[j4]; \
;                 acc -= l.x * x[4 * ((j0_) + j4)]; acc -= l.y * x[4 * ((j0_) + j4) + 1]; acc -= l.z * x[4 * ((j0_) + j4) + 2]; acc -= l.w * x[4 * ((j0_) + j4) + 3]; } } while (0)
; __device__ __forceinline__ void gdn_prep(KA a, int layer, unsigned char* lds, const int tid_, const int bid_) {
;     ...
;             for (int i = 33; i < 64; ++i) {
;                 float acc = x[i];
;                 SUB_LROW(bufB, i, 8, (i + 3) / 4 - 8); __builtin_amdgcn_sched_barrier(0);
;                 SUB_FROW(bufA, 0, 8); __builtin_amdgcn_sched_barrier(0);
;                 if (i + 1 < 64) SUB_LROW(bufA, i + 1, 0, 8);
;                 __builtin_amdgcn_sched_barrier(0);
;                 SUB_FROW(bufB, 8, (i + 3) / 4 - 8);
;                 x[i] = acc;
;                 __builtin_amdgcn_sched_barrier(0);
;             }
	v_pk_fma_f32 v[250:251], v[26:27], v[116:117], v[250:251] neg_lo:[1,0,0] neg_hi:[1,0,0]
	v_pk_fma_f32 v[252:253], v[28:29], v[118:119], v[252:253] neg_lo:[1,0,0] neg_hi:[1,0,0]
	ds_read_b128 v[86:89], v1 offset:51760
	s_waitcnt lgkmcnt(14)
	v_pk_fma_f32 v[250:251], v[30:31], v[120:121], v[250:251] neg_lo:[1,0,0] neg_hi:[1,0,0]
	v_pk_fma_f32 v[252:253], v[32:33], v[122:123], v[252:253] neg_lo:[1,0,0] neg_hi:[1,0,0]
	ds_read_b128 v[116:119], v1 offset:51776
	s_waitcnt lgkmcnt(14)
	v_pk_fma_f32 v[250:251], v[34:35], v[124:125], v[250:251] neg_lo:[1,0,0] neg_hi:[1,0,0]
	v_pk_fma_f32 v[252:253], v[36:37], v[126:127], v[252:253] neg_lo:[1,0,0] neg_hi:[1,0,0]
	ds_read_b128 v[120:123], v1 offset:51792
	s_waitcnt lgkmcnt(14)
	v_pk_fma_f32 v[250:251], v[38:39], v[128:129], v[250:251] neg_lo:[1,0,0] neg_hi:[1,0,0]
	v_pk_fma_f32 v[252:253], v[40:41], v[130:131], v[252:253] neg_lo:[1,0,0] neg_hi:[1,0,0]
	ds_read_b128 v[124:127], v1 offset:51808
	s_waitcnt lgkmcnt(14)
	v_pk_fma_f32 v[250:251], v[42:43], v[132:133], v[250:251] neg_lo:[1,0,0] neg_hi:[1,0,0]
	v_pk_fma_f32 v[252:253], v[44:45], v[134:135], v[252:253] neg_lo:[1,0,0] neg_hi:[1,0,0]
	ds_read_b128 v[128:131], v1 offset:51824
	s_waitcnt lgkmcnt(14)
	v_pk_fma_f32 v[250:251], v[46:47], v[136:137], v[250:251] neg_lo:[1,0,0] neg_hi:[1,0,0]
	v_pk_fma_f32 v[252:253], v[48:49], v[138:139], v[252:253] neg_lo:[1,0,0] neg_hi:[1,0,0]
	ds_read_b128 v[132:135], v1 offset:51840
	s_waitcnt lgkmcnt(14)
	v_pk_fma_f32 v[250:251], v[50:51], v[140:141], v[250:251] neg_lo:[1,0,0] neg_hi:[1,0,0]
	v_pk_fma_f32 v[252:253], v[52:53], v[142:143], v[252:253] neg_lo:[1,0,0] neg_hi:[1,0,0]
	ds_read_b128 v[136:139], v1 offset:51856
	s_waitcnt lgkmcnt(14)
	v_pk_fma_f32 v[250:251], v[54:55], v[200:201], v[250:251] neg_lo:[1,0,0] neg_hi:[1,0,0]
	v_pk_fma_f32 v[252:253], v[56:57], v[202:203], v[252:253] neg_lo:[1,0,0] neg_hi:[1,0,0]
	ds_read_b128 v[140:143], v1 offset:51872
	s_waitcnt lgkmcnt(14)
	v_pk_fma_f32 v[250:251], v[58:59], v[204:205], v[250:251] neg_lo:[1,0,0] neg_hi:[1,0,0]
	v_pk_fma_f32 v[252:253], v[60:61], v[206:207], v[252:253] neg_lo:[1,0,0] neg_hi:[1,0,0]
	ds_read_b128 v[200:203], v1 offset:51888
	s_waitcnt lgkmcnt(14)
	v_pk_fma_f32 v[250:251], v[62:63], v[246:247], v[250:251] neg_lo:[1,0,0] neg_hi:[1,0,0]
	v_pk_fma_f32 v[252:253], v[64:65], v[248:249], v[252:253] neg_lo:[1,0,0] neg_hi:[1,0,0]
	ds_read_b128 v[204:207], v1 offset:51904
	s_waitcnt lgkmcnt(14)
	v_pk_mul_f32 v[242:243], v[2:3], v[66:67] neg_lo:[1,0] neg_hi:[1,0]
	v_pk_mul_f32 v[244:245], v[4:5], v[68:69] neg_lo:[1,0] neg_hi:[1,0]
	v_pk_add_f32 v[250:251], v[250:251], v[252:253]
	ds_read_b128 v[246:249], v1 offset:51920
	s_waitcnt lgkmcnt(14)
	v_pk_fma_f32 v[242:243], v[6:7], v[70:71], v[242:243] neg_lo:[1,0,0] neg_hi:[1,0,0]
	v_add_f32_e32 v250, v250, v251
	v_pk_fma_f32 v[244:245], v[8:9], v[72:73], v[244:245] neg_lo:[1,0,0] neg_hi:[1,0,0]
	v_add_f32_e32 v63, v63, v250
	ds_read_b128 v[66:69], v1 offset:51952
	s_waitcnt lgkmcnt(14)
	v_pk_fma_f32 v[242:243], v[10:11], v[74:75], v[242:243] neg_lo:[1,0,0] neg_hi:[1,0,0]
	v_pk_fma_f32 v[244:245], v[12:13], v[76:77], v[244:245] neg_lo:[1,0,0] neg_hi:[1,0,0]
	ds_read_b128 v[70:73], v1 offset:51968
	s_waitcnt lgkmcnt(14)
	v_pk_fma_f32 v[242:243], v[14:15], v[78:79], v[242:243] neg_lo:[1,0,0] neg_hi:[1,0,0]
	v_pk_fma_f32 v[244:245], v[16:17], v[80:81], v[244:245] neg_lo:[1,0,0] neg_hi:[1,0,0]
	ds_read_b128 v[74:77], v1 offset:51984
	s_waitcnt lgkmcnt(14)
	v_pk_fma_f32 v[242:243], v[18:19], v[82:83], v[242:243] neg_lo:[1,0,0] neg_hi:[1,0,0]
	v_pk_fma_f32 v[244:245], v[20:21], v[84:85], v[244:245] neg_lo:[1,0,0] neg_hi:[1,0,0]
	ds_read_b128 v[78:81], v1 offset:52000
	s_waitcnt lgkmcnt(14)
	v_pk_fma_f32 v[242:243], v[22:23], v[86:87], v[242:243] neg_lo:[1,0,0] neg_hi:[1,0,0]
	v_pk_fma_f32 v[244:245], v[24:25], v[88:89], v[244:245] neg_lo:[1,0,0] neg_hi:[1,0,0]
	ds_read_b128 v[82:85], v1 offset:52016
	s_waitcnt lgkmcnt(14)
	v_pk_fma_f32 v[242:243], v[26:27], v[116:117], v[242:243] neg_lo:[1,0,0] neg_hi:[1,0,0]
	v_pk_fma_f32 v[244:245], v[28:29], v[118:119], v[244:245] neg_lo:[1,0,0] neg_hi:[1,0,0]
	ds_read_b128 v[86:89], v1 offset:52032
	s_waitcnt lgkmcnt(14)
	v_pk_fma_f32 v[242:243], v[30:31], v[120:121], v[242:243] neg_lo:[1,0,0] neg_hi:[1,0,0]
	v_pk_fma_f32 v[244:245], v[32:33], v[122:123], v[244:245] neg_lo:[1,0,0] neg_hi:[1,0,0]
	ds_read_b128 v[116:119], v1 offset:52048
	s_waitcnt lgkmcnt(14)
	v_pk_fma_f32 v[242:243], v[34:35], v[124:125], v[242:243] neg_lo:[1,0,0] neg_hi:[1,0,0]
	v_pk_fma_f32 v[244:245], v[36:37], v[126:127], v[244:245] neg_lo:[1,0,0] neg_hi:[1,0,0]
	ds_read_b128 v[120:123], v1 offset:52064
	s_waitcnt lgkmcnt(14)
	v_pk_fma_f32 v[242:243], v[38:39], v[128:129], v[242:243] neg_lo:[1,0,0] neg_hi:[1,0,0]
	v_pk_fma_f32 v[244:245], v[40:41], v[130:131], v[244:245] neg_lo:[1,0,0] neg_hi:[1,0,0]
	ds_read_b128 v[124:127], v1 offset:52080
	s_waitcnt lgkmcnt(14)
	v_pk_fma_f32 v[242:243], v[42:43], v[132:133], v[242:243] neg_lo:[1,0,0] neg_hi:[1,0,0]
	v_pk_fma_f32 v[244:245], v[44:45], v[134:135], v[244:245] neg_lo:[1,0,0] neg_hi:[1,0,0]
	ds_read_b128 v[128:131], v1 offset:52096
	s_waitcnt lgkmcnt(14)
	v_pk_fma_f32 v[242:243], v[46:47], v[136:137], v[242:243] neg_lo:[1,0,0] neg_hi:[1,0,0]
	v_pk_fma_f32 v[244:245], v[48:49], v[138:139], v[244:245] neg_lo:[1,0,0] neg_hi:[1,0,0]
	ds_read_b128 v[132:135], v1 offset:52112
	s_waitcnt lgkmcnt(14)
	v_pk_fma_f32 v[242:243], v[50:51], v[140:141], v[242:243] neg_lo:[1,0,0] neg_hi:[1,0,0]
	v_pk_fma_f32 v[244:245], v[52:53], v[142:143], v[244:245] neg_lo:[1,0,0] neg_hi:[1,0,0]
	ds_read_b128 v[136:139], v1 offset:52128
	s_waitcnt lgkmcnt(14)
; #define SUB_LROW(buf, i_, j0_, n_) do { _Pragma("unroll") for (int j4 = 0; j4 < (n_); ++j4) buf[j4] = *(const f32x4*)(Ls + (i_) * 68 + 4 * ((j0_) + j4)); } while (0)
; #define SUB_FROW(buf, j0_, n_) do { _Pragma("unroll") for (int j4 = 0; j4 < (n_); ++j4) { const f32x4 l = buf[j4]; \
;                 acc -= l.x * x[4 * ((j0_) + j4)]; acc -= l.y * x[4 * ((j0_) + j4) + 1]; acc -= l.z * x[4 * ((j0_) + j4) + 2]; acc -= l.w * x[4 * ((j0_) + j4) + 3]; } } while (0)
; __device__ __forceinline__ void gdn_prep(KA a, int layer, unsigned char* lds, const int tid_, const int bid_) {
;     ...
;             for (int i = 33; i < 64; ++i) {
;                 float acc = x[i];
;                 SUB_LROW(bufB, i, 8, (i + 3) / 4 - 8); __builtin_amdgcn_sched_barrier(0);
;                 SUB_FROW(bufA, 0, 8); __builtin_amdgcn_sched_barrier(0);
;                 if (i + 1 < 64) SUB_LROW(bufA, i + 1, 0, 8);
;                 __builtin_amdgcn_sched_barrier(0);
;                 SUB_FROW(bufB, 8, (i + 3) / 4 - 8);
;                 x[i] = acc;
;                 __builtin_amdgcn_sched_barrier(0);
;             }
;     ...
; #pragma unroll
;             for (int i = 0; i < 64; ++i) RHS[i * 260 + tid] = x[i];
	v_pk_fma_f32 v[242:243], v[54:55], v[200:201], v[242:243] neg_lo:[1,0,0] neg_hi:[1,0,0]
	v_pk_fma_f32 v[244:245], v[56:57], v[202:203], v[244:245] neg_lo:[1,0,0] neg_hi:[1,0,0]
	ds_read_b128 v[140:143], v1 offset:52144
	s_waitcnt lgkmcnt(14)
	v_pk_fma_f32 v[242:243], v[58:59], v[204:205], v[242:243] neg_lo:[1,0,0] neg_hi:[1,0,0]
	v_pk_fma_f32 v[244:245], v[60:61], v[206:207], v[244:245] neg_lo:[1,0,0] neg_hi:[1,0,0]
	ds_read_b128 v[200:203], v1 offset:52160
	s_waitcnt lgkmcnt(14)
	v_pk_fma_f32 v[242:243], v[62:63], v[246:247], v[242:243] neg_lo:[1,0,0] neg_hi:[1,0,0]
	v_pk_fma_f32 v[244:245], v[64:65], v[248:249], v[244:245] neg_lo:[1,0,0] neg_hi:[1,0,0]
	ds_read_b128 v[204:207], v1 offset:52176
	s_waitcnt lgkmcnt(14)
	v_pk_mul_f32 v[250:251], v[2:3], v[66:67] neg_lo:[1,0] neg_hi:[1,0]
	v_pk_mul_f32 v[252:253], v[4:5], v[68:69] neg_lo:[1,0] neg_hi:[1,0]
	v_pk_add_f32 v[242:243], v[242:243], v[244:245]
	ds_read_b128 v[246:249], v1 offset:52192
	s_waitcnt lgkmcnt(14)
	v_pk_fma_f32 v[250:251], v[6:7], v[70:71], v[250:251] neg_lo:[1,0,0] neg_hi:[1,0,0]
	v_add_f32_e32 v242, v242, v243
	v_pk_fma_f32 v[252:253], v[8:9], v[72:73], v[252:253] neg_lo:[1,0,0] neg_hi:[1,0,0]
	v_add_f32_e32 v64, v64, v242
	s_waitcnt lgkmcnt(13)
	v_pk_fma_f32 v[250:251], v[10:11], v[74:75], v[250:251] neg_lo:[1,0,0] neg_hi:[1,0,0]
	v_pk_fma_f32 v[252:253], v[12:13], v[76:77], v[252:253] neg_lo:[1,0,0] neg_hi:[1,0,0]
	s_waitcnt lgkmcnt(12)
	v_pk_fma_f32 v[250:251], v[14:15], v[78:79], v[250:251] neg_lo:[1,0,0] neg_hi:[1,0,0]
	v_pk_fma_f32 v[252:253], v[16:17], v[80:81], v[252:253] neg_lo:[1,0,0] neg_hi:[1,0,0]
	s_waitcnt lgkmcnt(11)
	v_pk_fma_f32 v[250:251], v[18:19], v[82:83], v[250:251] neg_lo:[1,0,0] neg_hi:[1,0,0]
	v_pk_fma_f32 v[252:253], v[20:21], v[84:85], v[252:253] neg_lo:[1,0,0] neg_hi:[1,0,0]
	s_waitcnt lgkmcnt(10)
	v_pk_fma_f32 v[250:251], v[22:23], v[86:87], v[250:251] neg_lo:[1,0,0] neg_hi:[1,0,0]
	v_pk_fma_f32 v[252:253], v[24:25], v[88:89], v[252:253] neg_lo:[1,0,0] neg_hi:[1,0,0]
	s_waitcnt lgkmcnt(9)
	v_pk_fma_f32 v[250:251], v[26:27], v[116:117], v[250:251] neg_lo:[1,0,0] neg_hi:[1,0,0]
	v_pk_fma_f32 v[252:253], v[28:29], v[118:119], v[252:253] neg_lo:[1,0,0] neg_hi:[1,0,0]
	s_waitcnt lgkmcnt(8)
	v_pk_fma_f32 v[250:251], v[30:31], v[120:121], v[250:251] neg_lo:[1,0,0] neg_hi:[1,0,0]
	v_pk_fma_f32 v[252:253], v[32:33], v[122:123], v[252:253] neg_lo:[1,0,0] neg_hi:[1,0,0]
	s_waitcnt lgkmcnt(7)
	v_pk_fma_f32 v[250:251], v[34:35], v[124:125], v[250:251] neg_lo:[1,0,0] neg_hi:[1,0,0]
	v_pk_fma_f32 v[252:253], v[36:37], v[126:127], v[252:253] neg_lo:[1,0,0] neg_hi:[1,0,0]
	s_waitcnt lgkmcnt(6)
	v_pk_fma_f32 v[250:251], v[38:39], v[128:129], v[250:251] neg_lo:[1,0,0] neg_hi:[1,0,0]
	v_pk_fma_f32 v[252:253], v[40:41], v[130:131], v[252:253] neg_lo:[1,0,0] neg_hi:[1,0,0]
	s_waitcnt lgkmcnt(5)
	v_pk_fma_f32 v[250:251], v[42:43], v[132:133], v[250:251] neg_lo:[1,0,0] neg_hi:[1,0,0]
	v_pk_fma_f32 v[252:253], v[44:45], v[134:135], v[252:253] neg_lo:[1,0,0] neg_hi:[1,0,0]
	s_waitcnt lgkmcnt(4)
	v_pk_fma_f32 v[250:251], v[46:47], v[136:137], v[250:251] neg_lo:[1,0,0] neg_hi:[1,0,0]
	v_pk_fma_f32 v[252:253], v[48:49], v[138:139], v[252:253] neg_lo:[1,0,0] neg_hi:[1,0,0]
	s_waitcnt lgkmcnt(3)
	v_pk_fma_f32 v[250:251], v[50:51], v[140:141], v[250:251] neg_lo:[1,0,0] neg_hi:[1,0,0]
	v_pk_fma_f32 v[252:253], v[52:53], v[142:143], v[252:253] neg_lo:[1,0,0] neg_hi:[1,0,0]
	s_waitcnt lgkmcnt(2)
	v_pk_fma_f32 v[250:251], v[54:55], v[200:201], v[250:251] neg_lo:[1,0,0] neg_hi:[1,0,0]
	v_pk_fma_f32 v[252:253], v[56:57], v[202:203], v[252:253] neg_lo:[1,0,0] neg_hi:[1,0,0]
	s_waitcnt lgkmcnt(1)
	v_pk_fma_f32 v[250:251], v[58:59], v[204:205], v[250:251] neg_lo:[1,0,0] neg_hi:[1,0,0]
	v_pk_fma_f32 v[252:253], v[60:61], v[206:207], v[252:253] neg_lo:[1,0,0] neg_hi:[1,0,0]
	s_waitcnt lgkmcnt(0)
	v_pk_fma_f32 v[250:251], v[62:63], v[246:247], v[250:251] neg_lo:[1,0,0] neg_hi:[1,0,0]
	v_pk_fma_f32 v[252:253], v[64:65], v[248:249], v[252:253] neg_lo:[1,0,0] neg_hi:[1,0,0]
	s_nop 0
	v_pk_add_f32 v[250:251], v[250:251], v[252:253]
	s_nop 0
	v_add_f32_e32 v250, v250, v251
	v_add_f32_e32 v65, v65, v250
	s_ashr_i32 s19, s18, 31
	ds_write_b32 v154, v2 offset:52224
	ds_write_b32 v154, v3 offset:53264
	ds_write_b32 v154, v4 offset:54304
	ds_write_b32 v154, v5 offset:55344
	ds_write_b32 v154, v6 offset:56384
	ds_write_b32 v154, v7 offset:57424
	ds_write_b32 v154, v8 offset:58464
	ds_write_b32 v154, v9 offset:59504
	ds_write_b32 v154, v10 offset:60544
	ds_write_b32 v154, v11 offset:61584
	ds_write_b32 v154, v12 offset:62624
	ds_write_b32 v154, v13 offset:63664
	ds_write_b32 v154, v14 offset:64704
	ds_write_b32 v155, v15 offset:13520
	ds_write_b32 v155, v16 offset:14560
	ds_write_b32 v155, v17 offset:15600
	ds_write_b32 v155, v18 offset:16640
	ds_write_b32 v155, v19 offset:17680
	ds_write_b32 v155, v20 offset:18720
	ds_write_b32 v155, v21 offset:19760
	ds_write_b32 v155, v22 offset:20800
	ds_write_b32 v155, v23 offset:21840
	ds_write_b32 v155, v24 offset:22880
	ds_write_b32 v155, v25 offset:23920
	ds_write_b32 v155, v26 offset:24960
	ds_write_b32 v155, v27 offset:26000
	ds_write_b32 v155, v28 offset:27040
	ds_write_b32 v155, v29 offset:28080
	ds_write_b32 v155, v30 offset:29120
	ds_write_b32 v155, v31 offset:30160
	ds_write_b32 v155, v32 offset:31200
	ds_write_b32 v155, v33 offset:32240
	ds_write_b32 v155, v34 offset:33280
	ds_write_b32 v155, v35 offset:34320
	ds_write_b32 v155, v36 offset:35360
	ds_write_b32 v155, v37 offset:36400
	ds_write_b32 v155, v38 offset:37440
	ds_write_b32 v155, v39 offset:38480
	ds_write_b32 v155, v40 offset:39520
	ds_write_b32 v155, v41 offset:40560
	ds_write_b32 v155, v42 offset:41600
	ds_write_b32 v155, v43 offset:42640
	ds_write_b32 v155, v44 offset:43680
	ds_write_b32 v155, v45 offset:44720
	ds_write_b32 v155, v46 offset:45760
	ds_write_b32 v155, v47 offset:46800
	ds_write_b32 v155, v48 offset:47840
	ds_write_b32 v155, v49 offset:48880
	ds_write_b32 v155, v50 offset:49920
	ds_write_b32 v155, v51 offset:50960
	ds_write_b32 v155, v52 offset:52000
	ds_write_b32 v155, v53 offset:53040
	ds_write_b32 v155, v54 offset:54080
	ds_write_b32 v155, v55 offset:55120
	ds_write_b32 v155, v56 offset:56160
	ds_write_b32 v155, v57 offset:57200
	ds_write_b32 v155, v58 offset:58240
	ds_write_b32 v155, v59 offset:59280
	ds_write_b32 v155, v60 offset:60320
	ds_write_b32 v155, v61 offset:61360
	ds_write_b32 v155, v62 offset:62400
	ds_write_b32 v155, v63 offset:63440
	ds_write_b32 v155, v64 offset:64480
	ds_write_b32 v155, v65 offset:65520
	v_mov_b64_e32 v[2:3], s[18:19]
	s_branch .LBB0_208
